# combo5: combo2 + up-epilogue (DPP bound_ctrl instead of pre-zeroing, -log2e folded into staged conv params), sig-epilogue (-log2e folded into row rstd), chunk attention (constant bias as accumulator i
# speedup vs baseline: 1.0051x; 1.0022x over previous
; template <int TYPE> __device__ __forceinline__ void attn_unit(const AttnCtx& C, int b, int h, int qb, LAS unsigned char* lds, int tid_in, unsigned* counter) {
;     ...
;     const int sq = 256 * qb + 32 * w + r32;
;     const size_t rowb = (size_t)b * SEQ;
;     LAS unsigned char* Kb = lds + AL_K; LAS unsigned char* Vb = lds + AL_V;
;     LAS float* Fb = (LAS float*)(lds + AL_F); LAS float* relb = (LAS float*)(lds + AL_REL); LAS float* wscr = (LAS float*)(lds + AL_WS) + w * 32;
;     constexpr int NPASS = (TYPE == 0) ? 2 : 1;
;     unsigned nclaim = 0u;
;     const float Mb = (TYPE == 0) ? C.Mb0 : (TYPE == 1) ? C.Mb1 : C.Mb2;
;     const int kwoff = w * 1024 + lane * 16, vwoff = ((tid & 7) >> 2) * 4096 + (tid >> 3) * 64 + (tid & 3) * 16;
;     const int vb0 = ((lane >> 4) & 1) * 32 + (lane & 3) * 8 + (4 * hi + ((lane & 15) >> 2)) * 64;
;     f32x16 o[2], o1[2];
;     if (TYPE == 2) { for (int i = tid; i < 257; i += 512) relb[i] = C.rel[h * 257 + i] * LOG2E; }
; #pragma unroll
;     for (int pass = 0; pass < NPASS; ++pass) {
;         int qcol, kcol, vcol;
;         if (TYPE == 0) { qcol = pass * 256 + 64 * h; kcol = 512 + pass * 256 + 64 * h; vcol = 1024 + 64 * h; }
;         else if (TYPE == 1) { qcol = 1280 + 64 * h; kcol = 1664 + 64 * h; vcol = 2048 + 64 * h; }
;         else { qcol = 2432 + 64 * h; kcol = 2816 + 64 * h; vcol = 3200 + 64 * h; }
;         const bf16_t* Qp = C.Z + (rowb + sq) * ZP + qcol + 8 * hi;
;         bf16x8 qr[4];
; #pragma unroll
;         for (int d0 = 0; d0 < 4; ++d0) qr[d0] = *(const bf16x8*)(Qp + 16 * d0);
;         float cinit = -Mb;
;         const float* f2p = C.F2 + (size_t)(b * 6 + h) * SEQ;
;         if (TYPE == 1) cinit += f2p[sq];
;         f32x16 cvec, zvec;
; #pragma unroll
;         for (int r = 0; r < 16; ++r) { cvec[r] = cinit; zvec[r] = 0.f; }
; #pragma unroll
;         for (int r = 0; r < 16; ++r) { o[0][r] = 0.f; o[1][r] = 0.f; }
;         float lsum = 0.f;
;         const bf16_t* kg = C.Z + (rowb + lane) * ZP + kcol + 8 * w;
;         const bf16_t* vg = C.Z + (rowb + (tid >> 3)) * ZP + vcol + 8 * (tid & 7);
;         u32x4 kreg = *(const u32x4*)(kg + (size_t)t0 * 64 * ZP), vreg = *(const u32x4*)(vg + (size_t)t0 * 64 * ZP);
;         u32x4 kreg2 = *(const u32x4*)(kg + (size_t)(t0 + 1) * 64 * ZP), vreg2 = *(const u32x4*)(vg + (size_t)(t0 + 1) * 64 * ZP);
;         float freg = 0.f, freg2 = 0.f;
.LBB0_383:
	s_or_b64 exec, exec, s[4:5]
	s_ashr_i32 s2, s0, 7
	s_ashr_i32 s13, s0, 6
	s_add_i32 s2, s2, s93
	s_add_i32 s10, s93, 4
	s_add_i32 s0, s93, -8
	v_readlane_b32 s1, v251, 32
	s_cmp_gt_u32 s1, 2
	s_cselect_b32 s11, s0, 0
	s_lshl_b32 s7, s1, 8
	s_lshl_b32 s6, s13, 5
	v_and_b32_e32 v133, 31, v0
	s_add_i32 s15, s6, s7
	v_or_b32_e32 v2, s15, v133
	v_readlane_b32 s16, v251, 21
	s_lshl_b32 s86, s24, 12
	v_ashrrev_i32_e32 v3, 31, v2
	v_readlane_b32 s17, v251, 22
	v_lshl_add_u64 v[2:3], v[2:3], 0, s[86:87]
	v_bfe_u32 v132, v0, 5, 1
	v_mov_b64_e32 v[10:11], s[16:17]
	v_mad_u64_u32 v[12:13], s[4:5], v2, s23, v[10:11]
	v_mad_i32_i24 v13, v3, s23, v13
	s_lshl_b32 s4, s78, 7
	s_mov_b32 s5, s87
	v_lshl_add_u64 v[2:3], v[12:13], 0, s[4:5]
	v_lshlrev_b32_e32 v144, 4, v132
	v_and_b32_e32 v134, 63, v0
	v_lshl_add_u64 v[2:3], v[2:3], 0, v[144:145]
	s_mov_b64 s[8:9], 0x1300
	s_movk_i32 s1, 0x1000
	v_or_b32_e32 v5, s86, v134
	s_movk_i32 s0, 0xe00
	v_lshl_add_u64 v[12:13], v[2:3], 0, s[8:9]
	v_add_co_u32_e32 v2, vcc, s1, v2
	v_mul_lo_u32 v6, v5, s0
	s_nop 0
	v_addc_co_u32_e32 v3, vcc, 0, v3, vcc
	v_mov_b32_e32 v7, v145
	v_ashrrev_i32_e32 v4, 3, v0
	s_lshl_b32 s0, s13, 3
	global_load_dwordx4 v[96:99], v[12:13], off offset:32
	global_load_dwordx4 v[100:103], v[12:13], off offset:64
	global_load_dwordx4 v[104:107], v[2:3], off offset:768
	global_load_dwordx4 v[108:111], v[12:13], off offset:96
	v_lshl_add_u64 v[2:3], v[6:7], 1, s[16:17]
	v_ashrrev_i32_e32 v5, 31, v4
	s_ashr_i32 s1, s0, 31
	v_lshl_add_u64 v[2:3], v[2:3], 0, s[4:5]
	v_lshl_add_u64 v[8:9], v[4:5], 0, s[86:87]
	v_lshl_add_u64 v[2:3], s[0:1], 1, v[2:3]
	s_mov_b64 s[0:1], 0x1600
	v_lshl_add_u64 v[128:129], v[2:3], 0, s[0:1]
	v_mad_u64_u32 v[2:3], s[0:1], v8, s23, v[10:11]
	v_and_b32_e32 v1, 7, v0
	v_mad_i32_i24 v3, v9, s23, v3
	v_lshl_add_u64 v[2:3], v[2:3], 0, s[4:5]
	v_lshlrev_b32_e32 v144, 4, v1
	v_lshl_add_u64 v[2:3], v[2:3], 0, v[144:145]
	s_mov_b64 s[0:1], 0x1900
	s_or_b32 s12, s11, 1
	v_lshl_add_u64 v[130:131], v[2:3], 0, s[0:1]
	v_mad_u64_u32 v[2:3], s[0:1], s11, v158, v[128:129]
	v_mad_u64_u32 v[6:7], s[0:1], s11, v158, v[130:131]
	global_load_dwordx4 v[112:115], v[2:3], off
	global_load_dwordx4 v[116:119], v[6:7], off
	v_mad_u64_u32 v[2:3], s[0:1], s12, v158, v[128:129]
	v_mad_u64_u32 v[6:7], s[0:1], s12, v158, v[130:131]
	global_load_dwordx4 v[120:123], v[2:3], off
	global_load_dwordx4 v[124:127], v[6:7], off
	v_lshlrev_b32_e32 v1, 4, v134
	v_lshlrev_b32_e32 v2, 10, v0
	v_lshlrev_b32_e32 v135, 2, v132
	v_lshrrev_b32_e32 v7, 2, v0
	s_sub_i32 s0, s15, 27
	v_and_b32_e32 v2, 0x1000, v2
	v_lshlrev_b32_e32 v3, 4, v0
	v_lshlrev_b32_e32 v5, 1, v0
	v_lshlrev_b32_e32 v6, 3, v0
	v_and_or_b32 v7, v7, 3, v135
	v_lshl_or_b32 v136, s13, 10, v1
	v_lshlrev_b32_e32 v1, 4, v133
	v_cmp_eq_u32_e64 s[84:85], 0, v0
	v_add_u32_e32 v0, s0, v133
	v_and_b32_e32 v5, 32, v5
	v_and_b32_e32 v6, 24, v6
	v_lshlrev_b32_e32 v7, 6, v7
	v_lshl_or_b32 v139, v132, 10, v1
	v_lshl_add_u32 v1, v4, 6, v2
	v_sub_u32_e32 v0, v0, v135
	s_lshl_b32 s0, s11, 6
	v_mov_b32_e32 v138, 0
	s_lshl_b32 s12, s78, 6
	s_add_i32 s13, s2, -8
	v_or3_b32 v137, v5, v6, v7
	v_and_or_b32 v140, v3, 48, v1
	s_add_i32 s14, s2, -2
	v_subrev_u32_e32 v141, s0, v0
	s_lshl_b32 s15, s11, 13
	v_mov_b32_e32 v164, 0
	v_mov_b32_e32 v0, 0
	v_mov_b32_e32 v1, v138
	v_mov_b32_e32 v2, v138
	v_mov_b32_e32 v3, v138
	v_mov_b32_e32 v4, v138
	v_mov_b32_e32 v5, v138
	v_mov_b32_e32 v6, v138
	v_mov_b32_e32 v7, v138
	v_mov_b32_e32 v8, v138
	v_mov_b32_e32 v9, v138
	v_mov_b32_e32 v10, v138
	v_mov_b32_e32 v11, v138
	v_mov_b32_e32 v12, v138
	v_mov_b32_e32 v13, v138
	v_mov_b32_e32 v14, v138
	v_mov_b32_e32 v15, v138
	v_mov_b32_e32 v16, 0
	v_mov_b32_e32 v17, v138
	v_mov_b32_e32 v18, v138
	v_mov_b32_e32 v19, v138
	v_mov_b32_e32 v20, v138
	v_mov_b32_e32 v21, v138
	v_mov_b32_e32 v22, v138
	v_mov_b32_e32 v23, v138
	v_mov_b32_e32 v24, v138
	v_mov_b32_e32 v25, v138
	v_mov_b32_e32 v26, v138
	v_mov_b32_e32 v27, v138
	v_mov_b32_e32 v28, v138
	v_mov_b32_e32 v29, v138
	v_mov_b32_e32 v30, v138
	v_mov_b32_e32 v31, v138
	s_waitcnt lgkmcnt(0)
	s_barrier
	ds_read_b32 v214, v155
	v_mbcnt_lo_u32_b32 v231, -1, 0
	v_mbcnt_hi_u32_b32 v231, -1, v231
	v_lshl_add_u32 v231, v231, 2, v155
	s_waitcnt lgkmcnt(0)
	v_mov_b32_e32 v215, v214
	v_mov_b32_e32 v216, v214
	v_mov_b32_e32 v217, v214
	v_mov_b32_e32 v218, v214
	v_mov_b32_e32 v219, v214
	v_mov_b32_e32 v220, v214
	v_mov_b32_e32 v221, v214
	v_mov_b32_e32 v222, v214
	v_mov_b32_e32 v223, v214
	v_mov_b32_e32 v224, v214
	v_mov_b32_e32 v225, v214
	v_mov_b32_e32 v226, v214
	v_mov_b32_e32 v227, v214
	v_mov_b32_e32 v228, v214
	v_mov_b32_e32 v229, v214
	ds_write_b32 v231, v214 offset:4
	s_branch .LBB0_386

; template <int TYPE> __device__ __forceinline__ void attn_unit(const AttnCtx& C, int b, int h, int qb, LAS unsigned char* lds, int tid_in, unsigned* counter) {
;     ...
;             const bool active = (TYPE == 2) ? (t >= cq - 8 && t <= cq) : (TYPE == 0) ? (t <= cq && (float)(256 * qb + 32 * w - 64 * t - 63) < dmax) : (t <= cq && t >= tfirst);
;             if (active) {
;                 f32x16 p0, p1;
;                 const LAS unsigned char* kp = Kb + bo + hi * 1024 + r32 * 16;
; #pragma unroll
;                 for (int d0 = 0; d0 < 4; ++d0) {
;                     const bf16x8 a0 = *(const LAS bf16x8*)(kp + d0 * 2048), a1 = *(const LAS bf16x8*)(kp + d0 * 2048 + 512);
;                     if (d0 == 0) { p0 = MFMA32(a0, qr[0], (TYPE == 1 ? cvec : zvec)); p1 = MFMA32(a1, qr[0], (TYPE == 1 ? cvec : zvec)); }
;                     else { p0 = MFMA32(a0, qr[d0], p0); p1 = MFMA32(a1, qr[d0], p1); }
;                 }
;                 const int xi = sq - 64 * t - 4 * hi;
;                 if (TYPE == 0) {
;                     const float xf = (float)xi;
; #pragma unroll
;                     for (int r = 0; r < 16; ++r) { const float c = (float)((r & 3) + 8 * (r >> 2));
;                         p0[r] = fast_exp2(p0[r] - sl2 * fabsf(xf - c)); p1[r] = fast_exp2(p1[r] - sl2 * fabsf(xf - (c + 32.f))); }
;                 } else if (TYPE == 1) {
;                     const LAS float* fp = Fb + (t & 3) * 64 + 4 * hi;
; #pragma unroll
;                     for (int g = 0; g < 4; ++g) { const f32x4 fa = *(const LAS f32x4*)(fp + 8 * g), fb2 = *(const LAS f32x4*)(fp + 32 + 8 * g);
; #pragma unroll
;                         for (int i = 0; i < 4; i += 2) {
;                             const f32x2_t d0_ = (f32x2_t){p0[4 * g + i], p0[4 * g + i + 1]} - (f32x2_t){fa[i], fa[i + 1]}, d1_ = (f32x2_t){p1[4 * g + i], p1[4 * g + i + 1]} - (f32x2_t){fb2[i], fb2[i + 1]};
;                             p0[4 * g + i] = fast_exp2(d0_[0]); p0[4 * g + i + 1] = fast_exp2(d0_[1]); p1[4 * g + i] = fast_exp2(d1_[0]); p1[4 * g + i + 1] = fast_exp2(d1_[1]); } }
;                     if (t == cq) { const int qrel = 32 * (w & 1) + r32;
; #pragma unroll
;                         for (int r = 0; r < 16; ++r) { const int kv = crow(r, hi); if (kv > qrel) p0[r] = 0.f; if (kv + 32 > qrel) p1[r] = 0.f; } }
;                 } else {
;                     if (cq - t >= 3) { const float bc = relb[256];
.LBB0_394:
	s_cmp_lt_i32 s11, s13
	s_cselect_b64 s[0:1], -1, 0
	s_cmp_gt_i32 s11, s2
	s_cselect_b64 s[4:5], -1, 0
	s_or_b64 s[0:1], s[0:1], s[4:5]
	s_and_b64 vcc, exec, s[0:1]
	s_cbranch_vccnz .LBB0_385
	s_cmp_lt_i32 s11, s14
	s_cbranch_scc1 .Lt2far_1
	v_add_u32_e32 v40, s16, v139
	ds_read_b128 v[32:35], v40
	ds_read_b128 v[36:39], v40 offset:512
	s_mov_b64 s[4:5], -1
	s_cmp_lt_i32 s11, s14
	s_waitcnt vmcnt(5) lgkmcnt(1)
	v_mfma_f32_32x32x16_bf16 v[80:95], v[32:35], v[104:107], 0
	s_waitcnt lgkmcnt(0)
	v_mfma_f32_32x32x16_bf16 v[64:79], v[36:39], v[104:107], 0
	ds_read_b128 v[32:35], v40 offset:2048
	ds_read_b128 v[36:39], v40 offset:2560
	s_waitcnt lgkmcnt(1)
	v_mfma_f32_32x32x16_bf16 v[80:95], v[32:35], v[96:99], v[80:95]
	s_waitcnt lgkmcnt(0)
	v_mfma_f32_32x32x16_bf16 v[64:79], v[36:39], v[96:99], v[64:79]
	ds_read_b128 v[32:35], v40 offset:4096
	ds_read_b128 v[36:39], v40 offset:4608
	s_waitcnt lgkmcnt(1)
	v_mfma_f32_32x32x16_bf16 v[80:95], v[32:35], v[100:103], v[80:95]
	ds_read_b128 v[32:35], v40 offset:6144
	ds_read_b128 v[146:149], v40 offset:6656
	s_waitcnt lgkmcnt(2)
	v_mfma_f32_32x32x16_bf16 v[64:79], v[36:39], v[100:103], v[64:79]
	s_waitcnt vmcnt(4) lgkmcnt(1)
	v_mfma_f32_32x32x16_bf16 v[80:95], v[32:35], v[108:111], v[80:95]
	s_waitcnt lgkmcnt(0)
	v_mfma_f32_32x32x16_bf16 v[64:79], v[146:149], v[108:111], v[64:79]
	s_cbranch_scc1 .LBB0_397
	v_lshl_add_u32 v230, v141, 2, v162
	s_nop 3
	ds_read_b32 v33, v230 offset:236
	ds_read_b32 v40, v230 offset:108
	ds_read_b32 v35, v230 offset:232
	ds_read_b32 v34, v230 offset:104
	ds_read_b32 v37, v230 offset:228
	ds_read_b32 v36, v230 offset:100
	ds_read_b32 v39, v230 offset:224
	ds_read_b32 v38, v230 offset:96
	s_waitcnt lgkmcnt(7)
	v_add_f32_e32 v32, v80, v33
	s_waitcnt lgkmcnt(6)
	v_add_f32_e32 v33, v64, v40
	v_exp_f32_e32 v48, v33
	s_waitcnt lgkmcnt(5)
	v_add_f32_e32 v33, v81, v35
	s_waitcnt lgkmcnt(2)
	v_add_f32_e32 v35, v66, v36
	s_waitcnt lgkmcnt(0)
	v_add_f32_e32 v36, v67, v38
	v_add_f32_e32 v34, v65, v34
	v_exp_f32_e32 v51, v36
	v_exp_f32_e32 v49, v34
	v_add_f32_e32 v34, v82, v37
	v_exp_f32_e32 v50, v35
	v_add_f32_e32 v35, v83, v39
	ds_read_b32 v37, v230 offset:204
	ds_read_b32 v44, v230 offset:76
	ds_read_b32 v39, v230 offset:200
	ds_read_b32 v38, v230 offset:72
	ds_read_b32 v41, v230 offset:196
	ds_read_b32 v40, v230 offset:68
	ds_read_b32 v43, v230 offset:192
	ds_read_b32 v42, v230 offset:64
	s_waitcnt lgkmcnt(7)
	v_add_f32_e32 v36, v84, v37
	s_waitcnt lgkmcnt(6)
	v_add_f32_e32 v37, v68, v44
	v_exp_f32_e32 v52, v37
	s_waitcnt lgkmcnt(5)
	v_add_f32_e32 v37, v85, v39
	s_waitcnt lgkmcnt(2)
	v_add_f32_e32 v39, v70, v40
	s_waitcnt lgkmcnt(0)
	v_add_f32_e32 v40, v71, v42
	v_add_f32_e32 v38, v69, v38
	v_exp_f32_e32 v55, v40
	v_exp_f32_e32 v53, v38
	v_add_f32_e32 v38, v86, v41
	v_exp_f32_e32 v54, v39
	v_add_f32_e32 v39, v87, v43
	ds_read_b32 v41, v230 offset:172
	ds_read_b32 v56, v230 offset:44
	ds_read_b32 v43, v230 offset:168
	ds_read_b32 v42, v230 offset:40
	ds_read_b32 v45, v230 offset:164
	ds_read_b32 v44, v230 offset:36
	ds_read_b32 v47, v230 offset:160
	ds_read_b32 v46, v230 offset:32
	s_waitcnt lgkmcnt(7)
	v_add_f32_e32 v40, v88, v41
	s_waitcnt lgkmcnt(6)
	v_add_f32_e32 v41, v72, v56
	v_exp_f32_e32 v56, v41
	s_waitcnt lgkmcnt(5)
	v_add_f32_e32 v41, v89, v43
	s_waitcnt lgkmcnt(2)
	v_add_f32_e32 v43, v74, v44
	s_waitcnt lgkmcnt(0)
	v_add_f32_e32 v44, v75, v46
	v_add_f32_e32 v42, v73, v42
	v_exp_f32_e32 v59, v44
	v_exp_f32_e32 v57, v42
	v_add_f32_e32 v42, v90, v45
	v_exp_f32_e32 v58, v43
	v_add_f32_e32 v43, v91, v47
	ds_read_b32 v45, v230 offset:140
	ds_read_b32 v142, v230 offset:12
	ds_read_b32 v47, v230 offset:136
	ds_read_b32 v46, v230 offset:8
	ds_read_b32 v143, v230 offset:132
	ds_read_b32 v144, v230 offset:4
	ds_read_b32 v146, v230 offset:128
	ds_read_b32 v63, v230
	s_waitcnt lgkmcnt(7)
	v_add_f32_e32 v44, v92, v45
	s_waitcnt lgkmcnt(6)
	v_add_f32_e32 v45, v76, v142
	v_exp_f32_e32 v60, v45
	s_waitcnt lgkmcnt(5)
	v_add_f32_e32 v45, v93, v47
	s_waitcnt lgkmcnt(4)
	v_add_f32_e32 v46, v77, v46
	s_waitcnt lgkmcnt(2)
	v_add_f32_e32 v47, v78, v144
	v_exp_f32_e32 v61, v46
	v_add_f32_e32 v46, v94, v143
	v_exp_f32_e32 v62, v47
	s_waitcnt lgkmcnt(1)
	v_add_f32_e32 v47, v95, v146
	v_exp_f32_e32 v32, v32
	v_exp_f32_e32 v33, v33
	v_exp_f32_e32 v34, v34
	v_exp_f32_e32 v35, v35
	v_exp_f32_e32 v36, v36
	v_exp_f32_e32 v37, v37
	v_exp_f32_e32 v38, v38
	v_exp_f32_e32 v39, v39
	v_exp_f32_e32 v40, v40
	v_exp_f32_e32 v41, v41
	v_exp_f32_e32 v42, v42
	v_exp_f32_e32 v43, v43
	v_exp_f32_e32 v44, v44
	v_exp_f32_e32 v45, v45
	v_exp_f32_e32 v46, v46
	v_exp_f32_e32 v47, v47
	s_waitcnt lgkmcnt(0)
	v_add_f32_e32 v63, v79, v63
	s_mov_b64 s[4:5], 0

; #define LAS __attribute__((address_space(3)))
; template <int TYPE> __device__ __forceinline__ void attn_unit(const AttnCtx& C, int b, int h, int qb, LAS unsigned char* lds, int tid_in, unsigned* counter) {
;     ...
;                 f32x16 p0, p1;
;                 const LAS unsigned char* kp = Kb + bo + hi * 1024 + r32 * 16;
; #pragma unroll
;                 for (int d0 = 0; d0 < 4; ++d0) {
;                     const bf16x8 a0 = *(const LAS bf16x8*)(kp + d0 * 2048), a1 = *(const LAS bf16x8*)(kp + d0 * 2048 + 512);
;                     if (d0 == 0) { p0 = MFMA32(a0, qr[0], (TYPE == 1 ? cvec : zvec)); p1 = MFMA32(a1, qr[0], (TYPE == 1 ? cvec : zvec)); }
;                     else { p0 = MFMA32(a0, qr[d0], p0); p1 = MFMA32(a1, qr[d0], p1); }
;                 }
;                 const int xi = sq - 64 * t - 4 * hi;
;                 if (TYPE == 0) {
;                     const float xf = (float)xi;
; #pragma unroll
;                     for (int r = 0; r < 16; ++r) { const float c = (float)((r & 3) + 8 * (r >> 2));
;                         p0[r] = fast_exp2(p0[r] - sl2 * fabsf(xf - c)); p1[r] = fast_exp2(p1[r] - sl2 * fabsf(xf - (c + 32.f))); }
;                 } else if (TYPE == 1) {
;                     const LAS float* fp = Fb + (t & 3) * 64 + 4 * hi;
; #pragma unroll
;                     for (int g = 0; g < 4; ++g) { const f32x4 fa = *(const LAS f32x4*)(fp + 8 * g), fb2 = *(const LAS f32x4*)(fp + 32 + 8 * g);
; #pragma unroll
;                         for (int i = 0; i < 4; i += 2) {
;                             const f32x2_t d0_ = (f32x2_t){p0[4 * g + i], p0[4 * g + i + 1]} - (f32x2_t){fa[i], fa[i + 1]}, d1_ = (f32x2_t){p1[4 * g + i], p1[4 * g + i + 1]} - (f32x2_t){fb2[i], fb2[i + 1]};
;                             p0[4 * g + i] = fast_exp2(d0_[0]); p0[4 * g + i + 1] = fast_exp2(d0_[1]); p1[4 * g + i] = fast_exp2(d1_[0]); p1[4 * g + i + 1] = fast_exp2(d1_[1]); } }
;                     if (t == cq) { const int qrel = 32 * (w & 1) + r32;
; #pragma unroll
;                         for (int r = 0; r < 16; ++r) { const int kv = crow(r, hi); if (kv > qrel) p0[r] = 0.f; if (kv + 32 > qrel) p1[r] = 0.f; } }
;                 } else {
;                     if (cq - t >= 3) { const float bc = relb[256];
; #pragma unroll
;                         for (int r = 0; r < 16; ++r) { p0[r] = fast_exp2(p0[r] + bc); p1[r] = fast_exp2(p1[r] + bc); }
.Lt2far_1:
	v_add_u32_e32 v40, s16, v139
	ds_read_b128 v[32:35], v40
	ds_read_b128 v[36:39], v40 offset:512
	s_waitcnt vmcnt(5) lgkmcnt(1)
	v_mfma_f32_32x32x16_bf16 v[80:95], v[32:35], v[104:107], v[214:229]
	s_waitcnt lgkmcnt(0)
	v_mfma_f32_32x32x16_bf16 v[64:79], v[36:39], v[104:107], v[214:229]
	ds_read_b128 v[32:35], v40 offset:2048
	ds_read_b128 v[36:39], v40 offset:2560
	s_waitcnt lgkmcnt(1)
	v_mfma_f32_32x32x16_bf16 v[80:95], v[32:35], v[96:99], v[80:95]
	s_waitcnt lgkmcnt(0)
	v_mfma_f32_32x32x16_bf16 v[64:79], v[36:39], v[96:99], v[64:79]
	ds_read_b128 v[32:35], v40 offset:4096
	ds_read_b128 v[36:39], v40 offset:4608
	s_waitcnt lgkmcnt(1)
	v_mfma_f32_32x32x16_bf16 v[80:95], v[32:35], v[100:103], v[80:95]
	ds_read_b128 v[32:35], v40 offset:6144
	ds_read_b128 v[146:149], v40 offset:6656
	s_waitcnt lgkmcnt(2)
	v_mfma_f32_32x32x16_bf16 v[64:79], v[36:39], v[100:103], v[64:79]
	s_waitcnt vmcnt(4) lgkmcnt(1)
	v_mfma_f32_32x32x16_bf16 v[80:95], v[32:35], v[108:111], v[80:95]
	s_waitcnt lgkmcnt(0)
	v_mfma_f32_32x32x16_bf16 v[64:79], v[146:149], v[108:111], v[64:79]
	s_nop 11
	v_exp_f32_e32 v48, v64
	v_exp_f32_e32 v33, v81
	v_exp_f32_e32 v49, v65
	v_exp_f32_e32 v50, v66
	v_exp_f32_e32 v51, v67
	v_exp_f32_e32 v52, v68
	v_exp_f32_e32 v53, v69
	v_exp_f32_e32 v54, v70
	v_exp_f32_e32 v55, v71
	v_exp_f32_e32 v56, v72
	v_exp_f32_e32 v57, v73
	v_exp_f32_e32 v58, v74
	v_exp_f32_e32 v59, v75
	v_exp_f32_e32 v60, v76
	v_exp_f32_e32 v61, v77
	v_exp_f32_e32 v62, v78
	v_exp_f32_e32 v32, v80
	v_exp_f32_e32 v34, v82
	v_exp_f32_e32 v35, v83
	v_exp_f32_e32 v36, v84
	v_exp_f32_e32 v37, v85
	v_exp_f32_e32 v38, v86
	v_exp_f32_e32 v39, v87
	v_exp_f32_e32 v40, v88
	v_exp_f32_e32 v41, v89
	v_exp_f32_e32 v42, v90
	v_exp_f32_e32 v43, v91
	v_exp_f32_e32 v44, v92
	v_exp_f32_e32 v45, v93
	v_exp_f32_e32 v46, v94
	v_exp_f32_e32 v47, v95
	v_mov_b32_e32 v63, v79
	s_branch .LBB0_384

; __device__ __forceinline__ float row_rstd(const u64_t* rsq, int row) { return fast_rsq(rsq_sum(rsq, row) * (1.0f / DM) + EPS); }
; #define PG8_EPI_BAR() do { asm volatile("s_waitcnt lgkmcnt(0)" ::: "memory"); __builtin_amdgcn_s_barrier(); asm volatile("" ::: "memory"); } while (0)
;     __device__ __forceinline__ void run(const f32x4 (&acc)[2][2][4][2], const Unit& u, const Unit& nxt, bool has_next, int ui, int wr, int wc, int fr_in, int fq_in) const {
;         int fr = fr_in, fq = fq_in; asm volatile("" : "+v"(fr), "+v"(fq));
;         const int tid = (wr * 4 + wc) * 64 + fq * 16 + fr;
;         const int slot = ui & 1;
;         if (ui == 0) {
;             prm[slot * 1024 + tid] = ldp(tid, u.pn); prm[slot * 1024 + tid + 512] = ldp(tid + 512, u.pn);
;             if (tid < 256) rsd[slot * 256 + tid] = row_rstd(rsq, u.pm * BM + tid);
;             PG8_EPI_BAR();
.LBB0_693:
	v_bfe_u32 v73, v226, 7, 2
	v_ashrrev_i32_e32 v72, 9, v226
	v_and_b32_e32 v74, 0x7f, v226
	v_mul_u32_u24_e32 v75, 0x1600, v73
	v_cmp_eq_u32_e64 s[10:11], 3, v73
	v_add_u32_e32 v102, 0x200, v226
	v_mul_i32_i24_e32 v72, 0xb00, v72
	v_cndmask_b32_e64 v100, v75, 0, s[10:11]
	v_lshl_or_b32 v101, s44, 7, v74
	v_mov_b32_e32 v73, s7
	v_mov_b32_e32 v74, s9
	v_ashrrev_i32_e32 v102, 9, v102
	v_add3_u32 v72, v101, v72, v100
	v_cndmask_b32_e64 v75, v73, v74, s[10:11]
	v_mov_b32_e32 v73, s6
	v_mov_b32_e32 v74, s8
	v_mul_i32_i24_e32 v102, 0xb00, v102
	v_cndmask_b32_e64 v74, v73, v74, s[10:11]
	v_ashrrev_i32_e32 v73, 31, v72
	v_add3_u32 v100, v102, v101, v100
	v_lshl_add_u64 v[72:73], v[72:73], 2, v[74:75]
	v_ashrrev_i32_e32 v101, 31, v100
	v_lshl_add_u64 v[74:75], v[100:101], 2, v[74:75]
	global_load_dword v72, v[72:73], off
	s_nop 0
	global_load_dword v73, v[74:75], off
	v_lshl_add_u32 v74, v226, 2, v224
	s_waitcnt vmcnt(0)
	v_mul_f32_e32 v72, 0xbfb8aa3b, v72
	v_mul_f32_e32 v73, 0xbf317218, v73
	ds_write2st64_b32 v74, v72, v73 offset1:8
	s_and_saveexec_b64 s[0:1], vcc
	s_cbranch_execz .LBB0_695
	v_lshl_add_u32 v72, s42, 8, v226
	v_ashrrev_i32_e32 v73, 31, v72
	v_lshl_add_u64 v[72:73], v[72:73], 3, s[22:23]
	global_load_dwordx2 v[72:73], v[72:73], off
	s_waitcnt vmcnt(0)
	v_ffbh_u32_e32 v74, v73
	v_min_u32_e32 v74, 32, v74
	v_lshlrev_b64 v[72:73], v74, v[72:73]
	v_min_u32_e32 v72, 1, v72
	v_or_b32_e32 v72, v73, v72
	v_cvt_f32_u32_e32 v72, v72
	v_sub_u32_e32 v73, 32, v74
	v_ldexp_f32 v72, v72, v73
	v_mul_f32_e32 v72, 0x33800000, v72
	v_fmamk_f32 v72, v72, 0x3a800000, v223
	v_rsq_f32_e32 v72, v72
	v_lshl_add_u32 v73, v226, 2, v225
	ds_write_b32 v73, v72

; __device__ __forceinline__ unsigned pk2(float lo, float hi) { f32x2_t v = {lo, hi}; bf16x2_t b = __builtin_convertvector(v, bf16x2_t); return __builtin_bit_cast(unsigned, b); }
; #define DPPF(v, ctrl) __builtin_bit_cast(float, __builtin_amdgcn_update_dpp(0, __builtin_bit_cast(int, (v)), (ctrl), 0xf, 0xf, false))
; __device__ __forceinline__ float sigmoidf_(float v) { return fast_rcp(1.0f + fast_exp2(-v * LOG2E)); }
; #define PG8_LAS __attribute__((address_space(3)))
;     __device__ __forceinline__ void run(const f32x4 (&acc)[2][2][4][2], const Unit& u, const Unit& nxt, bool has_next, int ui, int wr, int wc, int fr_in, int fq_in) const {
;     ...
;                 if (grp > 0 && fr == 0) { const PG8_LAS float* xp = xr + ((grp - 1) * 2) * 256 + cl;
;                     hg2 = *(const PG8_LAS f32x4*)(xp); hg3 = *(const PG8_LAS f32x4*)(xp + 256); hv2 = *(const PG8_LAS f32x4*)(xp + 128); hv3 = *(const PG8_LAS f32x4*)(xp + 256 + 128); }
;                 f32x4 pg2, pg1, pv2, pv1;
;                 {
;                     const f32x4 g2 = acc[ai][0][2][n] * rs[ai][2], g3 = acc[ai][0][3][n] * rs[ai][3], v2 = acc[ai][1][2][n] * rs[ai][2], v3 = acc[ai][1][3][n] * rs[ai][3];
; #pragma unroll
;                     for (int i = 0; i < 4; ++i) {
;                         float a0 = g2[i], a1 = g3[i], a2 = v2[i], a3 = v3[i];
;                         asm volatile("" : "+v"(a0), "+v"(a1), "+v"(a2), "+v"(a3));
;                         const float t0 = DPPF(a0, 0x111), t1 = DPPF(a1, 0x111), t2 = DPPF(a2, 0x111), t3 = DPPF(a3, 0x111);
;                         pg2[i] = t0 + hg2[i]; pg1[i] = t1 + hg3[i]; pv2[i] = t2 + hv2[i]; pv1[i] = t3 + hv3[i]; }
;                 }
; #pragma unroll
;                 for (int m = 0; m < 4; ++m) {
;                     const f32x4 gc = acc[ai][0][m][n] * rs[ai][m], vc = acc[ai][1][m][n] * rs[ai][m];
;                     const f32x4 cgt = bg + wg0 * pg2 + wg1 * pg1 + wg2 * gc, cvl = bv + wv0 * pv2 + wv1 * pv1 + wv2 * vc;
;                     float a[4];
; #pragma unroll
;                     for (int i = 0; i < 4; ++i) a[i] = cgt[i] * sigmoidf_(cgt[i]) * cvl[i];
;                     u32x2 w; w.x = pk2(a[0], a[1]); w.y = pk2(a[2], a[3]);
;                     *(u32x2*)(A + (size_t)(u.pm * BM + ai * 128 + wr * 64 + 4 * fr + m) * DFF + ch) = w;
;                     pg2 = pg1; pg1 = gc; pv2 = pv1; pv1 = vc;
;                 }
.LBB0_719:
	s_or_b64 exec, exec, s[0:1]
	s_lshl_b32 s0, s42, 8
	s_add_i32 s0, s0, s57
	v_lshl_add_u32 v231, v169, 2, s0
	v_mul_f32_e32 v169, v116, v102
	v_mul_f32_e32 v235, v108, v103
	v_mul_f32_e32 v237, v112, v102
	v_mul_f32_e32 v239, v104, v103
	v_mov_b32_dpp v234, v169 row_shr:1 row_mask:0xf bank_mask:0xf bound_ctrl:1
	s_nop 0
	v_mov_b32_dpp v240, v239 row_shr:1 row_mask:0xf bank_mask:0xf bound_ctrl:1
	v_mul_f32_e32 v169, v117, v102
	v_mul_f32_e32 v239, v109, v103
	v_mul_f32_e32 v241, v113, v102
	v_mul_f32_e32 v242, v105, v103
	v_mov_b32_dpp v236, v235 row_shr:1 row_mask:0xf bank_mask:0xf bound_ctrl:1
	v_mov_b32_dpp v238, v237 row_shr:1 row_mask:0xf bank_mask:0xf bound_ctrl:1
	v_mul_f32_e32 v243, v110, v103
	v_mov_b32_dpp v235, v169 row_shr:1 row_mask:0xf bank_mask:0xf bound_ctrl:1
	v_mov_b32_dpp v237, v239 row_shr:1 row_mask:0xf bank_mask:0xf bound_ctrl:1
	v_mul_f32_e32 v169, v118, v102
	v_mul_f32_e32 v245, v114, v102
	v_mov_b32_dpp v239, v241 row_shr:1 row_mask:0xf bank_mask:0xf bound_ctrl:1
	v_mul_f32_e32 v247, v106, v103
	s_waitcnt lgkmcnt(0)
	v_pk_add_f32 v[182:183], v[182:183], v[234:235]
	v_mov_b32_dpp v241, v242 row_shr:1 row_mask:0xf bank_mask:0xf bound_ctrl:1
	v_pk_add_f32 v[178:179], v[178:179], v[236:237]
	v_pk_fma_f32 v[182:183], v[152:153], v[182:183], v[164:165]
	v_mov_b32_dpp v242, v169 row_shr:1 row_mask:0xf bank_mask:0xf bound_ctrl:1
	v_mov_b32_dpp v248, v247 row_shr:1 row_mask:0xf bank_mask:0xf bound_ctrl:1
	v_mul_f32_e32 v169, v119, v102
	v_mul_f32_e32 v247, v111, v103
	v_mul_f32_e32 v249, v115, v102
	v_mul_f32_e32 v250, v107, v103
	v_pk_mul_f32 v[132:133], v[132:133], v[100:101] op_sel_hi:[1,0]
	v_pk_fma_f32 v[182:183], v[156:157], v[178:179], v[182:183]
	v_mov_b32_dpp v244, v243 row_shr:1 row_mask:0xf bank_mask:0xf bound_ctrl:1
	v_pk_fma_f32 v[182:183], v[132:133], v[160:161], v[182:183]
	v_mov_b32_dpp v243, v169 row_shr:1 row_mask:0xf bank_mask:0xf bound_ctrl:1
	v_exp_f32_e32 v169, v182
	v_exp_f32_e32 v235, v183
	v_mov_b32_dpp v246, v245 row_shr:1 row_mask:0xf bank_mask:0xf bound_ctrl:1
	v_add_f32_e32 v169, 1.0, v169
	v_rcp_f32_e32 v234, v169
	v_add_f32_e32 v169, 1.0, v235
	v_rcp_f32_e32 v235, v169
	v_pk_mul_f32 v[236:237], v[128:129], v[100:101] op_sel_hi:[1,0]
	v_pk_add_f32 v[128:129], v[174:175], v[238:239]
	v_mov_b32_dpp v245, v247 row_shr:1 row_mask:0xf bank_mask:0xf bound_ctrl:1
	v_pk_mul_f32 v[174:175], v[182:183], v[234:235]
	v_pk_add_f32 v[182:183], v[184:185], v[242:243]
	v_pk_add_f32 v[180:181], v[180:181], v[244:245]
	v_pk_fma_f32 v[182:183], v[154:155], v[182:183], v[166:167]
	v_pk_mul_f32 v[134:135], v[134:135], v[100:101] op_sel_hi:[1,0]
	v_pk_fma_f32 v[182:183], v[158:159], v[180:181], v[182:183]
	v_pk_add_f32 v[170:171], v[170:171], v[240:241]
	v_pk_fma_f32 v[182:183], v[134:135], v[162:163], v[182:183]
	v_pk_fma_f32 v[128:129], v[136:137], v[128:129], v[148:149]
	v_exp_f32_e32 v169, v182
	v_exp_f32_e32 v185, v183
	v_add_f32_e32 v169, 1.0, v169
	v_pk_fma_f32 v[128:129], v[140:141], v[170:171], v[128:129]
	v_rcp_f32_e32 v184, v169
	v_add_f32_e32 v169, 1.0, v185
	v_mov_b32_dpp v247, v249 row_shr:1 row_mask:0xf bank_mask:0xf bound_ctrl:1
	v_pk_fma_f32 v[128:129], v[236:237], v[144:145], v[128:129]
	v_rcp_f32_e32 v185, v169
	v_mov_b32_dpp v249, v250 row_shr:1 row_mask:0xf bank_mask:0xf bound_ctrl:1
	v_pk_mul_f32 v[128:129], v[128:129], v[174:175]
	v_pk_add_f32 v[174:175], v[176:177], v[246:247]
	v_pk_add_f32 v[172:173], v[172:173], v[248:249]
	v_pk_fma_f32 v[174:175], v[138:139], v[174:175], v[150:151]
	s_lshl_b32 s16, s44, 7
	v_pk_mul_f32 v[130:131], v[130:131], v[100:101] op_sel_hi:[1,0]
	v_pk_fma_f32 v[174:175], v[142:143], v[172:173], v[174:175]
	v_add_u32_e32 v232, s16, v202
	v_pk_mul_f32 v[176:177], v[182:183], v[184:185]
	v_pk_fma_f32 v[174:175], v[130:131], v[146:147], v[174:175]
	v_ashrrev_i32_e32 v233, 31, v232
	v_pk_mul_f32 v[174:175], v[174:175], v[176:177]
	v_pk_fma_f32 v[178:179], v[152:153], v[178:179], v[164:165]
	v_cvt_pk_bf16_f32 v177, v174, v175
	v_lshlrev_b64 v[174:175], 1, v[232:233]
	v_mov_b32_e32 v232, v101
	v_pk_mul_f32 v[124:125], v[124:125], v[232:233] op_sel_hi:[1,0]
	v_pk_fma_f32 v[178:179], v[132:133], v[156:157], v[178:179]
	v_mov_b64_e32 v[182:183], s[20:21]
	v_pk_fma_f32 v[178:179], v[124:125], v[160:161], v[178:179]
	v_cvt_pk_bf16_f32 v176, v128, v129
	v_exp_f32_e32 v169, v178
	v_exp_f32_e32 v233, v179
	v_mad_i64_i32 v[128:129], s[0:1], v231, s74, v[182:183]
	v_lshl_add_u64 v[184:185], v[128:129], 0, v[174:175]
	v_add_f32_e32 v169, 1.0, v169
	global_store_dwordx2 v[184:185], v[176:177], off
	v_rcp_f32_e32 v176, v169
	v_add_f32_e32 v169, 1.0, v233
	v_rcp_f32_e32 v177, v169
	v_pk_mul_f32 v[184:185], v[126:127], v[232:233] op_sel_hi:[1,0]
	v_pk_fma_f32 v[132:133], v[132:133], v[152:153], v[164:165]
	v_pk_fma_f32 v[170:171], v[136:137], v[170:171], v[148:149]
	v_pk_mul_f32 v[126:127], v[178:179], v[176:177]
	v_pk_fma_f32 v[176:177], v[154:155], v[180:181], v[166:167]
	v_pk_mul_f32 v[116:117], v[116:117], v[102:103] op_sel_hi:[1,0]
	v_pk_fma_f32 v[176:177], v[134:135], v[158:159], v[176:177]
	v_pk_fma_f32 v[132:133], v[124:125], v[156:157], v[132:133]
	v_pk_fma_f32 v[176:177], v[184:185], v[162:163], v[176:177]
	v_pk_mul_f32 v[120:121], v[120:121], v[232:233] op_sel_hi:[1,0]
	v_exp_f32_e32 v169, v176
	v_exp_f32_e32 v179, v177
	v_pk_fma_f32 v[170:171], v[236:237], v[140:141], v[170:171]
	v_add_f32_e32 v169, 1.0, v169
	v_rcp_f32_e32 v178, v169
	v_add_f32_e32 v169, 1.0, v179
	v_rcp_f32_e32 v179, v169
	v_pk_fma_f32 v[132:133], v[116:117], v[160:161], v[132:133]
	v_pk_fma_f32 v[170:171], v[120:121], v[144:145], v[170:171]
	v_pk_fma_f32 v[172:173], v[138:139], v[172:173], v[150:151]
; __device__ __forceinline__ unsigned pk2(float lo, float hi) { f32x2_t v = {lo, hi}; bf16x2_t b = __builtin_convertvector(v, bf16x2_t); return __builtin_bit_cast(unsigned, b); }
; #define DPPF(v, ctrl) __builtin_bit_cast(float, __builtin_amdgcn_update_dpp(0, __builtin_bit_cast(int, (v)), (ctrl), 0xf, 0xf, false))
; __device__ __forceinline__ float sigmoidf_(float v) { return fast_rcp(1.0f + fast_exp2(-v * LOG2E)); }
; #define PG8_LAS __attribute__((address_space(3)))
;     __device__ __forceinline__ void run(const f32x4 (&acc)[2][2][4][2], const Unit& u, const Unit& nxt, bool has_next, int ui, int wr, int wc, int fr_in, int fq_in) const {
;     ...
;                 if (grp > 0 && fr == 0) { const PG8_LAS float* xp = xr + ((grp - 1) * 2) * 256 + cl;
;                     hg2 = *(const PG8_LAS f32x4*)(xp); hg3 = *(const PG8_LAS f32x4*)(xp + 256); hv2 = *(const PG8_LAS f32x4*)(xp + 128); hv3 = *(const PG8_LAS f32x4*)(xp + 256 + 128); }
;                 f32x4 pg2, pg1, pv2, pv1;
;                 {
;                     const f32x4 g2 = acc[ai][0][2][n] * rs[ai][2], g3 = acc[ai][0][3][n] * rs[ai][3], v2 = acc[ai][1][2][n] * rs[ai][2], v3 = acc[ai][1][3][n] * rs[ai][3];
; #pragma unroll
;                     for (int i = 0; i < 4; ++i) {
;                         float a0 = g2[i], a1 = g3[i], a2 = v2[i], a3 = v3[i];
;                         asm volatile("" : "+v"(a0), "+v"(a1), "+v"(a2), "+v"(a3));
;                         const float t0 = DPPF(a0, 0x111), t1 = DPPF(a1, 0x111), t2 = DPPF(a2, 0x111), t3 = DPPF(a3, 0x111);
;                         pg2[i] = t0 + hg2[i]; pg1[i] = t1 + hg3[i]; pv2[i] = t2 + hv2[i]; pv1[i] = t3 + hv3[i]; }
;                 }
; #pragma unroll
;                 for (int m = 0; m < 4; ++m) {
;                     const f32x4 gc = acc[ai][0][m][n] * rs[ai][m], vc = acc[ai][1][m][n] * rs[ai][m];
;                     const f32x4 cgt = bg + wg0 * pg2 + wg1 * pg1 + wg2 * gc, cvl = bv + wv0 * pv2 + wv1 * pv1 + wv2 * vc;
;                     float a[4];
; #pragma unroll
;                     for (int i = 0; i < 4; ++i) a[i] = cgt[i] * sigmoidf_(cgt[i]) * cvl[i];
;                     u32x2 w; w.x = pk2(a[0], a[1]); w.y = pk2(a[2], a[3]);
;                     *(u32x2*)(A + (size_t)(u.pm * BM + ai * 128 + wr * 64 + 4 * fr + m) * DFF + ch) = w;
;                     pg2 = pg1; pg1 = gc; pv2 = pv1; pv1 = vc;
;                 }
	v_pk_mul_f32 v[122:123], v[122:123], v[232:233] op_sel_hi:[1,0]
	v_pk_mul_f32 v[126:127], v[170:171], v[126:127]
	v_pk_mul_f32 v[170:171], v[176:177], v[178:179]
	v_pk_fma_f32 v[172:173], v[130:131], v[142:143], v[172:173]
	v_exp_f32_e32 v169, v132
	v_pk_fma_f32 v[172:173], v[122:123], v[146:147], v[172:173]
	v_exp_f32_e32 v176, v133
	v_pk_mul_f32 v[170:171], v[172:173], v[170:171]
	v_cvt_pk_bf16_f32 v172, v126, v127
	v_or_b32_e32 v126, 1, v231
	v_mad_i64_i32 v[126:127], s[0:1], v126, s74, v[182:183]
	v_cvt_pk_bf16_f32 v173, v170, v171
	v_lshl_add_u64 v[170:171], v[126:127], 0, v[174:175]
	v_add_f32_e32 v169, 1.0, v169
	global_store_dwordx2 v[170:171], v[172:173], off
	v_rcp_f32_e32 v170, v169
	v_add_f32_e32 v169, 1.0, v176
	v_rcp_f32_e32 v171, v169
	v_pk_fma_f32 v[134:135], v[134:135], v[154:155], v[166:167]
	v_pk_mul_f32 v[118:119], v[118:119], v[102:103] op_sel_hi:[1,0]
	v_pk_fma_f32 v[134:135], v[184:185], v[158:159], v[134:135]
	v_pk_mul_f32 v[132:133], v[132:133], v[170:171]
	v_pk_fma_f32 v[134:135], v[118:119], v[162:163], v[134:135]
	v_pk_mul_f32 v[112:113], v[112:113], v[102:103] op_sel_hi:[1,0]
	v_exp_f32_e32 v173, v135
	v_pk_fma_f32 v[170:171], v[236:237], v[136:137], v[148:149]
	v_pk_fma_f32 v[124:125], v[124:125], v[152:153], v[164:165]
	v_pk_fma_f32 v[170:171], v[120:121], v[140:141], v[170:171]
	v_pk_fma_f32 v[116:117], v[116:117], v[156:157], v[124:125]
	v_pk_fma_f32 v[170:171], v[112:113], v[144:145], v[170:171]
	v_pk_mul_f32 v[132:133], v[170:171], v[132:133]
	v_mov_b32_e32 v170, v103
	v_pk_mul_f32 v[108:109], v[108:109], v[170:171] op_sel_hi:[1,0]
	v_pk_mul_f32 v[110:111], v[110:111], v[170:171] op_sel_hi:[1,0]
	v_pk_fma_f32 v[108:109], v[108:109], v[160:161], v[116:117]
	v_exp_f32_e32 v169, v134
	v_exp_f32_e32 v116, v108
	v_exp_f32_e32 v117, v109
	v_add_f32_e32 v169, 1.0, v169
	v_rcp_f32_e32 v172, v169
	v_add_f32_e32 v116, 1.0, v116
	v_add_f32_e32 v117, 1.0, v117
	v_rcp_f32_e32 v116, v116
	v_rcp_f32_e32 v117, v117
	v_add_f32_e32 v169, 1.0, v173
	v_rcp_f32_e32 v173, v169
	v_pk_mul_f32 v[104:105], v[104:105], v[170:171] op_sel_hi:[1,0]
	v_pk_mul_f32 v[108:109], v[108:109], v[116:117]
	v_pk_fma_f32 v[116:117], v[184:185], v[154:155], v[166:167]
	v_pk_mul_f32 v[114:115], v[114:115], v[102:103] op_sel_hi:[1,0]
	v_pk_fma_f32 v[116:117], v[118:119], v[158:159], v[116:117]
	v_pk_fma_f32 v[130:131], v[130:131], v[138:139], v[150:151]
	v_pk_fma_f32 v[110:111], v[110:111], v[162:163], v[116:117]
	v_pk_fma_f32 v[130:131], v[122:123], v[142:143], v[130:131]
	v_exp_f32_e32 v118, v110
	v_exp_f32_e32 v119, v111
	v_pk_fma_f32 v[116:117], v[120:121], v[136:137], v[148:149]
	v_add_f32_e32 v118, 1.0, v118
	v_rcp_f32_e32 v118, v118
	v_add_f32_e32 v119, 1.0, v119
	v_rcp_f32_e32 v119, v119
	v_pk_fma_f32 v[112:113], v[112:113], v[140:141], v[116:117]
	v_pk_mul_f32 v[106:107], v[106:107], v[170:171] op_sel_hi:[1,0]
	v_pk_fma_f32 v[104:105], v[104:105], v[144:145], v[112:113]
	v_pk_mul_f32 v[134:135], v[134:135], v[172:173]
	v_pk_mul_f32 v[104:105], v[104:105], v[108:109]
	v_pk_mul_f32 v[108:109], v[110:111], v[118:119]
	v_pk_fma_f32 v[110:111], v[122:123], v[138:139], v[150:151]
	v_pk_fma_f32 v[130:131], v[114:115], v[146:147], v[130:131]
	v_pk_fma_f32 v[110:111], v[114:115], v[142:143], v[110:111]
	v_pk_mul_f32 v[130:131], v[130:131], v[134:135]
	v_pk_fma_f32 v[106:107], v[106:107], v[146:147], v[110:111]
	v_cvt_pk_bf16_f32 v135, v130, v131
	v_pk_mul_f32 v[106:107], v[106:107], v[108:109]
	v_or_b32_e32 v130, 2, v231
	v_cvt_pk_bf16_f32 v104, v104, v105
	v_cvt_pk_bf16_f32 v105, v106, v107
	v_or_b32_e32 v106, 3, v231
	v_cvt_pk_bf16_f32 v134, v132, v133
	v_mad_i64_i32 v[132:133], s[0:1], v130, s74, v[182:183]
	v_mad_i64_i32 v[172:173], s[0:1], v106, s74, v[182:183]
	v_lshl_add_u64 v[130:131], v[132:133], 0, v[174:175]
	v_lshl_add_u64 v[106:107], v[172:173], 0, v[174:175]
	global_store_dwordx2 v[130:131], v[134:135], off
	global_store_dwordx2 v[106:107], v[104:105], off
	s_and_b64 s[14:15], s[30:31], s[14:15]
	v_mov_b32_e32 v169, 0
	v_mov_b32_e32 v170, 0
	v_mov_b32_e32 v171, 0
	v_mov_b32_e32 v104, 0
	v_mov_b32_e32 v105, 0
	v_mov_b32_e32 v106, 0
	v_mov_b32_e32 v107, 0
	v_mov_b32_e32 v108, 0
	v_mov_b32_e32 v109, 0
	v_mov_b32_e32 v110, 0
	v_mov_b32_e32 v111, 0
	v_mov_b32_e32 v112, 0
	v_mov_b32_e32 v113, 0
	v_mov_b32_e32 v114, 0
	v_mov_b32_e32 v115, 0
	s_and_saveexec_b64 s[0:1], s[14:15]
	s_cbranch_execz .LBB0_721
	ds_read_b128 v[112:115], v230 offset:2048
	ds_read_b128 v[104:107], v230 offset:2560
	ds_read_b128 v[108:111], v230 offset:3072
	ds_read_b128 v[168:171], v230 offset:3584
; #define DPPF(v, ctrl) __builtin_bit_cast(float, __builtin_amdgcn_update_dpp(0, __builtin_bit_cast(int, (v)), (ctrl), 0xf, 0xf, false))
; #define PG8_LAS __attribute__((address_space(3)))
;     __device__ __forceinline__ void run(const f32x4 (&acc)[2][2][4][2], const Unit& u, const Unit& nxt, bool has_next, int ui, int wr, int wc, int fr_in, int fq_in) const {
;     ...
;                 if (grp > 0 && fr == 0) { const PG8_LAS float* xp = xr + ((grp - 1) * 2) * 256 + cl;
;                     hg2 = *(const PG8_LAS f32x4*)(xp); hg3 = *(const PG8_LAS f32x4*)(xp + 256); hv2 = *(const PG8_LAS f32x4*)(xp + 128); hv3 = *(const PG8_LAS f32x4*)(xp + 256 + 128); }
;                 f32x4 pg2, pg1, pv2, pv1;
;                 {
;                     const f32x4 g2 = acc[ai][0][2][n] * rs[ai][2], g3 = acc[ai][0][3][n] * rs[ai][3], v2 = acc[ai][1][2][n] * rs[ai][2], v3 = acc[ai][1][3][n] * rs[ai][3];
; #pragma unroll
;                     for (int i = 0; i < 4; ++i) {
;                         float a0 = g2[i], a1 = g3[i], a2 = v2[i], a3 = v3[i];
;                         asm volatile("" : "+v"(a0), "+v"(a1), "+v"(a2), "+v"(a3));
;                         const float t0 = DPPF(a0, 0x111), t1 = DPPF(a1, 0x111), t2 = DPPF(a2, 0x111), t3 = DPPF(a3, 0x111);
;                         pg2[i] = t0 + hg2[i]; pg1[i] = t1 + hg3[i]; pv2[i] = t2 + hv2[i]; pv1[i] = t3 + hv3[i]; }
;                 }
; #pragma unroll
;                 for (int m = 0; m < 4; ++m) {
;                     const f32x4 gc = acc[ai][0][m][n] * rs[ai][m], vc = acc[ai][1][m][n] * rs[ai][m];
;                     const f32x4 cgt = bg + wg0 * pg2 + wg1 * pg1 + wg2 * gc, cvl = bv + wv0 * pv2 + wv1 * pv1 + wv2 * vc;
.LBB0_721:
	s_or_b64 exec, exec, s[0:1]
	v_mul_f32_e32 v117, v80, v74
	v_mul_f32_e32 v119, v68, v75
	v_mul_f32_e32 v121, v76, v74
	v_mul_f32_e32 v123, v64, v75
	v_mov_b32_dpp v118, v119 row_shr:1 row_mask:0xf bank_mask:0xf bound_ctrl:1
	v_mov_b32_dpp v120, v121 row_shr:1 row_mask:0xf bank_mask:0xf bound_ctrl:1
	v_mov_b32_dpp v122, v123 row_shr:1 row_mask:0xf bank_mask:0xf bound_ctrl:1
	v_mul_f32_e32 v119, v81, v74
	v_mul_f32_e32 v121, v69, v75
	v_mul_f32_e32 v123, v77, v74
	v_mul_f32_e32 v124, v65, v75
	v_mov_b32_dpp v116, v117 row_shr:1 row_mask:0xf bank_mask:0xf bound_ctrl:1
	v_pk_mul_f32 v[96:97], v[96:97], v[72:73] op_sel_hi:[1,0]
	v_mul_f32_e32 v125, v82, v74
	v_mov_b32_dpp v117, v119 row_shr:1 row_mask:0xf bank_mask:0xf bound_ctrl:1
	s_waitcnt lgkmcnt(0)
	v_pk_add_f32 v[112:113], v[112:113], v[116:117]
	v_mul_f32_e32 v131, v70, v75
	v_mov_b32_dpp v119, v121 row_shr:1 row_mask:0xf bank_mask:0xf bound_ctrl:1
	v_pk_add_f32 v[108:109], v[108:109], v[118:119]
	v_pk_fma_f32 v[112:113], v[152:153], v[112:113], v[164:165]
	v_pk_fma_f32 v[112:113], v[156:157], v[108:109], v[112:113]
	v_mul_f32_e32 v135, v78, v74
	v_pk_fma_f32 v[112:113], v[96:97], v[160:161], v[112:113]
	v_mul_f32_e32 v177, v66, v75
	v_exp_f32_e32 v116, v112
	v_exp_f32_e32 v117, v113
	v_mov_b32_dpp v121, v123 row_shr:1 row_mask:0xf bank_mask:0xf bound_ctrl:1
	v_mov_b32_dpp v123, v124 row_shr:1 row_mask:0xf bank_mask:0xf bound_ctrl:1
	v_mov_b32_dpp v130, v131 row_shr:1 row_mask:0xf bank_mask:0xf bound_ctrl:1
	v_mov_b32_dpp v134, v135 row_shr:1 row_mask:0xf bank_mask:0xf bound_ctrl:1
	v_mov_b32_dpp v178, v177 row_shr:1 row_mask:0xf bank_mask:0xf bound_ctrl:1
	v_mul_f32_e32 v131, v83, v74
	v_mul_f32_e32 v135, v71, v75
	v_mul_f32_e32 v177, v79, v74
	v_mul_f32_e32 v180, v67, v75
	v_mov_b32_dpp v124, v125 row_shr:1 row_mask:0xf bank_mask:0xf bound_ctrl:1
	v_add_f32_e32 v116, 1.0, v116
	v_add_f32_e32 v117, 1.0, v117
	v_mov_b32_dpp v125, v131 row_shr:1 row_mask:0xf bank_mask:0xf bound_ctrl:1
	v_rcp_f32_e32 v116, v116
	v_rcp_f32_e32 v117, v117
	v_mov_b32_dpp v131, v135 row_shr:1 row_mask:0xf bank_mask:0xf bound_ctrl:1
	v_pk_add_f32 v[114:115], v[114:115], v[124:125]
	v_pk_add_f32 v[110:111], v[110:111], v[130:131]
	v_pk_fma_f32 v[114:115], v[154:155], v[114:115], v[166:167]
	v_pk_mul_f32 v[98:99], v[98:99], v[72:73] op_sel_hi:[1,0]
	v_pk_fma_f32 v[114:115], v[158:159], v[110:111], v[114:115]
	v_pk_mul_f32 v[112:113], v[112:113], v[116:117]
	v_pk_fma_f32 v[114:115], v[98:99], v[162:163], v[114:115]
	v_pk_add_f32 v[104:105], v[104:105], v[120:121]
	v_exp_f32_e32 v116, v114
	v_exp_f32_e32 v117, v115
	v_pk_add_f32 v[118:119], v[168:169], v[122:123]
	v_add_f32_e32 v116, 1.0, v116
	v_add_f32_e32 v117, 1.0, v117
	v_rcp_f32_e32 v116, v116
	v_rcp_f32_e32 v117, v117
	v_pk_fma_f32 v[104:105], v[136:137], v[104:105], v[148:149]
	v_mov_b32_dpp v135, v177 row_shr:1 row_mask:0xf bank_mask:0xf bound_ctrl:1
	v_pk_mul_f32 v[92:93], v[92:93], v[72:73] op_sel_hi:[1,0]
	v_pk_fma_f32 v[104:105], v[140:141], v[118:119], v[104:105]
	v_mov_b32_dpp v179, v180 row_shr:1 row_mask:0xf bank_mask:0xf bound_ctrl:1
	v_pk_fma_f32 v[104:105], v[92:93], v[144:145], v[104:105]
	v_pk_add_f32 v[106:107], v[106:107], v[134:135]
	v_pk_mul_f32 v[114:115], v[114:115], v[116:117]
	v_mov_b32_e32 v116, v73
	v_pk_fma_f32 v[108:109], v[152:153], v[108:109], v[164:165]
	v_pk_mul_f32 v[104:105], v[104:105], v[112:113]
	v_pk_add_f32 v[112:113], v[170:171], v[178:179]
	v_pk_fma_f32 v[106:107], v[138:139], v[106:107], v[150:151]
	v_pk_mul_f32 v[88:89], v[88:89], v[116:117] op_sel_hi:[1,0]
	v_pk_fma_f32 v[108:109], v[96:97], v[156:157], v[108:109]
	v_pk_mul_f32 v[94:95], v[94:95], v[72:73] op_sel_hi:[1,0]
	v_pk_fma_f32 v[106:107], v[142:143], v[112:113], v[106:107]
	v_pk_fma_f32 v[108:109], v[88:89], v[160:161], v[108:109]
	v_pk_fma_f32 v[106:107], v[94:95], v[146:147], v[106:107]
	v_pk_mul_f32 v[106:107], v[106:107], v[114:115]
	v_exp_f32_e32 v117, v108
	v_exp_f32_e32 v120, v109
	v_add_u32_e32 v177, 0x80, v231
	v_cvt_pk_bf16_f32 v104, v104, v105
	v_cvt_pk_bf16_f32 v105, v106, v107
	v_mov_b64_e32 v[106:107], s[20:21]
	v_mad_i64_i32 v[122:123], s[0:1], v177, s74, v[106:107]
	v_lshl_add_u64 v[114:115], v[122:123], 0, v[174:175]
	global_store_dwordx2 v[114:115], v[104:105], off
	v_add_f32_e32 v104, 1.0, v117
	v_add_f32_e32 v105, 1.0, v120
	v_rcp_f32_e32 v104, v104
	v_rcp_f32_e32 v105, v105
	v_pk_mul_f32 v[90:91], v[90:91], v[116:117] op_sel_hi:[1,0]
	v_pk_mul_f32 v[84:85], v[84:85], v[116:117] op_sel_hi:[1,0]
	v_pk_fma_f32 v[96:97], v[96:97], v[152:153], v[164:165]
	v_pk_mul_f32 v[104:105], v[108:109], v[104:105]
	v_pk_fma_f32 v[108:109], v[154:155], v[110:111], v[166:167]
	v_pk_mul_f32 v[86:87], v[86:87], v[116:117] op_sel_hi:[1,0]
	v_pk_fma_f32 v[108:109], v[98:99], v[158:159], v[108:109]
	v_pk_mul_f32 v[80:81], v[80:81], v[74:75] op_sel_hi:[1,0]
	v_pk_fma_f32 v[108:109], v[90:91], v[162:163], v[108:109]
	v_pk_fma_f32 v[96:97], v[88:89], v[156:157], v[96:97]
	v_exp_f32_e32 v114, v108
	v_exp_f32_e32 v115, v109
	v_pk_fma_f32 v[110:111], v[136:137], v[118:119], v[148:149]
	v_add_f32_e32 v114, 1.0, v114
	v_rcp_f32_e32 v114, v114
	v_add_f32_e32 v115, 1.0, v115
	v_rcp_f32_e32 v115, v115
	v_pk_fma_f32 v[110:111], v[92:93], v[140:141], v[110:111]
	v_pk_fma_f32 v[96:97], v[80:81], v[160:161], v[96:97]
	v_pk_fma_f32 v[110:111], v[84:85], v[144:145], v[110:111]
	v_pk_mul_f32 v[108:109], v[108:109], v[114:115]
	v_pk_mul_f32 v[104:105], v[110:111], v[104:105]
	v_pk_fma_f32 v[110:111], v[138:139], v[112:113], v[150:151]
	v_cvt_pk_bf16_f32 v104, v104, v105
	v_pk_fma_f32 v[110:111], v[94:95], v[142:143], v[110:111]
	v_pk_fma_f32 v[98:99], v[98:99], v[154:155], v[166:167]
; __device__ __forceinline__ unsigned pk2(float lo, float hi) { f32x2_t v = {lo, hi}; bf16x2_t b = __builtin_convertvector(v, bf16x2_t); return __builtin_bit_cast(unsigned, b); }
; __device__ __forceinline__ float sigmoidf_(float v) { return fast_rcp(1.0f + fast_exp2(-v * LOG2E)); }
; #define PG8_LAS __attribute__((address_space(3)))
;     __device__ __forceinline__ void run(const f32x4 (&acc)[2][2][4][2], const Unit& u, const Unit& nxt, bool has_next, int ui, int wr, int wc, int fr_in, int fq_in) const {
;     ...
;         for (int n = 0; n < 2; ++n) {
;             const int cl = wc * 32 + n * 16 + 4 * fq, ch = u.pn * 128 + cl;
;             const PG8_LAS float* pp = prm + slot * 1024 + cl;
;             const f32x4 wg0 = *(const PG8_LAS f32x4*)(pp), wg1 = *(const PG8_LAS f32x4*)(pp + 128), wg2 = *(const PG8_LAS f32x4*)(pp + 256), bg = *(const PG8_LAS f32x4*)(pp + 384);
;             const f32x4 wv0 = *(const PG8_LAS f32x4*)(pp + 512), wv1 = *(const PG8_LAS f32x4*)(pp + 640), wv2 = *(const PG8_LAS f32x4*)(pp + 768), bv = *(const PG8_LAS f32x4*)(pp + 896);
; #pragma unroll
;             for (int ai = 0; ai < 2; ++ai) {
;                 const int grp = 2 * ai + wr;
;                 f32x4 hg2 = {0.f, 0.f, 0.f, 0.f}, hg3 = hg2, hv2 = hg2, hv3 = hg2;
;                 if (grp > 0 && fr == 0) { const PG8_LAS float* xp = xr + ((grp - 1) * 2) * 256 + cl;
;                     hg2 = *(const PG8_LAS f32x4*)(xp); hg3 = *(const PG8_LAS f32x4*)(xp + 256); hv2 = *(const PG8_LAS f32x4*)(xp + 128); hv3 = *(const PG8_LAS f32x4*)(xp + 256 + 128); }
;     ...
;                 for (int m = 0; m < 4; ++m) {
;                     const f32x4 gc = acc[ai][0][m][n] * rs[ai][m], vc = acc[ai][1][m][n] * rs[ai][m];
;                     const f32x4 cgt = bg + wg0 * pg2 + wg1 * pg1 + wg2 * gc, cvl = bv + wv0 * pv2 + wv1 * pv1 + wv2 * vc;
;                     float a[4];
; #pragma unroll
;                     for (int i = 0; i < 4; ++i) a[i] = cgt[i] * sigmoidf_(cgt[i]) * cvl[i];
;                     u32x2 w; w.x = pk2(a[0], a[1]); w.y = pk2(a[2], a[3]);
;                     *(u32x2*)(A + (size_t)(u.pm * BM + ai * 128 + wr * 64 + 4 * fr + m) * DFF + ch) = w;
;                     pg2 = pg1; pg1 = gc; pv2 = pv1; pv1 = vc;
;                 }
	v_pk_fma_f32 v[110:111], v[86:87], v[146:147], v[110:111]
	v_pk_mul_f32 v[82:83], v[82:83], v[74:75] op_sel_hi:[1,0]
	v_pk_mul_f32 v[108:109], v[110:111], v[108:109]
	v_exp_f32_e32 v110, v96
	v_exp_f32_e32 v111, v97
	v_cvt_pk_bf16_f32 v105, v108, v109
	v_add_u32_e32 v108, 0x81, v231
	v_mad_i64_i32 v[124:125], s[0:1], v108, s74, v[106:107]
	v_lshl_add_u64 v[108:109], v[124:125], 0, v[174:175]
	global_store_dwordx2 v[108:109], v[104:105], off
	v_add_f32_e32 v104, 1.0, v110
	v_add_f32_e32 v105, 1.0, v111
	v_rcp_f32_e32 v104, v104
	v_rcp_f32_e32 v105, v105
	v_pk_fma_f32 v[98:99], v[90:91], v[158:159], v[98:99]
	v_pk_fma_f32 v[92:93], v[92:93], v[136:137], v[148:149]
	v_pk_fma_f32 v[98:99], v[82:83], v[162:163], v[98:99]
	v_pk_mul_f32 v[96:97], v[96:97], v[104:105]
	v_exp_f32_e32 v104, v98
	v_exp_f32_e32 v105, v99
	v_pk_mul_f32 v[76:77], v[76:77], v[74:75] op_sel_hi:[1,0]
	v_pk_fma_f32 v[92:93], v[84:85], v[140:141], v[92:93]
	v_add_f32_e32 v104, 1.0, v104
	v_add_f32_e32 v105, 1.0, v105
	v_rcp_f32_e32 v104, v104
	v_rcp_f32_e32 v105, v105
	v_pk_fma_f32 v[94:95], v[94:95], v[138:139], v[150:151]
	v_pk_mul_f32 v[78:79], v[78:79], v[74:75] op_sel_hi:[1,0]
	v_pk_fma_f32 v[92:93], v[76:77], v[144:145], v[92:93]
	v_pk_fma_f32 v[94:95], v[86:87], v[142:143], v[94:95]
	v_pk_mul_f32 v[92:93], v[92:93], v[96:97]
	v_pk_mul_f32 v[96:97], v[98:99], v[104:105]
	v_pk_fma_f32 v[94:95], v[78:79], v[146:147], v[94:95]
	v_pk_fma_f32 v[88:89], v[152:153], v[88:89], v[164:165]
	v_pk_mul_f32 v[94:95], v[94:95], v[96:97]
	v_mov_b32_e32 v96, v75
	v_pk_mul_f32 v[68:69], v[68:69], v[96:97] op_sel_hi:[1,0]
	v_pk_fma_f32 v[80:81], v[156:157], v[80:81], v[88:89]
	v_pk_mul_f32 v[70:71], v[70:71], v[96:97] op_sel_hi:[1,0]
	v_pk_fma_f32 v[68:69], v[160:161], v[68:69], v[80:81]
	v_pk_mul_f32 v[64:65], v[64:65], v[96:97] op_sel_hi:[1,0]
	v_exp_f32_e32 v80, v68
	v_exp_f32_e32 v81, v69
	v_pk_mul_f32 v[66:67], v[66:67], v[96:97] op_sel_hi:[1,0]
	v_cvt_pk_bf16_f32 v92, v92, v93
	v_add_f32_e32 v80, 1.0, v80
	v_add_f32_e32 v81, 1.0, v81
	v_rcp_f32_e32 v80, v80
	v_rcp_f32_e32 v81, v81
	v_cvt_pk_bf16_f32 v93, v94, v95
	v_add_u32_e32 v94, 0x82, v231
	v_mad_i64_i32 v[130:131], s[0:1], v94, s74, v[106:107]
	v_pk_mul_f32 v[68:69], v[68:69], v[80:81]
	v_pk_fma_f32 v[80:81], v[154:155], v[90:91], v[166:167]
	v_lshl_add_u64 v[94:95], v[130:131], 0, v[174:175]
	v_pk_fma_f32 v[80:81], v[158:159], v[82:83], v[80:81]
	global_store_dwordx2 v[94:95], v[92:93], off
	v_pk_fma_f32 v[70:71], v[162:163], v[70:71], v[80:81]
	v_add_u32_e32 v176, 16, v202
	v_exp_f32_e32 v82, v70
	v_exp_f32_e32 v83, v71
	v_pk_fma_f32 v[80:81], v[84:85], v[136:137], v[148:149]
	v_add_f32_e32 v82, 1.0, v82
	v_rcp_f32_e32 v82, v82
	v_add_f32_e32 v83, 1.0, v83
	v_rcp_f32_e32 v83, v83
	v_pk_fma_f32 v[76:77], v[76:77], v[140:141], v[80:81]
	v_mov_b32_e32 v104, 0
	v_pk_fma_f32 v[64:65], v[64:65], v[144:145], v[76:77]
	v_mov_b32_e32 v108, 0
	v_pk_mul_f32 v[64:65], v[64:65], v[68:69]
	v_pk_mul_f32 v[68:69], v[70:71], v[82:83]
	v_pk_fma_f32 v[70:71], v[86:87], v[138:139], v[150:151]
	v_cvt_pk_bf16_f32 v64, v64, v65
	v_pk_fma_f32 v[70:71], v[78:79], v[142:143], v[70:71]
	v_mov_b32_e32 v109, 0
	v_pk_fma_f32 v[66:67], v[66:67], v[146:147], v[70:71]
	v_mov_b32_e32 v110, 0
	v_pk_mul_f32 v[66:67], v[66:67], v[68:69]
	v_mov_b32_e32 v111, 0
	v_cvt_pk_bf16_f32 v65, v66, v67
	v_add_u32_e32 v66, 0x83, v231
	v_mad_i64_i32 v[134:135], s[0:1], v66, s74, v[106:107]
	v_lshl_add_u64 v[66:67], v[134:135], 0, v[174:175]
	global_store_dwordx2 v[66:67], v[64:65], off
	ds_read_b128 v[84:87], v203 offset:64
	ds_read_b128 v[88:91], v203 offset:576
	ds_read_b128 v[92:95], v203 offset:1088
	ds_read_b128 v[96:99], v203 offset:1600
	ds_read_b128 v[64:67], v203 offset:2112
	ds_read_b128 v[68:71], v203 offset:2624
	ds_read_b128 v[76:79], v203 offset:3136
	ds_read_b128 v[80:83], v203 offset:3648
	v_mov_b32_e32 v106, 0
	v_mov_b32_e32 v107, 0
	v_mov_b32_e32 v112, 0
	v_mov_b32_e32 v113, 0
	v_mov_b32_e32 v114, 0
	v_mov_b32_e32 v115, 0
	v_mov_b32_e32 v116, 0
	v_mov_b32_e32 v117, 0
	v_mov_b32_e32 v118, 0
	v_mov_b32_e32 v119, 0
	v_mov_b32_e32 v120, 0
	v_mov_b32_e32 v121, 0
	s_and_saveexec_b64 s[0:1], s[4:5]
	s_cbranch_execz .LBB0_723
	v_lshl_add_u32 v105, v176, 2, s71
	ds_read_b128 v[118:121], v105
	ds_read_b128 v[110:113], v105 offset:512
	ds_read_b128 v[114:117], v105 offset:1024
	ds_read_b128 v[106:109], v105 offset:1536
; __device__ __forceinline__ unsigned pk2(float lo, float hi) { f32x2_t v = {lo, hi}; bf16x2_t b = __builtin_convertvector(v, bf16x2_t); return __builtin_bit_cast(unsigned, b); }
; #define DPPF(v, ctrl) __builtin_bit_cast(float, __builtin_amdgcn_update_dpp(0, __builtin_bit_cast(int, (v)), (ctrl), 0xf, 0xf, false))
; __device__ __forceinline__ float sigmoidf_(float v) { return fast_rcp(1.0f + fast_exp2(-v * LOG2E)); }
; #define PG8_LAS __attribute__((address_space(3)))
;     __device__ __forceinline__ void run(const f32x4 (&acc)[2][2][4][2], const Unit& u, const Unit& nxt, bool has_next, int ui, int wr, int wc, int fr_in, int fq_in) const {
;     ...
;                 if (grp > 0 && fr == 0) { const PG8_LAS float* xp = xr + ((grp - 1) * 2) * 256 + cl;
;                     hg2 = *(const PG8_LAS f32x4*)(xp); hg3 = *(const PG8_LAS f32x4*)(xp + 256); hv2 = *(const PG8_LAS f32x4*)(xp + 128); hv3 = *(const PG8_LAS f32x4*)(xp + 256 + 128); }
;                 f32x4 pg2, pg1, pv2, pv1;
;                 {
;                     const f32x4 g2 = acc[ai][0][2][n] * rs[ai][2], g3 = acc[ai][0][3][n] * rs[ai][3], v2 = acc[ai][1][2][n] * rs[ai][2], v3 = acc[ai][1][3][n] * rs[ai][3];
; #pragma unroll
;                     for (int i = 0; i < 4; ++i) {
;                         float a0 = g2[i], a1 = g3[i], a2 = v2[i], a3 = v3[i];
;                         asm volatile("" : "+v"(a0), "+v"(a1), "+v"(a2), "+v"(a3));
;                         const float t0 = DPPF(a0, 0x111), t1 = DPPF(a1, 0x111), t2 = DPPF(a2, 0x111), t3 = DPPF(a3, 0x111);
;                         pg2[i] = t0 + hg2[i]; pg1[i] = t1 + hg3[i]; pv2[i] = t2 + hv2[i]; pv1[i] = t3 + hv3[i]; }
;                 }
; #pragma unroll
;                 for (int m = 0; m < 4; ++m) {
;                     const f32x4 gc = acc[ai][0][m][n] * rs[ai][m], vc = acc[ai][1][m][n] * rs[ai][m];
;                     const f32x4 cgt = bg + wg0 * pg2 + wg1 * pg1 + wg2 * gc, cvl = bv + wv0 * pv2 + wv1 * pv1 + wv2 * vc;
;                     float a[4];
; #pragma unroll
;                     for (int i = 0; i < 4; ++i) a[i] = cgt[i] * sigmoidf_(cgt[i]) * cvl[i];
;                     u32x2 w; w.x = pk2(a[0], a[1]); w.y = pk2(a[2], a[3]);
;                     *(u32x2*)(A + (size_t)(u.pm * BM + ai * 128 + wr * 64 + 4 * fr + m) * DFF + ch) = w;
;                     pg2 = pg1; pg1 = gc; pv2 = pv1; pv1 = vc;
.LBB0_723:
	s_or_b64 exec, exec, s[0:1]
	v_mul_f32_e32 v105, v44, v102
	v_mul_f32_e32 v147, v36, v103
	v_mul_f32_e32 v149, v40, v102
	v_mul_f32_e32 v151, v32, v103
	v_mov_b32_dpp v146, v105 row_shr:1 row_mask:0xf bank_mask:0xf bound_ctrl:1
	s_nop 0
	v_mov_b32_dpp v152, v151 row_shr:1 row_mask:0xf bank_mask:0xf bound_ctrl:1
	v_mul_f32_e32 v105, v45, v102
	v_mul_f32_e32 v151, v37, v103
	v_mul_f32_e32 v153, v41, v102
	v_mul_f32_e32 v154, v33, v103
	v_mov_b32_dpp v150, v149 row_shr:1 row_mask:0xf bank_mask:0xf bound_ctrl:1
	v_mov_b32_dpp v148, v147 row_shr:1 row_mask:0xf bank_mask:0xf bound_ctrl:1
	v_mov_b32_dpp v149, v151 row_shr:1 row_mask:0xf bank_mask:0xf bound_ctrl:1
	v_mov_b32_dpp v147, v105 row_shr:1 row_mask:0xf bank_mask:0xf bound_ctrl:1
	v_mul_f32_e32 v105, v46, v102
	v_mov_b32_dpp v151, v153 row_shr:1 row_mask:0xf bank_mask:0xf bound_ctrl:1
	v_mul_f32_e32 v155, v38, v103
	v_mul_f32_e32 v157, v42, v102
	v_mul_f32_e32 v159, v34, v103
	v_mov_b32_dpp v153, v154 row_shr:1 row_mask:0xf bank_mask:0xf bound_ctrl:1
	v_mov_b32_dpp v154, v105 row_shr:1 row_mask:0xf bank_mask:0xf bound_ctrl:1
	v_mov_b32_dpp v160, v159 row_shr:1 row_mask:0xf bank_mask:0xf bound_ctrl:1
	v_mul_f32_e32 v105, v47, v102
	v_mul_f32_e32 v159, v39, v103
	v_mul_f32_e32 v161, v43, v102
	v_mul_f32_e32 v162, v35, v103
	s_waitcnt lgkmcnt(0)
	v_pk_add_f32 v[118:119], v[118:119], v[146:147]
	v_mov_b32_e32 v140, v100
	v_mov_b32_e32 v141, v100
	v_mov_b32_dpp v158, v157 row_shr:1 row_mask:0xf bank_mask:0xf bound_ctrl:1
	v_pk_add_f32 v[114:115], v[114:115], v[148:149]
	v_pk_fma_f32 v[118:119], v[84:85], v[118:119], v[96:97]
	v_mov_b32_dpp v157, v159 row_shr:1 row_mask:0xf bank_mask:0xf bound_ctrl:1
	v_pk_mul_f32 v[60:61], v[60:61], v[140:141]
	v_pk_fma_f32 v[118:119], v[88:89], v[114:115], v[118:119]
	v_mov_b32_dpp v159, v161 row_shr:1 row_mask:0xf bank_mask:0xf bound_ctrl:1
	v_pk_fma_f32 v[118:119], v[60:61], v[92:93], v[118:119]
	v_mov_b32_dpp v156, v155 row_shr:1 row_mask:0xf bank_mask:0xf bound_ctrl:1
	v_mov_b32_dpp v161, v162 row_shr:1 row_mask:0xf bank_mask:0xf bound_ctrl:1
	v_mov_b32_e32 v162, v100
	v_mov_b32_e32 v163, v100
	v_mov_b32_dpp v155, v105 row_shr:1 row_mask:0xf bank_mask:0xf bound_ctrl:1
	v_exp_f32_e32 v100, v118
	v_exp_f32_e32 v105, v119
	v_pk_mul_f32 v[140:141], v[56:57], v[140:141]
	v_add_f32_e32 v100, 1.0, v100
	v_rcp_f32_e32 v146, v100
	v_add_f32_e32 v100, 1.0, v105
	v_rcp_f32_e32 v147, v100
	v_pk_add_f32 v[56:57], v[110:111], v[150:151]
	v_pk_add_f32 v[116:117], v[116:117], v[156:157]
	v_pk_mul_f32 v[62:63], v[62:63], v[162:163]
	v_pk_mul_f32 v[110:111], v[118:119], v[146:147]
	v_pk_add_f32 v[118:119], v[120:121], v[154:155]
	v_pk_add_f32 v[106:107], v[106:107], v[152:153]
	v_pk_fma_f32 v[118:119], v[86:87], v[118:119], v[98:99]
	v_pk_fma_f32 v[56:57], v[64:65], v[56:57], v[80:81]
	v_pk_fma_f32 v[118:119], v[90:91], v[116:117], v[118:119]
	v_pk_fma_f32 v[56:57], v[68:69], v[106:107], v[56:57]
	v_pk_fma_f32 v[118:119], v[62:63], v[94:95], v[118:119]
	v_pk_fma_f32 v[56:57], v[140:141], v[76:77], v[56:57]
	v_exp_f32_e32 v100, v118
	v_exp_f32_e32 v105, v119
	v_pk_mul_f32 v[56:57], v[56:57], v[110:111]
	v_add_f32_e32 v100, 1.0, v100
	v_rcp_f32_e32 v120, v100
	v_add_f32_e32 v100, 1.0, v105
	v_rcp_f32_e32 v121, v100
	v_pk_add_f32 v[110:111], v[112:113], v[158:159]
	v_pk_add_f32 v[108:109], v[108:109], v[160:161]
	v_pk_fma_f32 v[110:111], v[66:67], v[110:111], v[82:83]
	v_add_u32_e32 v144, s16, v176
	v_pk_mul_f32 v[58:59], v[58:59], v[162:163]
	v_pk_fma_f32 v[110:111], v[70:71], v[108:109], v[110:111]
	v_ashrrev_i32_e32 v145, 31, v144
	v_pk_mul_f32 v[112:113], v[118:119], v[120:121]
	v_pk_fma_f32 v[110:111], v[58:59], v[78:79], v[110:111]
	v_mov_b32_e32 v142, v101
	v_pk_mul_f32 v[110:111], v[110:111], v[112:113]
	v_cvt_pk_bf16_f32 v112, v56, v57
	v_lshlrev_b64 v[56:57], 1, v[144:145]
	v_cvt_pk_bf16_f32 v113, v110, v111
	v_lshl_add_u64 v[110:111], v[128:129], 0, v[56:57]
	v_mov_b32_e32 v143, v101
	global_store_dwordx2 v[110:111], v[112:113], off
	v_pk_fma_f32 v[110:111], v[84:85], v[114:115], v[96:97]
	v_pk_mul_f32 v[52:53], v[52:53], v[142:143]
	v_pk_fma_f32 v[110:111], v[60:61], v[88:89], v[110:111]
	v_pk_fma_f32 v[106:107], v[64:65], v[106:107], v[80:81]
	v_pk_fma_f32 v[110:111], v[52:53], v[92:93], v[110:111]
	v_pk_mul_f32 v[48:49], v[48:49], v[142:143]
	v_exp_f32_e32 v105, v110
	v_exp_f32_e32 v113, v111
	v_mov_b32_e32 v100, v101
	v_add_f32_e32 v105, 1.0, v105
	v_rcp_f32_e32 v112, v105
	v_add_f32_e32 v105, 1.0, v113
	v_rcp_f32_e32 v113, v105
	v_pk_mul_f32 v[54:55], v[54:55], v[100:101]
	v_pk_mul_f32 v[50:51], v[50:51], v[100:101]
	v_pk_fma_f32 v[106:107], v[140:141], v[68:69], v[106:107]
	v_pk_mul_f32 v[100:101], v[110:111], v[112:113]
	v_pk_fma_f32 v[110:111], v[86:87], v[116:117], v[98:99]
	v_pk_fma_f32 v[108:109], v[66:67], v[108:109], v[82:83]
	v_pk_fma_f32 v[110:111], v[62:63], v[90:91], v[110:111]
	v_pk_fma_f32 v[106:107], v[48:49], v[76:77], v[106:107]
	v_pk_fma_f32 v[110:111], v[54:55], v[94:95], v[110:111]
	v_pk_fma_f32 v[108:109], v[58:59], v[70:71], v[108:109]
	v_exp_f32_e32 v105, v110
	v_exp_f32_e32 v113, v111
	v_mov_b32_e32 v138, v102
	v_add_f32_e32 v105, 1.0, v105
	v_rcp_f32_e32 v112, v105
	v_add_f32_e32 v105, 1.0, v113
	v_rcp_f32_e32 v113, v105
	v_mov_b32_e32 v139, v102
	v_pk_mul_f32 v[100:101], v[106:107], v[100:101]
	v_pk_fma_f32 v[108:109], v[50:51], v[78:79], v[108:109]
	v_pk_mul_f32 v[106:107], v[110:111], v[112:113]
	v_pk_fma_f32 v[60:61], v[60:61], v[84:85], v[96:97]
	v_pk_mul_f32 v[106:107], v[108:109], v[106:107]
	v_pk_mul_f32 v[44:45], v[44:45], v[138:139]
	v_pk_fma_f32 v[60:61], v[52:53], v[88:89], v[60:61]
	v_cvt_pk_bf16_f32 v100, v100, v101
; __device__ __forceinline__ unsigned pk2(float lo, float hi) { f32x2_t v = {lo, hi}; bf16x2_t b = __builtin_convertvector(v, bf16x2_t); return __builtin_bit_cast(unsigned, b); }
; #define DPPF(v, ctrl) __builtin_bit_cast(float, __builtin_amdgcn_update_dpp(0, __builtin_bit_cast(int, (v)), (ctrl), 0xf, 0xf, false))
; __device__ __forceinline__ float sigmoidf_(float v) { return fast_rcp(1.0f + fast_exp2(-v * LOG2E)); }
; #define PG8_LAS __attribute__((address_space(3)))
;     __device__ __forceinline__ void run(const f32x4 (&acc)[2][2][4][2], const Unit& u, const Unit& nxt, bool has_next, int ui, int wr, int wc, int fr_in, int fq_in) const {
;     ...
;                 if (grp > 0 && fr == 0) { const PG8_LAS float* xp = xr + ((grp - 1) * 2) * 256 + cl;
;                     hg2 = *(const PG8_LAS f32x4*)(xp); hg3 = *(const PG8_LAS f32x4*)(xp + 256); hv2 = *(const PG8_LAS f32x4*)(xp + 128); hv3 = *(const PG8_LAS f32x4*)(xp + 256 + 128); }
;                 f32x4 pg2, pg1, pv2, pv1;
;                 {
;                     const f32x4 g2 = acc[ai][0][2][n] * rs[ai][2], g3 = acc[ai][0][3][n] * rs[ai][3], v2 = acc[ai][1][2][n] * rs[ai][2], v3 = acc[ai][1][3][n] * rs[ai][3];
; #pragma unroll
;                     for (int i = 0; i < 4; ++i) {
;                         float a0 = g2[i], a1 = g3[i], a2 = v2[i], a3 = v3[i];
;                         asm volatile("" : "+v"(a0), "+v"(a1), "+v"(a2), "+v"(a3));
;                         const float t0 = DPPF(a0, 0x111), t1 = DPPF(a1, 0x111), t2 = DPPF(a2, 0x111), t3 = DPPF(a3, 0x111);
;                         pg2[i] = t0 + hg2[i]; pg1[i] = t1 + hg3[i]; pv2[i] = t2 + hv2[i]; pv1[i] = t3 + hv3[i]; }
;                 }
; #pragma unroll
;                 for (int m = 0; m < 4; ++m) {
;                     const f32x4 gc = acc[ai][0][m][n] * rs[ai][m], vc = acc[ai][1][m][n] * rs[ai][m];
;                     const f32x4 cgt = bg + wg0 * pg2 + wg1 * pg1 + wg2 * gc, cvl = bv + wv0 * pv2 + wv1 * pv1 + wv2 * vc;
;                     float a[4];
; #pragma unroll
;                     for (int i = 0; i < 4; ++i) a[i] = cgt[i] * sigmoidf_(cgt[i]) * cvl[i];
;                     u32x2 w; w.x = pk2(a[0], a[1]); w.y = pk2(a[2], a[3]);
;                     *(u32x2*)(A + (size_t)(u.pm * BM + ai * 128 + wr * 64 + 4 * fr + m) * DFF + ch) = w;
;                     pg2 = pg1; pg1 = gc; pv2 = pv1; pv1 = vc;
;                 }
	v_cvt_pk_bf16_f32 v101, v106, v107
	v_lshl_add_u64 v[106:107], v[126:127], 0, v[56:57]
	v_pk_fma_f32 v[60:61], v[44:45], v[92:93], v[60:61]
	v_mov_b32_e32 v136, v103
	v_mov_b32_e32 v137, v103
	global_store_dwordx2 v[106:107], v[100:101], off
	v_pk_fma_f32 v[52:53], v[52:53], v[84:85], v[96:97]
	v_exp_f32_e32 v105, v60
	v_pk_mul_f32 v[36:37], v[36:37], v[136:137]
	v_pk_fma_f32 v[44:45], v[44:45], v[88:89], v[52:53]
	v_exp_f32_e32 v107, v61
	v_pk_fma_f32 v[36:37], v[36:37], v[92:93], v[44:45]
	v_mov_b32_e32 v100, v102
	v_mov_b32_e32 v101, v102
	v_pk_fma_f32 v[62:63], v[62:63], v[86:87], v[98:99]
	v_pk_mul_f32 v[46:47], v[46:47], v[100:101]
	v_pk_fma_f32 v[62:63], v[54:55], v[90:91], v[62:63]
	v_exp_f32_e32 v44, v36
	v_exp_f32_e32 v45, v37
	v_add_f32_e32 v102, 1.0, v105
	v_pk_fma_f32 v[62:63], v[46:47], v[94:95], v[62:63]
	v_rcp_f32_e32 v106, v102
	v_add_f32_e32 v102, 1.0, v107
	v_pk_mul_f32 v[42:43], v[42:43], v[100:101]
	v_rcp_f32_e32 v107, v102
	v_exp_f32_e32 v102, v62
	v_exp_f32_e32 v105, v63
	v_add_f32_e32 v44, 1.0, v44
	v_add_f32_e32 v45, 1.0, v45
	v_rcp_f32_e32 v44, v44
	v_rcp_f32_e32 v45, v45
	v_add_f32_e32 v102, 1.0, v102
	v_pk_mul_f32 v[60:61], v[60:61], v[106:107]
	v_rcp_f32_e32 v106, v102
	v_add_f32_e32 v102, 1.0, v105
	v_rcp_f32_e32 v107, v102
	v_mov_b32_e32 v102, v103
	v_pk_mul_f32 v[36:37], v[36:37], v[44:45]
	v_pk_fma_f32 v[44:45], v[54:55], v[86:87], v[98:99]
	v_pk_mul_f32 v[38:39], v[38:39], v[102:103]
	v_pk_fma_f32 v[44:45], v[46:47], v[90:91], v[44:45]
	v_pk_fma_f32 v[100:101], v[140:141], v[64:65], v[80:81]
	v_pk_fma_f32 v[38:39], v[38:39], v[94:95], v[44:45]
	v_pk_mul_f32 v[40:41], v[40:41], v[138:139]
	v_exp_f32_e32 v46, v38
	v_exp_f32_e32 v47, v39
	v_pk_fma_f32 v[100:101], v[48:49], v[68:69], v[100:101]
	v_add_f32_e32 v46, 1.0, v46
	v_rcp_f32_e32 v46, v46
	v_add_f32_e32 v47, 1.0, v47
	v_rcp_f32_e32 v47, v47
	v_pk_fma_f32 v[44:45], v[48:49], v[64:65], v[80:81]
	v_pk_fma_f32 v[100:101], v[40:41], v[76:77], v[100:101]
	v_pk_mul_f32 v[32:33], v[32:33], v[136:137]
	v_pk_fma_f32 v[40:41], v[40:41], v[68:69], v[44:45]
	v_pk_fma_f32 v[58:59], v[58:59], v[66:67], v[82:83]
	v_pk_fma_f32 v[32:33], v[32:33], v[76:77], v[40:41]
	v_pk_fma_f32 v[58:59], v[50:51], v[70:71], v[58:59]
	v_pk_mul_f32 v[32:33], v[32:33], v[36:37]
	v_pk_mul_f32 v[36:37], v[38:39], v[46:47]
	v_pk_fma_f32 v[38:39], v[50:51], v[66:67], v[82:83]
	v_pk_mul_f32 v[34:35], v[34:35], v[102:103]
	v_pk_fma_f32 v[38:39], v[42:43], v[70:71], v[38:39]
	v_pk_mul_f32 v[62:63], v[62:63], v[106:107]
	v_pk_fma_f32 v[58:59], v[42:43], v[78:79], v[58:59]
	v_pk_fma_f32 v[34:35], v[34:35], v[78:79], v[38:39]
	v_pk_mul_f32 v[60:61], v[100:101], v[60:61]
	v_pk_mul_f32 v[58:59], v[58:59], v[62:63]
	v_pk_mul_f32 v[34:35], v[34:35], v[36:37]
	v_cvt_pk_bf16_f32 v60, v60, v61
	v_cvt_pk_bf16_f32 v61, v58, v59
	v_lshl_add_u64 v[58:59], v[132:133], 0, v[56:57]
	v_cvt_pk_bf16_f32 v32, v32, v33
	v_cvt_pk_bf16_f32 v33, v34, v35
	v_lshl_add_u64 v[34:35], v[172:173], 0, v[56:57]
	global_store_dwordx2 v[58:59], v[60:61], off
	global_store_dwordx2 v[34:35], v[32:33], off
	v_mov_b32_e32 v105, 0
	v_mov_b32_e32 v106, 0
	v_mov_b32_e32 v107, 0
	v_mov_b32_e32 v32, 0
	v_mov_b32_e32 v33, 0
	v_mov_b32_e32 v34, 0
	v_mov_b32_e32 v35, 0
	v_mov_b32_e32 v36, 0
	v_mov_b32_e32 v37, 0
	v_mov_b32_e32 v38, 0
	v_mov_b32_e32 v39, 0
	v_mov_b32_e32 v40, 0
	v_mov_b32_e32 v41, 0
	v_mov_b32_e32 v42, 0
	v_mov_b32_e32 v43, 0
	s_and_saveexec_b64 s[0:1], s[14:15]
	s_cbranch_execz .LBB0_725
	ds_read_b128 v[40:43], v230 offset:2112
	ds_read_b128 v[32:35], v230 offset:2624
	ds_read_b128 v[36:39], v230 offset:3136
	ds_read_b128 v[104:107], v230 offset:3648
.LBB0_725:
	s_or_b64 exec, exec, s[0:1]
	v_mul_f32_e32 v53, v12, v74
	v_mul_f32_e32 v55, v4, v75
	v_mul_f32_e32 v59, v8, v74
	v_mul_f32_e32 v61, v0, v75
	v_mov_b32_dpp v54, v55 row_shr:1 row_mask:0xf bank_mask:0xf bound_ctrl:1
	v_mov_b32_dpp v58, v59 row_shr:1 row_mask:0xf bank_mask:0xf bound_ctrl:1
	v_mov_b32_dpp v60, v61 row_shr:1 row_mask:0xf bank_mask:0xf bound_ctrl:1
	v_mul_f32_e32 v55, v13, v74
	v_mul_f32_e32 v59, v5, v75
	v_mul_f32_e32 v61, v9, v74
	v_mul_f32_e32 v62, v1, v75
	v_mov_b32_dpp v52, v53 row_shr:1 row_mask:0xf bank_mask:0xf bound_ctrl:1
	v_mov_b32_e32 v48, v72
	v_mov_b32_e32 v49, v72
	v_mov_b32_dpp v53, v55 row_shr:1 row_mask:0xf bank_mask:0xf bound_ctrl:1
	s_waitcnt lgkmcnt(0)
; __device__ __forceinline__ unsigned pk2(float lo, float hi) { f32x2_t v = {lo, hi}; bf16x2_t b = __builtin_convertvector(v, bf16x2_t); return __builtin_bit_cast(unsigned, b); }
; #define DPPF(v, ctrl) __builtin_bit_cast(float, __builtin_amdgcn_update_dpp(0, __builtin_bit_cast(int, (v)), (ctrl), 0xf, 0xf, false))
; __device__ __forceinline__ float sigmoidf_(float v) { return fast_rcp(1.0f + fast_exp2(-v * LOG2E)); }
; #define PG8_LAS __attribute__((address_space(3)))
;     __device__ __forceinline__ void run(const f32x4 (&acc)[2][2][4][2], const Unit& u, const Unit& nxt, bool has_next, int ui, int wr, int wc, int fr_in, int fq_in) const {
;     ...
;                 if (grp > 0 && fr == 0) { const PG8_LAS float* xp = xr + ((grp - 1) * 2) * 256 + cl;
;                     hg2 = *(const PG8_LAS f32x4*)(xp); hg3 = *(const PG8_LAS f32x4*)(xp + 256); hv2 = *(const PG8_LAS f32x4*)(xp + 128); hv3 = *(const PG8_LAS f32x4*)(xp + 256 + 128); }
;                 f32x4 pg2, pg1, pv2, pv1;
;                 {
;                     const f32x4 g2 = acc[ai][0][2][n] * rs[ai][2], g3 = acc[ai][0][3][n] * rs[ai][3], v2 = acc[ai][1][2][n] * rs[ai][2], v3 = acc[ai][1][3][n] * rs[ai][3];
; #pragma unroll
;                     for (int i = 0; i < 4; ++i) {
;                         float a0 = g2[i], a1 = g3[i], a2 = v2[i], a3 = v3[i];
;                         asm volatile("" : "+v"(a0), "+v"(a1), "+v"(a2), "+v"(a3));
;                         const float t0 = DPPF(a0, 0x111), t1 = DPPF(a1, 0x111), t2 = DPPF(a2, 0x111), t3 = DPPF(a3, 0x111);
;                         pg2[i] = t0 + hg2[i]; pg1[i] = t1 + hg3[i]; pv2[i] = t2 + hv2[i]; pv1[i] = t3 + hv3[i]; }
;                 }
; #pragma unroll
;                 for (int m = 0; m < 4; ++m) {
;                     const f32x4 gc = acc[ai][0][m][n] * rs[ai][m], vc = acc[ai][1][m][n] * rs[ai][m];
;                     const f32x4 cgt = bg + wg0 * pg2 + wg1 * pg1 + wg2 * gc, cvl = bv + wv0 * pv2 + wv1 * pv1 + wv2 * vc;
;                     float a[4];
; #pragma unroll
;                     for (int i = 0; i < 4; ++i) a[i] = cgt[i] * sigmoidf_(cgt[i]) * cvl[i];
;                     u32x2 w; w.x = pk2(a[0], a[1]); w.y = pk2(a[2], a[3]);
;                     *(u32x2*)(A + (size_t)(u.pm * BM + ai * 128 + wr * 64 + 4 * fr + m) * DFF + ch) = w;
;                     pg2 = pg1; pg1 = gc; pv2 = pv1; pv1 = vc;
	v_pk_add_f32 v[40:41], v[40:41], v[52:53]
	v_pk_mul_f32 v[28:29], v[28:29], v[48:49]
	v_mov_b32_dpp v55, v59 row_shr:1 row_mask:0xf bank_mask:0xf bound_ctrl:1
	v_pk_add_f32 v[36:37], v[36:37], v[54:55]
	v_pk_fma_f32 v[40:41], v[84:85], v[40:41], v[96:97]
	v_pk_fma_f32 v[40:41], v[88:89], v[36:37], v[40:41]
	v_mul_f32_e32 v63, v14, v74
	v_pk_fma_f32 v[40:41], v[28:29], v[92:93], v[40:41]
	v_mul_f32_e32 v101, v6, v75
	v_mul_f32_e32 v103, v10, v74
	v_mul_f32_e32 v109, v2, v75
	v_mov_b32_dpp v59, v61 row_shr:1 row_mask:0xf bank_mask:0xf bound_ctrl:1
	v_exp_f32_e32 v52, v40
	v_exp_f32_e32 v53, v41
	v_mov_b32_dpp v61, v62 row_shr:1 row_mask:0xf bank_mask:0xf bound_ctrl:1
	v_mov_b32_dpp v100, v101 row_shr:1 row_mask:0xf bank_mask:0xf bound_ctrl:1
	v_mov_b32_dpp v102, v103 row_shr:1 row_mask:0xf bank_mask:0xf bound_ctrl:1
	v_mov_b32_dpp v108, v109 row_shr:1 row_mask:0xf bank_mask:0xf bound_ctrl:1
	v_mul_f32_e32 v101, v15, v74
	v_mul_f32_e32 v103, v7, v75
	v_mul_f32_e32 v109, v11, v74
	v_mul_f32_e32 v110, v3, v75
	v_mov_b32_dpp v62, v63 row_shr:1 row_mask:0xf bank_mask:0xf bound_ctrl:1
	v_add_f32_e32 v52, 1.0, v52
	v_add_f32_e32 v53, 1.0, v53
	v_mov_b32_dpp v63, v101 row_shr:1 row_mask:0xf bank_mask:0xf bound_ctrl:1
	v_rcp_f32_e32 v52, v52
	v_rcp_f32_e32 v53, v53
	v_mov_b32_dpp v101, v103 row_shr:1 row_mask:0xf bank_mask:0xf bound_ctrl:1
	v_pk_add_f32 v[42:43], v[42:43], v[62:63]
	v_mov_b32_e32 v111, v72
	v_mov_b32_dpp v103, v109 row_shr:1 row_mask:0xf bank_mask:0xf bound_ctrl:1
	v_pk_add_f32 v[38:39], v[38:39], v[100:101]
	v_pk_fma_f32 v[42:43], v[86:87], v[42:43], v[98:99]
	v_mov_b32_dpp v109, v110 row_shr:1 row_mask:0xf bank_mask:0xf bound_ctrl:1
	v_mov_b32_e32 v110, v72
	v_pk_mul_f32 v[30:31], v[30:31], v[110:111]
	v_pk_fma_f32 v[42:43], v[90:91], v[38:39], v[42:43]
	v_pk_mul_f32 v[40:41], v[40:41], v[52:53]
	v_pk_fma_f32 v[42:43], v[30:31], v[94:95], v[42:43]
	v_pk_add_f32 v[32:33], v[32:33], v[58:59]
	v_exp_f32_e32 v52, v42
	v_exp_f32_e32 v53, v43
	v_pk_mul_f32 v[24:25], v[24:25], v[48:49]
	v_pk_add_f32 v[48:49], v[104:105], v[60:61]
	v_pk_fma_f32 v[32:33], v[64:65], v[32:33], v[80:81]
	v_add_f32_e32 v52, 1.0, v52
	v_add_f32_e32 v53, 1.0, v53
	v_pk_fma_f32 v[32:33], v[68:69], v[48:49], v[32:33]
	v_rcp_f32_e32 v52, v52
	v_rcp_f32_e32 v53, v53
	v_pk_fma_f32 v[32:33], v[24:25], v[76:77], v[32:33]
	v_pk_add_f32 v[34:35], v[34:35], v[102:103]
	v_pk_mul_f32 v[32:33], v[32:33], v[40:41]
	v_pk_add_f32 v[40:41], v[106:107], v[108:109]
	v_pk_fma_f32 v[34:35], v[66:67], v[34:35], v[82:83]
	v_pk_mul_f32 v[26:27], v[26:27], v[110:111]
	v_pk_fma_f32 v[34:35], v[70:71], v[40:41], v[34:35]
	v_pk_mul_f32 v[42:43], v[42:43], v[52:53]
	v_pk_fma_f32 v[34:35], v[26:27], v[78:79], v[34:35]
	v_cvt_pk_bf16_f32 v32, v32, v33
	v_pk_mul_f32 v[34:35], v[34:35], v[42:43]
	v_mov_b32_e32 v50, v73
	v_cvt_pk_bf16_f32 v33, v34, v35
	v_lshl_add_u64 v[34:35], v[122:123], 0, v[56:57]
	v_mov_b32_e32 v51, v73
	global_store_dwordx2 v[34:35], v[32:33], off
	v_pk_fma_f32 v[32:33], v[84:85], v[36:37], v[96:97]
	v_pk_mul_f32 v[20:21], v[20:21], v[50:51]
	v_pk_fma_f32 v[32:33], v[28:29], v[88:89], v[32:33]
	v_mov_b32_e32 v72, v73
	v_pk_fma_f32 v[32:33], v[20:21], v[92:93], v[32:33]
	v_pk_mul_f32 v[22:23], v[22:23], v[72:73]
	v_exp_f32_e32 v34, v32
	v_exp_f32_e32 v35, v33
	v_mov_b32_e32 v46, v74
	v_mov_b32_e32 v47, v74
	v_add_f32_e32 v34, 1.0, v34
	v_add_f32_e32 v35, 1.0, v35
	v_rcp_f32_e32 v34, v34
	v_rcp_f32_e32 v35, v35
	v_pk_fma_f32 v[28:29], v[28:29], v[84:85], v[96:97]
	v_mov_b32_e32 v44, v75
	v_mov_b32_e32 v45, v75
	v_pk_mul_f32 v[32:33], v[32:33], v[34:35]
	v_pk_fma_f32 v[34:35], v[86:87], v[38:39], v[98:99]
	v_pk_mul_f32 v[12:13], v[12:13], v[46:47]
	v_pk_fma_f32 v[34:35], v[30:31], v[90:91], v[34:35]
	v_pk_fma_f32 v[28:29], v[20:21], v[88:89], v[28:29]
	v_pk_fma_f32 v[34:35], v[22:23], v[94:95], v[34:35]
	v_pk_fma_f32 v[20:21], v[20:21], v[84:85], v[96:97]
	v_exp_f32_e32 v38, v34
	v_exp_f32_e32 v39, v35
	v_pk_fma_f32 v[28:29], v[12:13], v[92:93], v[28:29]
; __device__ __forceinline__ unsigned pk2(float lo, float hi) { f32x2_t v = {lo, hi}; bf16x2_t b = __builtin_convertvector(v, bf16x2_t); return __builtin_bit_cast(unsigned, b); }
; __device__ __forceinline__ float fast_rsq(float x) { return __builtin_amdgcn_rsqf(x); }
; __device__ __forceinline__ float sigmoidf_(float v) { return fast_rcp(1.0f + fast_exp2(-v * LOG2E)); }
;     __device__ __forceinline__ void run(const f32x4 (&acc)[2][2][4][2], const Unit& u, const Unit& nxt, bool has_next, int ui, int wr, int wc, int fr_in, int fq_in) const {
;     ...
;                 for (int m = 0; m < 4; ++m) {
;                     const f32x4 gc = acc[ai][0][m][n] * rs[ai][m], vc = acc[ai][1][m][n] * rs[ai][m];
;                     const f32x4 cgt = bg + wg0 * pg2 + wg1 * pg1 + wg2 * gc, cvl = bv + wv0 * pv2 + wv1 * pv1 + wv2 * vc;
;                     float a[4];
; #pragma unroll
;                     for (int i = 0; i < 4; ++i) a[i] = cgt[i] * sigmoidf_(cgt[i]) * cvl[i];
;                     u32x2 w; w.x = pk2(a[0], a[1]); w.y = pk2(a[2], a[3]);
;                     *(u32x2*)(A + (size_t)(u.pm * BM + ai * 128 + wr * 64 + 4 * fr + m) * DFF + ch) = w;
;                     pg2 = pg1; pg1 = gc; pv2 = pv1; pv1 = vc;
;                 }
;                 asm volatile("" ::: "memory");
;             }
;         }
;         if (has_next) {
;             prm[(slot ^ 1) * 1024 + tid] = nx0; prm[(slot ^ 1) * 1024 + tid + 512] = nx1;
;             if (tid < 256) rsd[(slot ^ 1) * 256 + tid] = fast_rsq(nrs * (1.0f / DM) + EPS);
;         }
	v_pk_mul_f32 v[4:5], v[4:5], v[44:45]
	v_pk_fma_f32 v[12:13], v[12:13], v[88:89], v[20:21]
	v_pk_fma_f32 v[36:37], v[64:65], v[48:49], v[80:81]
	v_add_f32_e32 v38, 1.0, v38
	v_add_f32_e32 v39, 1.0, v39
	v_pk_fma_f32 v[4:5], v[4:5], v[92:93], v[12:13]
	v_pk_mul_f32 v[16:17], v[16:17], v[50:51]
	v_rcp_f32_e32 v38, v38
	v_rcp_f32_e32 v39, v39
	v_pk_fma_f32 v[36:37], v[24:25], v[68:69], v[36:37]
	v_pk_fma_f32 v[36:37], v[16:17], v[76:77], v[36:37]
	v_exp_f32_e32 v12, v4
	v_exp_f32_e32 v13, v5
	v_pk_mul_f32 v[32:33], v[36:37], v[32:33]
	v_pk_fma_f32 v[36:37], v[66:67], v[40:41], v[82:83]
	v_pk_mul_f32 v[18:19], v[18:19], v[72:73]
	v_pk_fma_f32 v[36:37], v[26:27], v[70:71], v[36:37]
	v_pk_mul_f32 v[34:35], v[34:35], v[38:39]
	v_pk_fma_f32 v[36:37], v[18:19], v[78:79], v[36:37]
	v_add_f32_e32 v12, 1.0, v12
	v_pk_mul_f32 v[34:35], v[36:37], v[34:35]
	v_add_f32_e32 v13, 1.0, v13
	v_cvt_pk_bf16_f32 v32, v32, v33
	v_cvt_pk_bf16_f32 v33, v34, v35
	v_lshl_add_u64 v[34:35], v[124:125], 0, v[56:57]
	v_rcp_f32_e32 v12, v12
	v_rcp_f32_e32 v13, v13
	global_store_dwordx2 v[34:35], v[32:33], off
	v_exp_f32_e32 v34, v28
	v_mov_b32_e32 v32, v74
	v_exp_f32_e32 v35, v29
	v_mov_b32_e32 v33, v74
	v_pk_mul_f32 v[14:15], v[14:15], v[32:33]
	v_mov_b32_e32 v74, v75
	v_pk_mul_f32 v[4:5], v[4:5], v[12:13]
	v_pk_fma_f32 v[12:13], v[22:23], v[86:87], v[98:99]
	v_pk_mul_f32 v[6:7], v[6:7], v[74:75]
	v_pk_fma_f32 v[12:13], v[14:15], v[90:91], v[12:13]
	v_pk_fma_f32 v[30:31], v[30:31], v[86:87], v[98:99]
	v_pk_fma_f32 v[6:7], v[6:7], v[94:95], v[12:13]
	v_pk_fma_f32 v[30:31], v[22:23], v[90:91], v[30:31]
	v_pk_fma_f32 v[30:31], v[14:15], v[94:95], v[30:31]
	v_exp_f32_e32 v14, v6
	v_exp_f32_e32 v15, v7
	v_pk_mul_f32 v[10:11], v[10:11], v[32:33]
	v_exp_f32_e32 v32, v30
	v_exp_f32_e32 v33, v31
	v_add_f32_e32 v14, 1.0, v14
	v_add_f32_e32 v15, 1.0, v15
	v_add_f32_e32 v34, 1.0, v34
	v_add_f32_e32 v35, 1.0, v35
	v_pk_fma_f32 v[24:25], v[24:25], v[64:65], v[80:81]
	v_rcp_f32_e32 v14, v14
	v_rcp_f32_e32 v15, v15
	v_rcp_f32_e32 v34, v34
	v_rcp_f32_e32 v35, v35
	v_pk_mul_f32 v[8:9], v[8:9], v[46:47]
	v_add_f32_e32 v32, 1.0, v32
	v_add_f32_e32 v33, 1.0, v33
	v_pk_fma_f32 v[24:25], v[16:17], v[68:69], v[24:25]
	v_pk_fma_f32 v[12:13], v[16:17], v[64:65], v[80:81]
	v_rcp_f32_e32 v32, v32
	v_rcp_f32_e32 v33, v33
	v_pk_fma_f32 v[24:25], v[8:9], v[76:77], v[24:25]
	v_pk_mul_f32 v[0:1], v[0:1], v[44:45]
	v_pk_fma_f32 v[8:9], v[8:9], v[68:69], v[12:13]
	v_pk_fma_f32 v[26:27], v[26:27], v[66:67], v[82:83]
	v_pk_fma_f32 v[0:1], v[0:1], v[76:77], v[8:9]
	v_pk_mul_f32 v[28:29], v[28:29], v[34:35]
	v_pk_mul_f32 v[0:1], v[0:1], v[4:5]
	v_pk_mul_f32 v[4:5], v[6:7], v[14:15]
	v_pk_fma_f32 v[6:7], v[18:19], v[66:67], v[82:83]
	v_pk_fma_f32 v[26:27], v[18:19], v[70:71], v[26:27]
	v_pk_mul_f32 v[2:3], v[2:3], v[74:75]
	v_pk_fma_f32 v[6:7], v[10:11], v[70:71], v[6:7]
	v_pk_mul_f32 v[24:25], v[24:25], v[28:29]
	v_pk_mul_f32 v[28:29], v[30:31], v[32:33]
	v_pk_fma_f32 v[26:27], v[10:11], v[78:79], v[26:27]
	v_pk_fma_f32 v[2:3], v[2:3], v[78:79], v[6:7]
	v_pk_mul_f32 v[26:27], v[26:27], v[28:29]
	v_pk_mul_f32 v[2:3], v[2:3], v[4:5]
	v_cvt_pk_bf16_f32 v24, v24, v25
	v_cvt_pk_bf16_f32 v25, v26, v27
	v_lshl_add_u64 v[26:27], v[130:131], 0, v[56:57]
	v_cvt_pk_bf16_f32 v0, v0, v1
	v_cvt_pk_bf16_f32 v1, v2, v3
	v_lshl_add_u64 v[2:3], v[134:135], 0, v[56:57]
	global_store_dwordx2 v[26:27], v[24:25], off
	global_store_dwordx2 v[2:3], v[0:1], off
	s_and_b64 vcc, exec, s[10:11]
	s_mov_b64 s[0:1], -1
	s_cbranch_vccnz .LBB0_681
	s_xor_b32 s4, s35, 0x400
	v_lshlrev_b32_e32 v0, 2, v226
	v_lshl_add_u32 v0, s4, 2, v0
	v_add_u32_e32 v0, 0x22040, v0
	v_cmp_gt_i32_e32 vcc, s65, v226
	s_waitcnt vmcnt(0)
	v_mul_f32_e32 v228, 0xbfb8aa3b, v228
	v_mul_f32_e32 v227, 0xbf317218, v227
	ds_write2st64_b32 v0, v228, v227 offset1:8
	s_and_saveexec_b64 s[0:1], vcc
	s_cbranch_execz .LBB0_728
	v_rsq_f32_e32 v0, v229
	v_lshl_add_u32 v1, v226, 2, s4
	v_add_u32_e32 v1, 0x24040, v1
	ds_write_b32 v1, v0

; __device__ __forceinline__ unsigned pk2(float lo, float hi) { f32x2_t v = {lo, hi}; bf16x2_t b = __builtin_convertvector(v, bf16x2_t); return __builtin_bit_cast(unsigned, b); }
; __device__ __forceinline__ float fast_rsq(float x) { return __builtin_amdgcn_rsqf(x); }
; __device__ __forceinline__ float rsq_sum(const u64_t* rsq, int row) { return (float)rsq[row] * (1.0f / 16777216.0f); }
; __device__ __forceinline__ float sigmoidf_(float v) { return fast_rcp(1.0f + fast_exp2(-v * LOG2E)); }
;     __device__ __forceinline__ void operator()(const f32x4 (&acc)[2][2][4][2], const Unit& u, int wr, int wc, int fr_in, int fq_in) const {
;     ...
;         const int rowb = u.pm * BM + wr * 64 + fr;
;         float rs[2][4];
; #pragma unroll
;         for (int ai = 0; ai < 2; ++ai)
; #pragma unroll
;             for (int m = 0; m < 4; ++m) rs[ai][m] = rsq_sum(rsq, rowb + ai * 128 + m * 16);
; #pragma unroll
;         for (int ai = 0; ai < 2; ++ai)
; #pragma unroll
;             for (int m = 0; m < 4; ++m) rs[ai][m] = fast_rsq(rs[ai][m] * (1.0f / DM) + EPS);
; #pragma unroll
;         for (int ai = 0; ai < 2; ++ai)
; #pragma unroll
;             for (int m = 0; m < 4; ++m) {
;                 const int row = rowb + ai * 128 + m * 16;
; #pragma unroll
;                 for (int bj = 0; bj < 2; ++bj) {
;                     const size_t off = (size_t)row * DM + u.pn * BM + bj * HALF + wc * 32 + 8 * fq;
;                     const f32x4 a = acc[ai][bj][m][0] * rs[ai][m], b = acc[ai][bj][m][1] * rs[ai][m];
;                     u32x4 w; w.x = pk2(sigmoidf_(a[0]), sigmoidf_(a[1])); w.y = pk2(sigmoidf_(a[2]), sigmoidf_(a[3]));
;                     w.z = pk2(sigmoidf_(b[0]), sigmoidf_(b[1])); w.w = pk2(sigmoidf_(b[2]), sigmoidf_(b[3]));
;                     *(u32x4*)(SG + off) = w;
.LBB0_968:
	s_lshl_b32 s0, s4, 8
	v_mov_b32_e32 v144, v145
	v_mov_b32_e32 v188, v147
	s_add_i32 s0, s0, s53
	s_nop 0
	v_add_u32_e32 v170, s0, v144
	v_ashrrev_i32_e32 v171, 31, v170
	v_lshl_add_u64 v[172:173], v[170:171], 3, s[8:9]
	global_load_dwordx2 v[174:175], v[172:173], off
	global_load_dwordx2 v[176:177], v[172:173], off offset:128
	global_load_dwordx2 v[178:179], v[172:173], off offset:256
	global_load_dwordx2 v[180:181], v[172:173], off offset:384
	global_load_dwordx2 v[182:183], v[172:173], off offset:1024
	global_load_dwordx2 v[184:185], v[172:173], off offset:1152
	global_load_dwordx2 v[186:187], v[172:173], off offset:1280
	s_nop 0
	global_load_dwordx2 v[172:173], v[172:173], off offset:1408
	s_lshl_b32 s0, s67, 8
	v_lshlrev_b64 v[170:171], 11, v[170:171]
	s_ashr_i32 s1, s0, 31
	s_waitcnt vmcnt(0)
	v_ffbh_u32_e32 v144, v175
	v_min_u32_e32 v144, 32, v144
	v_lshlrev_b64 v[174:175], v144, v[174:175]
	v_ffbh_u32_e32 v146, v177
	v_ffbh_u32_e32 v148, v179
	v_ffbh_u32_e32 v150, v181
	v_min_u32_e32 v174, 1, v174
	v_ffbh_u32_e32 v190, v173
	v_min_u32_e32 v190, 32, v190
	v_lshlrev_b64 v[172:173], v190, v[172:173]
	v_min_u32_e32 v146, 32, v146
	v_min_u32_e32 v148, 32, v148
	v_min_u32_e32 v150, 32, v150
	v_min_u32_e32 v172, 1, v172
	v_or_b32_e32 v174, v175, v174
	v_ffbh_u32_e32 v152, v183
	v_ffbh_u32_e32 v154, v185
	v_ffbh_u32_e32 v189, v187
	v_lshlrev_b64 v[176:177], v146, v[176:177]
	v_lshlrev_b64 v[178:179], v148, v[178:179]
	v_lshlrev_b64 v[180:181], v150, v[180:181]
	v_or_b32_e32 v172, v173, v172
	v_cvt_f32_u32_e32 v173, v174
	v_min_u32_e32 v152, 32, v152
	v_min_u32_e32 v154, 32, v154
	v_min_u32_e32 v189, 32, v189
	v_min_u32_e32 v176, 1, v176
	v_min_u32_e32 v178, 1, v178
	v_min_u32_e32 v180, 1, v180
	v_lshlrev_b64 v[182:183], v152, v[182:183]
	v_lshlrev_b64 v[184:185], v154, v[184:185]
	v_lshlrev_b64 v[186:187], v189, v[186:187]
	v_or_b32_e32 v175, v177, v176
	v_or_b32_e32 v176, v179, v178
	v_or_b32_e32 v177, v181, v180
	v_cvt_f32_u32_e32 v172, v172
	v_sub_u32_e32 v144, 32, v144
	v_min_u32_e32 v182, 1, v182
	v_min_u32_e32 v184, 1, v184
	v_min_u32_e32 v186, 1, v186
	v_cvt_f32_u32_e32 v174, v175
	v_cvt_f32_u32_e32 v175, v176
	v_cvt_f32_u32_e32 v176, v177
	v_or_b32_e32 v178, v183, v182
	v_or_b32_e32 v179, v185, v184
	v_or_b32_e32 v180, v187, v186
	v_ldexp_f32 v144, v173, v144
	v_sub_u32_e32 v190, 32, v190
	v_cvt_f32_u32_e32 v177, v178
	v_cvt_f32_u32_e32 v178, v179
	v_cvt_f32_u32_e32 v179, v180
	v_mul_f32_e32 v144, 0x33800000, v144
	v_sub_u32_e32 v150, 32, v150
	v_ldexp_f32 v172, v172, v190
	v_fmamk_f32 v144, v144, 0x3a800000, v169
	v_ldexp_f32 v150, v176, v150
	v_mul_f32_e32 v176, 0x33800000, v172
	v_rsq_f32_e32 v172, v144
	s_nop 0
	v_mul_f32_e32 v172, 0xbfb8aa3b, v172
	v_sub_u32_e32 v189, 32, v189
	v_ldexp_f32 v173, v179, v189
	v_mul_f32_e32 v173, 0x33800000, v173
	v_pk_mul_f32 v[122:123], v[122:123], v[172:173] op_sel_hi:[1,0]
	v_sub_u32_e32 v148, 32, v148
	v_exp_f32_e32 v122, v122
	v_sub_u32_e32 v154, 32, v154
	v_pk_mul_f32 v[124:125], v[124:125], v[172:173] op_sel_hi:[1,0]
	v_pk_mul_f32 v[120:121], v[120:121], v[172:173] op_sel_hi:[1,0]
	v_ldexp_f32 v148, v175, v148
	v_ldexp_f32 v154, v178, v154
	v_mul_f32_e32 v148, 0x33800000, v148
	v_mul_f32_e32 v175, 0x33800000, v154
	v_exp_f32_e32 v124, v124
	v_exp_f32_e32 v125, v125
	v_exp_f32_e32 v120, v120
	v_exp_f32_e32 v121, v121
	v_fmamk_f32 v148, v148, 0x3a800000, v169
	v_fmamk_f32 v144, v175, 0x3a800000, v169
	v_pk_mul_f32 v[126:127], v[126:127], v[172:173] op_sel_hi:[1,0]
	v_add_f32_e32 v122, 1.0, v122
	v_rsq_f32_e32 v154, v148
	s_nop 0
	v_mul_f32_e32 v154, 0xbfb8aa3b, v154
	v_rsq_f32_e32 v148, v144
	s_nop 0
	v_mul_f32_e32 v148, 0xbfb8aa3b, v148
	v_fmamk_f32 v144, v173, 0x3a800000, v169
	v_rcp_f32_e32 v173, v122
	v_exp_f32_e32 v126, v126
	v_exp_f32_e32 v127, v127
	v_exp_f32_e32 v123, v123
	v_add_f32_e32 v124, 1.0, v124
	v_add_f32_e32 v125, 1.0, v125
	v_add_f32_e32 v120, 1.0, v120
	v_add_f32_e32 v121, 1.0, v121
	v_rcp_f32_e32 v124, v124
	v_rcp_f32_e32 v125, v125
	v_rcp_f32_e32 v120, v120
	v_rcp_f32_e32 v121, v121
	v_sub_u32_e32 v146, 32, v146
	v_pk_mul_f32 v[112:113], v[112:113], v[172:173] op_sel_hi:[1,0]
	v_sub_u32_e32 v152, 32, v152
	v_ldexp_f32 v146, v174, v146
	v_add_f32_e32 v126, 1.0, v126
	v_add_f32_e32 v127, 1.0, v127
	v_add_f32_e32 v122, 1.0, v123
	v_ldexp_f32 v152, v177, v152
	v_mul_f32_e32 v146, 0x33800000, v146
	v_rcp_f32_e32 v126, v126
	v_rcp_f32_e32 v127, v127
	v_rcp_f32_e32 v175, v122
	v_exp_f32_e32 v112, v112
	v_mul_f32_e32 v150, 0x33800000, v150
	v_mul_f32_e32 v152, 0x33800000, v152
	v_fmamk_f32 v146, v146, 0x3a800000, v169
	v_cvt_pk_bf16_f32 v122, v124, v125
	v_cvt_pk_bf16_f32 v124, v120, v121
	v_lshl_add_u64 v[120:121], s[16:17], 0, v[170:171]
	v_exp_f32_e32 v113, v113
	v_fmamk_f32 v150, v150, 0x3a800000, v169
	v_fmamk_f32 v177, v152, 0x3a800000, v169
	v_rsq_f32_e32 v174, v146
	s_nop 0
	v_mul_f32_e32 v174, 0xbfb8aa3b, v174
	v_rsq_f32_e32 v146, v144
	s_nop 0
	v_mul_f32_e32 v146, 0xbfb8aa3b, v146
	v_fmamk_f32 v144, v176, 0x3a800000, v169
	v_lshlrev_b32_e32 v176, 3, v188
	v_lshl_add_u64 v[120:121], s[0:1], 1, v[120:121]
	v_rsq_f32_e32 v152, v150
	s_nop 0
	v_mul_f32_e32 v152, 0xbfb8aa3b, v152
	v_rsq_f32_e32 v150, v177
	s_nop 0
	v_mul_f32_e32 v150, 0xbfb8aa3b, v150
	v_ashrrev_i32_e32 v177, 31, v176
	v_lshl_add_u64 v[120:121], v[120:121], 0, s[18:19]
	v_cvt_pk_bf16_f32 v123, v126, v127
	v_cvt_pk_bf16_f32 v125, v173, v175
	v_lshl_add_u64 v[120:121], v[176:177], 1, v[120:121]
	v_pk_mul_f32 v[114:115], v[114:115], v[172:173] op_sel_hi:[1,0]
	v_add_f32_e32 v112, 1.0, v112
	global_store_dwordx4 v[120:121], v[122:125], off
	v_pk_mul_f32 v[118:119], v[118:119], v[172:173] op_sel_hi:[1,0]
; __device__ __forceinline__ unsigned pk2(float lo, float hi) { f32x2_t v = {lo, hi}; bf16x2_t b = __builtin_convertvector(v, bf16x2_t); return __builtin_bit_cast(unsigned, b); }
; __device__ __forceinline__ float sigmoidf_(float v) { return fast_rcp(1.0f + fast_exp2(-v * LOG2E)); }
;     __device__ __forceinline__ void operator()(const f32x4 (&acc)[2][2][4][2], const Unit& u, int wr, int wc, int fr_in, int fq_in) const {
;     ...
;         for (int ai = 0; ai < 2; ++ai)
; #pragma unroll
;             for (int m = 0; m < 4; ++m) {
;                 const int row = rowb + ai * 128 + m * 16;
; #pragma unroll
;                 for (int bj = 0; bj < 2; ++bj) {
;                     const size_t off = (size_t)row * DM + u.pn * BM + bj * HALF + wc * 32 + 8 * fq;
;                     const f32x4 a = acc[ai][bj][m][0] * rs[ai][m], b = acc[ai][bj][m][1] * rs[ai][m];
;                     u32x4 w; w.x = pk2(sigmoidf_(a[0]), sigmoidf_(a[1])); w.y = pk2(sigmoidf_(a[2]), sigmoidf_(a[3]));
;                     w.z = pk2(sigmoidf_(b[0]), sigmoidf_(b[1])); w.w = pk2(sigmoidf_(b[2]), sigmoidf_(b[3]));
;                     *(u32x4*)(SG + off) = w;
;                 }
;             }
	v_pk_mul_f32 v[116:117], v[116:117], v[172:173] op_sel_hi:[1,0]
	v_rcp_f32_e32 v122, v112
	v_add_f32_e32 v112, 1.0, v113
	v_exp_f32_e32 v113, v114
	v_exp_f32_e32 v116, v116
	v_exp_f32_e32 v117, v117
	v_exp_f32_e32 v118, v118
	v_exp_f32_e32 v119, v119
	v_exp_f32_e32 v114, v115
	v_rcp_f32_e32 v115, v112
	v_add_f32_e32 v112, 1.0, v113
	v_pk_mul_f32 v[104:105], v[104:105], v[174:175] op_sel_hi:[1,0]
	v_add_f32_e32 v116, 1.0, v116
	v_add_f32_e32 v117, 1.0, v117
	v_add_f32_e32 v118, 1.0, v118
	v_add_f32_e32 v119, 1.0, v119
	v_rcp_f32_e32 v123, v112
	v_add_f32_e32 v112, 1.0, v114
	v_rcp_f32_e32 v116, v116
	v_rcp_f32_e32 v117, v117
	v_rcp_f32_e32 v118, v118
	v_rcp_f32_e32 v119, v119
	v_rcp_f32_e32 v124, v112
	v_exp_f32_e32 v104, v104
	v_exp_f32_e32 v105, v105
	v_pk_mul_f32 v[108:109], v[108:109], v[174:175] op_sel_hi:[1,0]
	v_cvt_pk_bf16_f32 v112, v116, v117
	v_cvt_pk_bf16_f32 v113, v118, v119
	v_cvt_pk_bf16_f32 v114, v122, v115
	v_cvt_pk_bf16_f32 v115, v123, v124
	v_pk_mul_f32 v[110:111], v[110:111], v[174:175] op_sel_hi:[1,0]
	v_pk_mul_f32 v[106:107], v[106:107], v[174:175] op_sel_hi:[1,0]
	v_add_f32_e32 v104, 1.0, v104
	global_store_dwordx4 v[120:121], v[112:115], off offset:256
	v_exp_f32_e32 v108, v108
	v_exp_f32_e32 v109, v109
	v_rcp_f32_e32 v112, v104
	v_add_f32_e32 v104, 1.0, v105
	v_exp_f32_e32 v110, v110
	v_exp_f32_e32 v111, v111
	v_exp_f32_e32 v105, v106
	v_exp_f32_e32 v106, v107
	v_add_f32_e32 v108, 1.0, v108
	v_add_f32_e32 v109, 1.0, v109
	v_rcp_f32_e32 v108, v108
	v_rcp_f32_e32 v109, v109
	v_add_f32_e32 v110, 1.0, v110
	v_add_f32_e32 v111, 1.0, v111
	v_rcp_f32_e32 v107, v104
	v_add_f32_e32 v104, 1.0, v105
	v_pk_mul_f32 v[96:97], v[96:97], v[174:175] op_sel_hi:[1,0]
	v_rcp_f32_e32 v110, v110
	v_rcp_f32_e32 v111, v111
	v_rcp_f32_e32 v113, v104
	v_add_f32_e32 v104, 1.0, v106
	v_rcp_f32_e32 v114, v104
	v_exp_f32_e32 v96, v96
	s_mov_b64 s[0:1], 0x8000
	v_exp_f32_e32 v97, v97
	v_cvt_pk_bf16_f32 v104, v108, v109
	v_lshl_add_u64 v[108:109], v[120:121], 0, s[0:1]
	s_mov_b32 s0, 0x8000
	v_cvt_pk_bf16_f32 v105, v110, v111
	v_add_co_u32_e32 v110, vcc, s0, v120
	v_cvt_pk_bf16_f32 v106, v112, v107
	v_cvt_pk_bf16_f32 v107, v113, v114
	v_addc_co_u32_e32 v111, vcc, 0, v121, vcc
	v_pk_mul_f32 v[98:99], v[98:99], v[174:175] op_sel_hi:[1,0]
	v_add_f32_e32 v96, 1.0, v96
	global_store_dwordx4 v[110:111], v[104:107], off
	v_pk_mul_f32 v[102:103], v[102:103], v[174:175] op_sel_hi:[1,0]
	v_pk_mul_f32 v[100:101], v[100:101], v[174:175] op_sel_hi:[1,0]
	v_rcp_f32_e32 v104, v96
	v_add_f32_e32 v96, 1.0, v97
	v_exp_f32_e32 v97, v98
	v_exp_f32_e32 v100, v100
	v_exp_f32_e32 v101, v101
	v_exp_f32_e32 v102, v102
	v_exp_f32_e32 v103, v103
	v_exp_f32_e32 v98, v99
	v_rcp_f32_e32 v99, v96
	v_add_f32_e32 v96, 1.0, v97
	v_pk_mul_f32 v[88:89], v[88:89], v[154:155] op_sel_hi:[1,0]
	v_add_f32_e32 v100, 1.0, v100
	v_add_f32_e32 v101, 1.0, v101
	v_add_f32_e32 v102, 1.0, v102
	v_add_f32_e32 v103, 1.0, v103
	v_rcp_f32_e32 v105, v96
	v_add_f32_e32 v96, 1.0, v98
	v_rcp_f32_e32 v100, v100
	v_rcp_f32_e32 v101, v101
	v_rcp_f32_e32 v102, v102
	v_rcp_f32_e32 v103, v103
	v_rcp_f32_e32 v106, v96
	v_exp_f32_e32 v88, v88
	v_exp_f32_e32 v89, v89
	v_cvt_pk_bf16_f32 v96, v100, v101
	v_cvt_pk_bf16_f32 v97, v102, v103
	v_cvt_pk_bf16_f32 v98, v104, v99
	v_cvt_pk_bf16_f32 v99, v105, v106
	v_pk_mul_f32 v[94:95], v[94:95], v[154:155] op_sel_hi:[1,0]
	v_pk_mul_f32 v[90:91], v[90:91], v[154:155] op_sel_hi:[1,0]
	v_add_f32_e32 v88, 1.0, v88
	global_store_dwordx4 v[108:109], v[96:99], off offset:256
	v_pk_mul_f32 v[92:93], v[92:93], v[154:155] op_sel_hi:[1,0]
	v_rcp_f32_e32 v96, v88
	v_add_f32_e32 v88, 1.0, v89
	v_exp_f32_e32 v94, v94
	v_exp_f32_e32 v95, v95
	v_exp_f32_e32 v89, v90
	v_exp_f32_e32 v92, v92
	v_exp_f32_e32 v93, v93
	v_exp_f32_e32 v90, v91
	v_add_f32_e32 v94, 1.0, v94
	v_add_f32_e32 v95, 1.0, v95
	v_rcp_f32_e32 v91, v88
	v_add_f32_e32 v88, 1.0, v89
	v_pk_mul_f32 v[80:81], v[80:81], v[154:155] op_sel_hi:[1,0]
	v_add_f32_e32 v92, 1.0, v92
	v_add_f32_e32 v93, 1.0, v93
	v_rcp_f32_e32 v94, v94
	v_rcp_f32_e32 v95, v95
	v_rcp_f32_e32 v97, v88
	v_add_f32_e32 v88, 1.0, v90
	v_rcp_f32_e32 v92, v92
	v_rcp_f32_e32 v93, v93
	v_rcp_f32_e32 v98, v88
	v_exp_f32_e32 v80, v80
	v_exp_f32_e32 v81, v81
	s_mov_b32 s0, 0x10000
	v_cvt_pk_bf16_f32 v89, v94, v95
	v_add_co_u32_e32 v94, vcc, s0, v120
	v_cvt_pk_bf16_f32 v88, v92, v93
	v_cvt_pk_bf16_f32 v90, v96, v91
	v_cvt_pk_bf16_f32 v91, v97, v98
	v_addc_co_u32_e32 v95, vcc, 0, v121, vcc
	v_pk_mul_f32 v[82:83], v[82:83], v[154:155] op_sel_hi:[1,0]
	v_add_f32_e32 v80, 1.0, v80
	global_store_dwordx4 v[94:95], v[88:91], off
	v_pk_mul_f32 v[86:87], v[86:87], v[154:155] op_sel_hi:[1,0]
	v_pk_mul_f32 v[84:85], v[84:85], v[154:155] op_sel_hi:[1,0]
	v_rcp_f32_e32 v88, v80
	v_add_f32_e32 v80, 1.0, v81
	v_exp_f32_e32 v81, v82
	v_exp_f32_e32 v84, v84
	v_exp_f32_e32 v85, v85
	v_exp_f32_e32 v86, v86
	v_exp_f32_e32 v87, v87
	v_exp_f32_e32 v82, v83
	v_rcp_f32_e32 v83, v80
	v_add_f32_e32 v80, 1.0, v81
	v_pk_mul_f32 v[72:73], v[72:73], v[152:153] op_sel_hi:[1,0]
	v_add_f32_e32 v84, 1.0, v84
	v_add_f32_e32 v85, 1.0, v85
	v_add_f32_e32 v86, 1.0, v86
	v_add_f32_e32 v87, 1.0, v87
	v_rcp_f32_e32 v89, v80
	v_add_f32_e32 v80, 1.0, v82
	v_rcp_f32_e32 v84, v84
	v_rcp_f32_e32 v85, v85
	v_rcp_f32_e32 v86, v86
	v_rcp_f32_e32 v87, v87
	v_rcp_f32_e32 v90, v80
	v_exp_f32_e32 v72, v72
	v_exp_f32_e32 v73, v73
	v_lshl_add_u64 v[92:93], v[120:121], 0, s[20:21]
	v_cvt_pk_bf16_f32 v80, v84, v85
	v_cvt_pk_bf16_f32 v81, v86, v87
	v_cvt_pk_bf16_f32 v82, v88, v83
	v_cvt_pk_bf16_f32 v83, v89, v90
	v_pk_mul_f32 v[78:79], v[78:79], v[152:153] op_sel_hi:[1,0]
	v_pk_mul_f32 v[74:75], v[74:75], v[152:153] op_sel_hi:[1,0]
; __device__ __forceinline__ unsigned pk2(float lo, float hi) { f32x2_t v = {lo, hi}; bf16x2_t b = __builtin_convertvector(v, bf16x2_t); return __builtin_bit_cast(unsigned, b); }
; __device__ __forceinline__ float sigmoidf_(float v) { return fast_rcp(1.0f + fast_exp2(-v * LOG2E)); }
;     __device__ __forceinline__ void operator()(const f32x4 (&acc)[2][2][4][2], const Unit& u, int wr, int wc, int fr_in, int fq_in) const {
;     ...
;         for (int ai = 0; ai < 2; ++ai)
; #pragma unroll
;             for (int m = 0; m < 4; ++m) {
;                 const int row = rowb + ai * 128 + m * 16;
; #pragma unroll
;                 for (int bj = 0; bj < 2; ++bj) {
;                     const size_t off = (size_t)row * DM + u.pn * BM + bj * HALF + wc * 32 + 8 * fq;
;                     const f32x4 a = acc[ai][bj][m][0] * rs[ai][m], b = acc[ai][bj][m][1] * rs[ai][m];
;                     u32x4 w; w.x = pk2(sigmoidf_(a[0]), sigmoidf_(a[1])); w.y = pk2(sigmoidf_(a[2]), sigmoidf_(a[3]));
;                     w.z = pk2(sigmoidf_(b[0]), sigmoidf_(b[1])); w.w = pk2(sigmoidf_(b[2]), sigmoidf_(b[3]));
;                     *(u32x4*)(SG + off) = w;
;                 }
;             }
	v_add_f32_e32 v72, 1.0, v72
	global_store_dwordx4 v[92:93], v[80:83], off offset:256
	v_pk_mul_f32 v[76:77], v[76:77], v[152:153] op_sel_hi:[1,0]
	v_rcp_f32_e32 v80, v72
	v_add_f32_e32 v72, 1.0, v73
	v_exp_f32_e32 v78, v78
	v_exp_f32_e32 v79, v79
	v_exp_f32_e32 v73, v74
	v_exp_f32_e32 v76, v76
	v_exp_f32_e32 v77, v77
	v_exp_f32_e32 v74, v75
	v_add_f32_e32 v78, 1.0, v78
	v_add_f32_e32 v79, 1.0, v79
	v_rcp_f32_e32 v75, v72
	v_add_f32_e32 v72, 1.0, v73
	v_pk_mul_f32 v[64:65], v[64:65], v[152:153] op_sel_hi:[1,0]
	v_add_f32_e32 v76, 1.0, v76
	v_add_f32_e32 v77, 1.0, v77
	v_rcp_f32_e32 v78, v78
	v_rcp_f32_e32 v79, v79
	v_rcp_f32_e32 v81, v72
	v_add_f32_e32 v72, 1.0, v74
	v_rcp_f32_e32 v76, v76
	v_rcp_f32_e32 v77, v77
	v_rcp_f32_e32 v82, v72
	v_exp_f32_e32 v64, v64
	v_exp_f32_e32 v65, v65
	s_mov_b32 s0, 0x18000
	v_cvt_pk_bf16_f32 v73, v78, v79
	v_add_co_u32_e32 v78, vcc, s0, v120
	v_cvt_pk_bf16_f32 v72, v76, v77
	v_cvt_pk_bf16_f32 v74, v80, v75
	v_cvt_pk_bf16_f32 v75, v81, v82
	v_addc_co_u32_e32 v79, vcc, 0, v121, vcc
	v_pk_mul_f32 v[66:67], v[66:67], v[152:153] op_sel_hi:[1,0]
	v_add_f32_e32 v64, 1.0, v64
	global_store_dwordx4 v[78:79], v[72:75], off
	v_pk_mul_f32 v[70:71], v[70:71], v[152:153] op_sel_hi:[1,0]
	v_pk_mul_f32 v[68:69], v[68:69], v[152:153] op_sel_hi:[1,0]
	v_rcp_f32_e32 v72, v64
	v_add_f32_e32 v64, 1.0, v65
	v_exp_f32_e32 v65, v66
	v_exp_f32_e32 v68, v68
	v_exp_f32_e32 v69, v69
	v_exp_f32_e32 v70, v70
	v_exp_f32_e32 v71, v71
	v_exp_f32_e32 v66, v67
	v_rcp_f32_e32 v67, v64
	v_add_f32_e32 v64, 1.0, v65
	v_pk_mul_f32 v[56:57], v[56:57], v[150:151] op_sel_hi:[1,0]
	v_add_f32_e32 v68, 1.0, v68
	v_add_f32_e32 v69, 1.0, v69
	v_add_f32_e32 v70, 1.0, v70
	v_add_f32_e32 v71, 1.0, v71
	v_rcp_f32_e32 v73, v64
	v_add_f32_e32 v64, 1.0, v66
	v_rcp_f32_e32 v68, v68
	v_rcp_f32_e32 v69, v69
	v_rcp_f32_e32 v70, v70
	v_rcp_f32_e32 v71, v71
	v_rcp_f32_e32 v74, v64
	v_exp_f32_e32 v56, v56
	v_exp_f32_e32 v57, v57
	v_lshl_add_u64 v[76:77], v[120:121], 0, s[22:23]
	v_cvt_pk_bf16_f32 v64, v68, v69
	v_cvt_pk_bf16_f32 v65, v70, v71
	v_cvt_pk_bf16_f32 v66, v72, v67
	v_cvt_pk_bf16_f32 v67, v73, v74
	v_pk_mul_f32 v[62:63], v[62:63], v[150:151] op_sel_hi:[1,0]
	v_pk_mul_f32 v[58:59], v[58:59], v[150:151] op_sel_hi:[1,0]
	v_add_f32_e32 v56, 1.0, v56
	global_store_dwordx4 v[76:77], v[64:67], off offset:256
	v_pk_mul_f32 v[60:61], v[60:61], v[150:151] op_sel_hi:[1,0]
	v_rcp_f32_e32 v64, v56
	v_add_f32_e32 v56, 1.0, v57
	v_exp_f32_e32 v62, v62
	v_exp_f32_e32 v63, v63
	v_exp_f32_e32 v57, v58
	v_exp_f32_e32 v60, v60
	v_exp_f32_e32 v61, v61
	v_exp_f32_e32 v58, v59
	v_add_f32_e32 v62, 1.0, v62
	v_add_f32_e32 v63, 1.0, v63
	v_rcp_f32_e32 v59, v56
	v_add_f32_e32 v56, 1.0, v57
	v_pk_mul_f32 v[48:49], v[48:49], v[150:151] op_sel_hi:[1,0]
	v_add_f32_e32 v60, 1.0, v60
	v_add_f32_e32 v61, 1.0, v61
	v_rcp_f32_e32 v62, v62
	v_rcp_f32_e32 v63, v63
	v_rcp_f32_e32 v65, v56
	v_add_f32_e32 v56, 1.0, v58
	v_rcp_f32_e32 v60, v60
	v_rcp_f32_e32 v61, v61
	v_rcp_f32_e32 v66, v56
	v_exp_f32_e32 v48, v48
	v_exp_f32_e32 v49, v49
	v_cvt_pk_bf16_f32 v57, v62, v63
	v_add_co_u32_e32 v62, vcc, s62, v120
	v_cvt_pk_bf16_f32 v56, v60, v61
	v_cvt_pk_bf16_f32 v58, v64, v59
	v_cvt_pk_bf16_f32 v59, v65, v66
	v_addc_co_u32_e32 v63, vcc, 0, v121, vcc
	v_pk_mul_f32 v[50:51], v[50:51], v[150:151] op_sel_hi:[1,0]
	v_add_f32_e32 v48, 1.0, v48
	global_store_dwordx4 v[62:63], v[56:59], off
	v_pk_mul_f32 v[54:55], v[54:55], v[150:151] op_sel_hi:[1,0]
	v_pk_mul_f32 v[52:53], v[52:53], v[150:151] op_sel_hi:[1,0]
	v_rcp_f32_e32 v56, v48
	v_add_f32_e32 v48, 1.0, v49
	v_exp_f32_e32 v49, v50
	v_exp_f32_e32 v52, v52
	v_exp_f32_e32 v53, v53
	v_exp_f32_e32 v54, v54
	v_exp_f32_e32 v55, v55
	v_exp_f32_e32 v50, v51
	v_rcp_f32_e32 v51, v48
	v_add_f32_e32 v48, 1.0, v49
	v_pk_mul_f32 v[40:41], v[40:41], v[148:149] op_sel_hi:[1,0]
	v_add_f32_e32 v52, 1.0, v52
	v_add_f32_e32 v53, 1.0, v53
	v_add_f32_e32 v54, 1.0, v54
	v_add_f32_e32 v55, 1.0, v55
	v_rcp_f32_e32 v57, v48
	v_add_f32_e32 v48, 1.0, v50
	v_rcp_f32_e32 v52, v52
	v_rcp_f32_e32 v53, v53
	v_rcp_f32_e32 v54, v54
	v_rcp_f32_e32 v55, v55
	v_rcp_f32_e32 v58, v48
	v_exp_f32_e32 v40, v40
	v_exp_f32_e32 v41, v41
	s_mov_b64 s[0:1], 0x40000
	v_lshl_add_u64 v[60:61], v[120:121], 0, s[0:1]
	v_cvt_pk_bf16_f32 v48, v52, v53
	v_cvt_pk_bf16_f32 v49, v54, v55
	v_cvt_pk_bf16_f32 v50, v56, v51
	v_cvt_pk_bf16_f32 v51, v57, v58
	v_pk_mul_f32 v[46:47], v[46:47], v[148:149] op_sel_hi:[1,0]
	v_pk_mul_f32 v[42:43], v[42:43], v[148:149] op_sel_hi:[1,0]
	v_add_f32_e32 v40, 1.0, v40
	global_store_dwordx4 v[60:61], v[48:51], off offset:256
	v_pk_mul_f32 v[44:45], v[44:45], v[148:149] op_sel_hi:[1,0]
	v_rcp_f32_e32 v48, v40
	v_add_f32_e32 v40, 1.0, v41
	v_exp_f32_e32 v46, v46
	v_exp_f32_e32 v47, v47
	v_exp_f32_e32 v41, v42
	v_exp_f32_e32 v44, v44
	v_exp_f32_e32 v45, v45
	v_exp_f32_e32 v42, v43
	v_add_f32_e32 v46, 1.0, v46
	v_add_f32_e32 v47, 1.0, v47
	v_rcp_f32_e32 v43, v40
	v_add_f32_e32 v40, 1.0, v41
	v_pk_mul_f32 v[32:33], v[32:33], v[148:149] op_sel_hi:[1,0]
	v_add_f32_e32 v44, 1.0, v44
	v_add_f32_e32 v45, 1.0, v45
	v_rcp_f32_e32 v46, v46
	v_rcp_f32_e32 v47, v47
	v_rcp_f32_e32 v49, v40
	v_add_f32_e32 v40, 1.0, v42
	v_rcp_f32_e32 v44, v44
	v_rcp_f32_e32 v45, v45
	v_rcp_f32_e32 v50, v40
	v_exp_f32_e32 v32, v32
	v_exp_f32_e32 v33, v33
	v_cvt_pk_bf16_f32 v41, v46, v47
	v_add_co_u32_e32 v46, vcc, s63, v120
	v_cvt_pk_bf16_f32 v40, v44, v45
	v_cvt_pk_bf16_f32 v42, v48, v43
	v_cvt_pk_bf16_f32 v43, v49, v50
	v_addc_co_u32_e32 v47, vcc, 0, v121, vcc
	v_pk_mul_f32 v[34:35], v[34:35], v[148:149] op_sel_hi:[1,0]
; __device__ __forceinline__ unsigned pk2(float lo, float hi) { f32x2_t v = {lo, hi}; bf16x2_t b = __builtin_convertvector(v, bf16x2_t); return __builtin_bit_cast(unsigned, b); }
; __device__ __forceinline__ float sigmoidf_(float v) { return fast_rcp(1.0f + fast_exp2(-v * LOG2E)); }
;     __device__ __forceinline__ void operator()(const f32x4 (&acc)[2][2][4][2], const Unit& u, int wr, int wc, int fr_in, int fq_in) const {
;     ...
;         for (int ai = 0; ai < 2; ++ai)
; #pragma unroll
;             for (int m = 0; m < 4; ++m) {
;                 const int row = rowb + ai * 128 + m * 16;
; #pragma unroll
;                 for (int bj = 0; bj < 2; ++bj) {
;                     const size_t off = (size_t)row * DM + u.pn * BM + bj * HALF + wc * 32 + 8 * fq;
;                     const f32x4 a = acc[ai][bj][m][0] * rs[ai][m], b = acc[ai][bj][m][1] * rs[ai][m];
;                     u32x4 w; w.x = pk2(sigmoidf_(a[0]), sigmoidf_(a[1])); w.y = pk2(sigmoidf_(a[2]), sigmoidf_(a[3]));
;                     w.z = pk2(sigmoidf_(b[0]), sigmoidf_(b[1])); w.w = pk2(sigmoidf_(b[2]), sigmoidf_(b[3]));
;                     *(u32x4*)(SG + off) = w;
;                 }
;             }
	v_add_f32_e32 v32, 1.0, v32
	global_store_dwordx4 v[46:47], v[40:43], off
	v_pk_mul_f32 v[38:39], v[38:39], v[148:149] op_sel_hi:[1,0]
	v_pk_mul_f32 v[36:37], v[36:37], v[148:149] op_sel_hi:[1,0]
	v_rcp_f32_e32 v40, v32
	v_add_f32_e32 v32, 1.0, v33
	v_exp_f32_e32 v33, v34
	v_exp_f32_e32 v36, v36
	v_exp_f32_e32 v37, v37
	v_exp_f32_e32 v38, v38
	v_exp_f32_e32 v39, v39
	v_exp_f32_e32 v34, v35
	v_rcp_f32_e32 v35, v32
	v_add_f32_e32 v32, 1.0, v33
	v_pk_mul_f32 v[24:25], v[24:25], v[146:147] op_sel_hi:[1,0]
	v_add_f32_e32 v36, 1.0, v36
	v_add_f32_e32 v37, 1.0, v37
	v_add_f32_e32 v38, 1.0, v38
	v_add_f32_e32 v39, 1.0, v39
	v_rcp_f32_e32 v41, v32
	v_add_f32_e32 v32, 1.0, v34
	v_rcp_f32_e32 v36, v36
	v_rcp_f32_e32 v37, v37
	v_rcp_f32_e32 v38, v38
	v_rcp_f32_e32 v39, v39
	v_rcp_f32_e32 v42, v32
	v_exp_f32_e32 v24, v24
	v_exp_f32_e32 v25, v25
	v_lshl_add_u64 v[44:45], v[120:121], 0, s[24:25]
	v_cvt_pk_bf16_f32 v32, v36, v37
	v_cvt_pk_bf16_f32 v33, v38, v39
	v_cvt_pk_bf16_f32 v34, v40, v35
	v_cvt_pk_bf16_f32 v35, v41, v42
	v_pk_mul_f32 v[30:31], v[30:31], v[146:147] op_sel_hi:[1,0]
	v_pk_mul_f32 v[26:27], v[26:27], v[146:147] op_sel_hi:[1,0]
	v_add_f32_e32 v24, 1.0, v24
	global_store_dwordx4 v[44:45], v[32:35], off offset:256
	v_pk_mul_f32 v[28:29], v[28:29], v[146:147] op_sel_hi:[1,0]
	v_rcp_f32_e32 v32, v24
	v_add_f32_e32 v24, 1.0, v25
	v_exp_f32_e32 v30, v30
	v_exp_f32_e32 v31, v31
	v_exp_f32_e32 v25, v26
	v_exp_f32_e32 v28, v28
	v_exp_f32_e32 v29, v29
	v_exp_f32_e32 v26, v27
	v_add_f32_e32 v30, 1.0, v30
	v_add_f32_e32 v31, 1.0, v31
	v_rcp_f32_e32 v27, v24
	v_add_f32_e32 v24, 1.0, v25
	v_pk_mul_f32 v[16:17], v[16:17], v[146:147] op_sel_hi:[1,0]
	v_add_f32_e32 v28, 1.0, v28
	v_add_f32_e32 v29, 1.0, v29
	v_rcp_f32_e32 v30, v30
	v_rcp_f32_e32 v31, v31
	v_rcp_f32_e32 v33, v24
	v_add_f32_e32 v24, 1.0, v26
	v_rcp_f32_e32 v28, v28
	v_rcp_f32_e32 v29, v29
	v_rcp_f32_e32 v34, v24
	v_exp_f32_e32 v16, v16
	v_exp_f32_e32 v17, v17
	v_cvt_pk_bf16_f32 v25, v30, v31
	v_add_co_u32_e32 v30, vcc, s64, v120
	v_cvt_pk_bf16_f32 v24, v28, v29
	v_cvt_pk_bf16_f32 v26, v32, v27
	v_cvt_pk_bf16_f32 v27, v33, v34
	v_addc_co_u32_e32 v31, vcc, 0, v121, vcc
	v_pk_mul_f32 v[18:19], v[18:19], v[146:147] op_sel_hi:[1,0]
	v_add_f32_e32 v16, 1.0, v16
	global_store_dwordx4 v[30:31], v[24:27], off
	v_pk_mul_f32 v[22:23], v[22:23], v[146:147] op_sel_hi:[1,0]
	v_pk_mul_f32 v[20:21], v[20:21], v[146:147] op_sel_hi:[1,0]
	v_rcp_f32_e32 v24, v16
	v_add_f32_e32 v16, 1.0, v17
	v_rsq_f32_e32 v144, v144
	s_nop 0
	v_mul_f32_e32 v144, 0xbfb8aa3b, v144
	v_exp_f32_e32 v17, v18
	v_exp_f32_e32 v20, v20
	v_exp_f32_e32 v21, v21
	v_exp_f32_e32 v22, v22
	v_exp_f32_e32 v23, v23
	v_exp_f32_e32 v18, v19
	v_rcp_f32_e32 v19, v16
	v_add_f32_e32 v16, 1.0, v17
	v_pk_mul_f32 v[8:9], v[8:9], v[144:145] op_sel_hi:[1,0]
	v_add_f32_e32 v20, 1.0, v20
	v_add_f32_e32 v21, 1.0, v21
	v_add_f32_e32 v22, 1.0, v22
	v_add_f32_e32 v23, 1.0, v23
	v_rcp_f32_e32 v25, v16
	v_add_f32_e32 v16, 1.0, v18
	v_rcp_f32_e32 v20, v20
	v_rcp_f32_e32 v21, v21
	v_rcp_f32_e32 v22, v22
	v_rcp_f32_e32 v23, v23
	v_rcp_f32_e32 v26, v16
	v_exp_f32_e32 v8, v8
	v_exp_f32_e32 v9, v9
	v_lshl_add_u64 v[28:29], v[120:121], 0, s[26:27]
	v_cvt_pk_bf16_f32 v16, v20, v21
	v_cvt_pk_bf16_f32 v17, v22, v23
	v_cvt_pk_bf16_f32 v18, v24, v19
	v_cvt_pk_bf16_f32 v19, v25, v26
	v_pk_mul_f32 v[14:15], v[14:15], v[144:145] op_sel_hi:[1,0]
	v_pk_mul_f32 v[10:11], v[10:11], v[144:145] op_sel_hi:[1,0]
	v_add_f32_e32 v8, 1.0, v8
	global_store_dwordx4 v[28:29], v[16:19], off offset:256
	v_pk_mul_f32 v[12:13], v[12:13], v[144:145] op_sel_hi:[1,0]
	v_rcp_f32_e32 v16, v8
	v_add_f32_e32 v8, 1.0, v9
	v_exp_f32_e32 v14, v14
	v_exp_f32_e32 v15, v15
	v_exp_f32_e32 v9, v10
	v_exp_f32_e32 v12, v12
	v_exp_f32_e32 v13, v13
	v_exp_f32_e32 v10, v11
	v_add_f32_e32 v14, 1.0, v14
	v_add_f32_e32 v15, 1.0, v15
	v_rcp_f32_e32 v11, v8
	v_add_f32_e32 v8, 1.0, v9
	v_pk_mul_f32 v[0:1], v[0:1], v[144:145] op_sel_hi:[1,0]
	v_add_f32_e32 v12, 1.0, v12
	v_add_f32_e32 v13, 1.0, v13
	v_rcp_f32_e32 v14, v14
	v_rcp_f32_e32 v15, v15
	v_rcp_f32_e32 v17, v8
	v_add_f32_e32 v8, 1.0, v10
	v_rcp_f32_e32 v12, v12
	v_rcp_f32_e32 v13, v13
	v_rcp_f32_e32 v18, v8
	v_exp_f32_e32 v0, v0
	v_exp_f32_e32 v1, v1
	v_cvt_pk_bf16_f32 v9, v14, v15
	v_add_co_u32_e32 v14, vcc, s65, v120
	v_cvt_pk_bf16_f32 v8, v12, v13
	v_cvt_pk_bf16_f32 v10, v16, v11
	v_cvt_pk_bf16_f32 v11, v17, v18
	v_addc_co_u32_e32 v15, vcc, 0, v121, vcc
	v_pk_mul_f32 v[2:3], v[2:3], v[144:145] op_sel_hi:[1,0]
	v_add_f32_e32 v0, 1.0, v0
	global_store_dwordx4 v[14:15], v[8:11], off
	v_pk_mul_f32 v[6:7], v[6:7], v[144:145] op_sel_hi:[1,0]
	v_pk_mul_f32 v[4:5], v[4:5], v[144:145] op_sel_hi:[1,0]
	v_rcp_f32_e32 v8, v0
	v_add_f32_e32 v0, 1.0, v1
	v_exp_f32_e32 v1, v2
	v_exp_f32_e32 v4, v4
	v_exp_f32_e32 v5, v5
	v_exp_f32_e32 v6, v6
	v_exp_f32_e32 v7, v7
	v_exp_f32_e32 v2, v3
	v_rcp_f32_e32 v3, v0
	v_add_f32_e32 v0, 1.0, v1
	v_add_f32_e32 v4, 1.0, v4
	v_add_f32_e32 v5, 1.0, v5
	v_add_f32_e32 v6, 1.0, v6
	v_add_f32_e32 v7, 1.0, v7
	v_rcp_f32_e32 v9, v0
	v_add_f32_e32 v0, 1.0, v2
	v_rcp_f32_e32 v4, v4
	v_rcp_f32_e32 v5, v5
	v_rcp_f32_e32 v6, v6
	v_rcp_f32_e32 v7, v7
	v_rcp_f32_e32 v10, v0
	v_lshl_add_u64 v[12:13], v[120:121], 0, s[28:29]
	v_cvt_pk_bf16_f32 v0, v4, v5
	v_cvt_pk_bf16_f32 v1, v6, v7
	v_cvt_pk_bf16_f32 v2, v8, v3
	v_cvt_pk_bf16_f32 v3, v9, v10
	s_andn2_b64 vcc, exec, s[10:11]
	s_mov_b64 s[0:1], -1
	global_store_dwordx4 v[12:13], v[0:3], off offset:256
	s_cbranch_vccnz .LBB0_957
	s_andn2_b64 vcc, exec, s[6:7]
	s_cbranch_vccnz .LBB0_956
	s_barrier
	s_branch .LBB0_956

; template <int TYPE> __device__ __forceinline__ void attn_unit(const AttnCtx& C, int b, int h, int qb, LAS unsigned char* lds, int tid_in, unsigned* counter) {
;     ...
;     const int sq = 256 * qb + 32 * w + r32;
;     const size_t rowb = (size_t)b * SEQ;
;     LAS unsigned char* Kb = lds + AL_K; LAS unsigned char* Vb = lds + AL_V;
;     LAS float* Fb = (LAS float*)(lds + AL_F); LAS float* relb = (LAS float*)(lds + AL_REL); LAS float* wscr = (LAS float*)(lds + AL_WS) + w * 32;
;     constexpr int NPASS = (TYPE == 0) ? 2 : 1;
;     unsigned nclaim = 0u;
;     const float Mb = (TYPE == 0) ? C.Mb0 : (TYPE == 1) ? C.Mb1 : C.Mb2;
;     const int kwoff = w * 1024 + lane * 16, vwoff = ((tid & 7) >> 2) * 4096 + (tid >> 3) * 64 + (tid & 3) * 16;
;     const int vb0 = ((lane >> 4) & 1) * 32 + (lane & 3) * 8 + (4 * hi + ((lane & 15) >> 2)) * 64;
;     f32x16 o[2], o1[2];
;     if (TYPE == 2) { for (int i = tid; i < 257; i += 512) relb[i] = C.rel[h * 257 + i] * LOG2E; }
; #pragma unroll
;     for (int pass = 0; pass < NPASS; ++pass) {
;         int qcol, kcol, vcol;
;         if (TYPE == 0) { qcol = pass * 256 + 64 * h; kcol = 512 + pass * 256 + 64 * h; vcol = 1024 + 64 * h; }
;         else if (TYPE == 1) { qcol = 1280 + 64 * h; kcol = 1664 + 64 * h; vcol = 2048 + 64 * h; }
;         else { qcol = 2432 + 64 * h; kcol = 2816 + 64 * h; vcol = 3200 + 64 * h; }
;         const bf16_t* Qp = C.Z + (rowb + sq) * ZP + qcol + 8 * hi;
;         bf16x8 qr[4];
; #pragma unroll
;         for (int d0 = 0; d0 < 4; ++d0) qr[d0] = *(const bf16x8*)(Qp + 16 * d0);
;         float cinit = -Mb;
;         const float* f2p = C.F2 + (size_t)(b * 6 + h) * SEQ;
;         if (TYPE == 1) cinit += f2p[sq];
;         f32x16 cvec, zvec;
; #pragma unroll
;         for (int r = 0; r < 16; ++r) { cvec[r] = cinit; zvec[r] = 0.f; }
; #pragma unroll
;         for (int r = 0; r < 16; ++r) { o[0][r] = 0.f; o[1][r] = 0.f; }
;         float lsum = 0.f;
;         const bf16_t* kg = C.Z + (rowb + lane) * ZP + kcol + 8 * w;
;         const bf16_t* vg = C.Z + (rowb + (tid >> 3)) * ZP + vcol + 8 * (tid & 7);
;         u32x4 kreg = *(const u32x4*)(kg + (size_t)t0 * 64 * ZP), vreg = *(const u32x4*)(vg + (size_t)t0 * 64 * ZP);
;         u32x4 kreg2 = *(const u32x4*)(kg + (size_t)(t0 + 1) * 64 * ZP), vreg2 = *(const u32x4*)(vg + (size_t)(t0 + 1) * 64 * ZP);
;         float freg = 0.f, freg2 = 0.f;
.LBB0_1309:
	s_or_b64 exec, exec, s[4:5]
	s_ashr_i32 s10, s2, 7
	s_ashr_i32 s8, s2, 6
	s_add_i32 s10, s10, s33
	s_add_i32 s11, s33, 4
	s_add_i32 s0, s33, -8
	v_readlane_b32 s1, v251, 32
	s_cmp_gt_u32 s1, 2
	s_cselect_b32 s12, s0, 0
	s_lshl_b32 s7, s1, 8
	s_lshl_b32 s6, s8, 5
	v_and_b32_e32 v133, 31, v0
	s_add_i32 s16, s6, s7
	v_or_b32_e32 v2, s16, v133
	v_readlane_b32 s14, v251, 21
	s_lshl_b32 s94, s24, 12
	v_ashrrev_i32_e32 v3, 31, v2
	v_readlane_b32 s15, v251, 22
	v_lshl_add_u64 v[2:3], v[2:3], 0, s[94:95]
	v_bfe_u32 v132, v0, 5, 1
	v_mov_b64_e32 v[10:11], s[14:15]
	v_mad_u64_u32 v[12:13], s[2:3], v2, s23, v[10:11]
	v_mad_i32_i24 v13, v3, s23, v13
	s_lshl_b32 s2, s78, 7
	s_mov_b32 s3, s95
	v_lshl_add_u64 v[2:3], v[12:13], 0, s[2:3]
	v_lshlrev_b32_e32 v144, 4, v132
	v_and_b32_e32 v134, 63, v0
	v_lshl_add_u64 v[2:3], v[2:3], 0, v[144:145]
	s_mov_b64 s[4:5], 0x1300
	s_movk_i32 s1, 0x1000
	v_or_b32_e32 v5, s94, v134
	s_movk_i32 s0, 0xe00
	v_lshl_add_u64 v[12:13], v[2:3], 0, s[4:5]
	v_add_co_u32_e32 v2, vcc, s1, v2
	v_mul_lo_u32 v6, v5, s0
	s_nop 0
	v_addc_co_u32_e32 v3, vcc, 0, v3, vcc
	v_mov_b32_e32 v7, v145
	v_ashrrev_i32_e32 v4, 3, v0
	s_lshl_b32 s0, s8, 3
	global_load_dwordx4 v[96:99], v[12:13], off offset:32
	global_load_dwordx4 v[100:103], v[12:13], off offset:64
	global_load_dwordx4 v[104:107], v[2:3], off offset:768
	global_load_dwordx4 v[108:111], v[12:13], off offset:96
	v_lshl_add_u64 v[2:3], v[6:7], 1, s[14:15]
	v_ashrrev_i32_e32 v5, 31, v4
	s_ashr_i32 s1, s0, 31
	v_lshl_add_u64 v[2:3], v[2:3], 0, s[2:3]
	v_lshl_add_u64 v[8:9], v[4:5], 0, s[94:95]
	v_lshl_add_u64 v[2:3], s[0:1], 1, v[2:3]
	s_mov_b64 s[0:1], 0x1600
	v_lshl_add_u64 v[128:129], v[2:3], 0, s[0:1]
	v_mad_u64_u32 v[2:3], s[0:1], v8, s23, v[10:11]
	v_and_b32_e32 v1, 7, v0
	v_mad_i32_i24 v3, v9, s23, v3
	v_lshl_add_u64 v[2:3], v[2:3], 0, s[2:3]
	v_lshlrev_b32_e32 v144, 4, v1
	v_lshl_add_u64 v[2:3], v[2:3], 0, v[144:145]
	s_mov_b64 s[0:1], 0x1900
	s_or_b32 s9, s12, 1
	v_lshl_add_u64 v[130:131], v[2:3], 0, s[0:1]
	v_mad_u64_u32 v[2:3], s[0:1], s12, v158, v[128:129]
	v_mad_u64_u32 v[6:7], s[0:1], s12, v158, v[130:131]
	global_load_dwordx4 v[112:115], v[2:3], off
	global_load_dwordx4 v[116:119], v[6:7], off
	v_mad_u64_u32 v[2:3], s[0:1], s9, v158, v[128:129]
	v_mad_u64_u32 v[6:7], s[0:1], s9, v158, v[130:131]
	global_load_dwordx4 v[120:123], v[2:3], off
	global_load_dwordx4 v[124:127], v[6:7], off
	v_lshlrev_b32_e32 v1, 4, v134
	v_lshlrev_b32_e32 v2, 10, v0
	v_lshlrev_b32_e32 v135, 2, v132
	v_lshrrev_b32_e32 v7, 2, v0
	s_sub_i32 s0, s16, 27
	v_and_b32_e32 v2, 0x1000, v2
	v_lshlrev_b32_e32 v3, 4, v0
	v_lshlrev_b32_e32 v5, 1, v0
	v_lshlrev_b32_e32 v6, 3, v0
	v_and_or_b32 v7, v7, 3, v135
	v_lshl_or_b32 v136, s8, 10, v1
	v_lshlrev_b32_e32 v1, 4, v133
	v_cmp_eq_u32_e64 s[8:9], 0, v0
	v_add_u32_e32 v0, s0, v133
	v_and_b32_e32 v5, 32, v5
	v_and_b32_e32 v6, 24, v6
	v_lshlrev_b32_e32 v7, 6, v7
	v_lshl_or_b32 v139, v132, 10, v1
	v_lshl_add_u32 v1, v4, 6, v2
	v_sub_u32_e32 v0, v0, v135
	s_lshl_b32 s0, s12, 6
	v_mov_b32_e32 v138, 0
	s_lshl_b32 s13, s78, 6
	s_add_i32 s14, s10, -8
	v_or3_b32 v137, v5, v6, v7
	v_and_or_b32 v140, v3, 48, v1
	s_add_i32 s15, s10, -2
	v_subrev_u32_e32 v141, s0, v0
	s_lshl_b32 s16, s12, 13
	v_mov_b32_e32 v164, 0
	v_mov_b32_e32 v0, 0
	v_mov_b32_e32 v1, v138
	v_mov_b32_e32 v2, v138
	v_mov_b32_e32 v3, v138
	v_mov_b32_e32 v4, v138
	v_mov_b32_e32 v5, v138
	v_mov_b32_e32 v6, v138
	v_mov_b32_e32 v7, v138
	v_mov_b32_e32 v8, v138
	v_mov_b32_e32 v9, v138
	v_mov_b32_e32 v10, v138
	v_mov_b32_e32 v11, v138
	v_mov_b32_e32 v12, v138
	v_mov_b32_e32 v13, v138
	v_mov_b32_e32 v14, v138
	v_mov_b32_e32 v15, v138
	v_mov_b32_e32 v16, 0
	v_mov_b32_e32 v17, v138
	v_mov_b32_e32 v18, v138
	v_mov_b32_e32 v19, v138
	v_mov_b32_e32 v20, v138
	v_mov_b32_e32 v21, v138
	v_mov_b32_e32 v22, v138
	v_mov_b32_e32 v23, v138
	v_mov_b32_e32 v24, v138
	v_mov_b32_e32 v25, v138
	v_mov_b32_e32 v26, v138
	v_mov_b32_e32 v27, v138
	v_mov_b32_e32 v28, v138
	v_mov_b32_e32 v29, v138
	v_mov_b32_e32 v30, v138
	v_mov_b32_e32 v31, v138
	s_waitcnt lgkmcnt(0)
	s_barrier
	ds_read_b32 v214, v155
	v_mbcnt_lo_u32_b32 v231, -1, 0
	v_mbcnt_hi_u32_b32 v231, -1, v231
	v_lshl_add_u32 v231, v231, 2, v155
	s_waitcnt lgkmcnt(0)
	v_mov_b32_e32 v215, v214
	v_mov_b32_e32 v216, v214
	v_mov_b32_e32 v217, v214
	v_mov_b32_e32 v218, v214
	v_mov_b32_e32 v219, v214
	v_mov_b32_e32 v220, v214
	v_mov_b32_e32 v221, v214
	v_mov_b32_e32 v222, v214
	v_mov_b32_e32 v223, v214
	v_mov_b32_e32 v224, v214
	v_mov_b32_e32 v225, v214
	v_mov_b32_e32 v226, v214
	v_mov_b32_e32 v227, v214
	v_mov_b32_e32 v228, v214
	v_mov_b32_e32 v229, v214
	ds_write_b32 v231, v214 offset:4
	s_branch .LBB0_1312

; template <int TYPE> __device__ __forceinline__ void attn_unit(const AttnCtx& C, int b, int h, int qb, LAS unsigned char* lds, int tid_in, unsigned* counter) {
;     ...
;             if (active) {
;                 f32x16 p0, p1;
;                 const LAS unsigned char* kp = Kb + bo + hi * 1024 + r32 * 16;
; #pragma unroll
;                 for (int d0 = 0; d0 < 4; ++d0) {
;                     const bf16x8 a0 = *(const LAS bf16x8*)(kp + d0 * 2048), a1 = *(const LAS bf16x8*)(kp + d0 * 2048 + 512);
;                     if (d0 == 0) { p0 = MFMA32(a0, qr[0], (TYPE == 1 ? cvec : zvec)); p1 = MFMA32(a1, qr[0], (TYPE == 1 ? cvec : zvec)); }
;                     else { p0 = MFMA32(a0, qr[d0], p0); p1 = MFMA32(a1, qr[d0], p1); }
;                 }
;                 const int xi = sq - 64 * t - 4 * hi;
;                 if (TYPE == 0) {
;                     const float xf = (float)xi;
; #pragma unroll
;                     for (int r = 0; r < 16; ++r) { const float c = (float)((r & 3) + 8 * (r >> 2));
;                         p0[r] = fast_exp2(p0[r] - sl2 * fabsf(xf - c)); p1[r] = fast_exp2(p1[r] - sl2 * fabsf(xf - (c + 32.f))); }
;                 } else if (TYPE == 1) {
;                     const LAS float* fp = Fb + (t & 3) * 64 + 4 * hi;
; #pragma unroll
;                     for (int g = 0; g < 4; ++g) { const f32x4 fa = *(const LAS f32x4*)(fp + 8 * g), fb2 = *(const LAS f32x4*)(fp + 32 + 8 * g);
; #pragma unroll
;                         for (int i = 0; i < 4; i += 2) {
;                             const f32x2_t d0_ = (f32x2_t){p0[4 * g + i], p0[4 * g + i + 1]} - (f32x2_t){fa[i], fa[i + 1]}, d1_ = (f32x2_t){p1[4 * g + i], p1[4 * g + i + 1]} - (f32x2_t){fb2[i], fb2[i + 1]};
;                             p0[4 * g + i] = fast_exp2(d0_[0]); p0[4 * g + i + 1] = fast_exp2(d0_[1]); p1[4 * g + i] = fast_exp2(d1_[0]); p1[4 * g + i + 1] = fast_exp2(d1_[1]); } }
;                     if (t == cq) { const int qrel = 32 * (w & 1) + r32;
; #pragma unroll
;                         for (int r = 0; r < 16; ++r) { const int kv = crow(r, hi); if (kv > qrel) p0[r] = 0.f; if (kv + 32 > qrel) p1[r] = 0.f; } }
;                 } else {
;                     if (cq - t >= 3) { const float bc = relb[256];
; #pragma unroll
;                         for (int r = 0; r < 16; ++r) { p0[r] = fast_exp2(p0[r] + bc); p1[r] = fast_exp2(p1[r] + bc); }
;                     } else {
.LBB0_1320:
	s_cmp_lt_i32 s12, s14
	s_cselect_b64 s[0:1], -1, 0
	s_cmp_gt_i32 s12, s10
	s_cselect_b64 s[2:3], -1, 0
	s_or_b64 s[0:1], s[0:1], s[2:3]
	s_and_b64 vcc, exec, s[0:1]
	s_cbranch_vccnz .LBB0_1311
	s_cmp_lt_i32 s12, s15
	s_cbranch_scc1 .Lt2far_2
	v_add_u32_e32 v40, s17, v139
	ds_read_b128 v[32:35], v40
	ds_read_b128 v[36:39], v40 offset:512
	s_mov_b64 s[0:1], -1
	s_cmp_lt_i32 s12, s15
	s_waitcnt vmcnt(5) lgkmcnt(1)
	v_mfma_f32_32x32x16_bf16 v[80:95], v[32:35], v[104:107], 0
	s_waitcnt lgkmcnt(0)
	v_mfma_f32_32x32x16_bf16 v[64:79], v[36:39], v[104:107], 0
	ds_read_b128 v[32:35], v40 offset:2048
	ds_read_b128 v[36:39], v40 offset:2560
	s_waitcnt lgkmcnt(1)
	v_mfma_f32_32x32x16_bf16 v[80:95], v[32:35], v[96:99], v[80:95]
	s_waitcnt lgkmcnt(0)
	v_mfma_f32_32x32x16_bf16 v[64:79], v[36:39], v[96:99], v[64:79]
	ds_read_b128 v[32:35], v40 offset:4096
	ds_read_b128 v[36:39], v40 offset:4608
	s_waitcnt lgkmcnt(1)
	v_mfma_f32_32x32x16_bf16 v[80:95], v[32:35], v[100:103], v[80:95]
	ds_read_b128 v[32:35], v40 offset:6144
	ds_read_b128 v[146:149], v40 offset:6656
	s_waitcnt lgkmcnt(2)
	v_mfma_f32_32x32x16_bf16 v[64:79], v[36:39], v[100:103], v[64:79]
	s_waitcnt vmcnt(4) lgkmcnt(1)
	v_mfma_f32_32x32x16_bf16 v[80:95], v[32:35], v[108:111], v[80:95]
	s_waitcnt lgkmcnt(0)
	v_mfma_f32_32x32x16_bf16 v[64:79], v[146:149], v[108:111], v[64:79]
	s_cbranch_scc1 .LBB0_1323
	v_lshl_add_u32 v230, v141, 2, v162
	s_nop 3
	ds_read_b32 v33, v230 offset:236
	ds_read_b32 v40, v230 offset:108
	ds_read_b32 v35, v230 offset:232
	ds_read_b32 v34, v230 offset:104
	ds_read_b32 v37, v230 offset:228
	ds_read_b32 v36, v230 offset:100
	ds_read_b32 v39, v230 offset:224
	ds_read_b32 v38, v230 offset:96
	s_waitcnt lgkmcnt(7)
	v_add_f32_e32 v32, v80, v33
	s_waitcnt lgkmcnt(6)
	v_add_f32_e32 v33, v64, v40
	v_exp_f32_e32 v48, v33
	s_waitcnt lgkmcnt(5)
	v_add_f32_e32 v33, v81, v35
	s_waitcnt lgkmcnt(2)
	v_add_f32_e32 v35, v66, v36
	s_waitcnt lgkmcnt(0)
	v_add_f32_e32 v36, v67, v38
	v_add_f32_e32 v34, v65, v34
	v_exp_f32_e32 v51, v36
	v_exp_f32_e32 v49, v34
	v_add_f32_e32 v34, v82, v37
	v_exp_f32_e32 v50, v35
	v_add_f32_e32 v35, v83, v39
	ds_read_b32 v37, v230 offset:204
	ds_read_b32 v44, v230 offset:76
	ds_read_b32 v39, v230 offset:200
	ds_read_b32 v38, v230 offset:72
	ds_read_b32 v41, v230 offset:196
	ds_read_b32 v40, v230 offset:68
	ds_read_b32 v43, v230 offset:192
	ds_read_b32 v42, v230 offset:64
	s_waitcnt lgkmcnt(7)
	v_add_f32_e32 v36, v84, v37
	s_waitcnt lgkmcnt(6)
	v_add_f32_e32 v37, v68, v44
	v_exp_f32_e32 v52, v37
	s_waitcnt lgkmcnt(5)
	v_add_f32_e32 v37, v85, v39
	s_waitcnt lgkmcnt(2)
	v_add_f32_e32 v39, v70, v40
	s_waitcnt lgkmcnt(0)
	v_add_f32_e32 v40, v71, v42
	v_add_f32_e32 v38, v69, v38
	v_exp_f32_e32 v55, v40
	v_exp_f32_e32 v53, v38
	v_add_f32_e32 v38, v86, v41
	v_exp_f32_e32 v54, v39
	v_add_f32_e32 v39, v87, v43
	ds_read_b32 v41, v230 offset:172
	ds_read_b32 v56, v230 offset:44
	ds_read_b32 v43, v230 offset:168
	ds_read_b32 v42, v230 offset:40
	ds_read_b32 v45, v230 offset:164
	ds_read_b32 v44, v230 offset:36
	ds_read_b32 v47, v230 offset:160
	ds_read_b32 v46, v230 offset:32
	s_waitcnt lgkmcnt(7)
	v_add_f32_e32 v40, v88, v41
	s_waitcnt lgkmcnt(6)
	v_add_f32_e32 v41, v72, v56
	v_exp_f32_e32 v56, v41
	s_waitcnt lgkmcnt(5)
	v_add_f32_e32 v41, v89, v43
	s_waitcnt lgkmcnt(2)
	v_add_f32_e32 v43, v74, v44
	s_waitcnt lgkmcnt(0)
	v_add_f32_e32 v44, v75, v46
	v_add_f32_e32 v42, v73, v42
	v_exp_f32_e32 v59, v44
	v_exp_f32_e32 v57, v42
	v_add_f32_e32 v42, v90, v45
	v_exp_f32_e32 v58, v43
	v_add_f32_e32 v43, v91, v47
	ds_read_b32 v45, v230 offset:140
	ds_read_b32 v142, v230 offset:12
	ds_read_b32 v47, v230 offset:136
	ds_read_b32 v46, v230 offset:8
	ds_read_b32 v143, v230 offset:132
	ds_read_b32 v144, v230 offset:4
	ds_read_b32 v146, v230 offset:128
	ds_read_b32 v63, v230
	s_waitcnt lgkmcnt(7)
	v_add_f32_e32 v44, v92, v45
	s_waitcnt lgkmcnt(6)
	v_add_f32_e32 v45, v76, v142
	v_exp_f32_e32 v60, v45
	s_waitcnt lgkmcnt(5)
	v_add_f32_e32 v45, v93, v47
	s_waitcnt lgkmcnt(4)
	v_add_f32_e32 v46, v77, v46
	s_waitcnt lgkmcnt(2)
	v_add_f32_e32 v47, v78, v144
	v_exp_f32_e32 v61, v46
	v_add_f32_e32 v46, v94, v143
	v_exp_f32_e32 v62, v47
	s_waitcnt lgkmcnt(1)
	v_add_f32_e32 v47, v95, v146
	v_exp_f32_e32 v32, v32
	v_exp_f32_e32 v33, v33
	v_exp_f32_e32 v34, v34
	v_exp_f32_e32 v35, v35
	v_exp_f32_e32 v36, v36
	v_exp_f32_e32 v37, v37
	v_exp_f32_e32 v38, v38
	v_exp_f32_e32 v39, v39
	v_exp_f32_e32 v40, v40
	v_exp_f32_e32 v41, v41
	v_exp_f32_e32 v42, v42
	v_exp_f32_e32 v43, v43
	v_exp_f32_e32 v44, v44
	v_exp_f32_e32 v45, v45
	v_exp_f32_e32 v46, v46
	v_exp_f32_e32 v47, v47
	s_waitcnt lgkmcnt(0)
	v_add_f32_e32 v63, v79, v63
	s_mov_b64 s[0:1], 0

; #define LAS __attribute__((address_space(3)))
; __device__ __forceinline__ float fast_exp2(float x) { return __builtin_amdgcn_exp2f(x); }
; template <int TYPE> __device__ __forceinline__ void attn_unit(const AttnCtx& C, int b, int h, int qb, LAS unsigned char* lds, int tid_in, unsigned* counter) {
;     ...
;                 for (int d0 = 0; d0 < 4; ++d0) {
;                     const bf16x8 a0 = *(const LAS bf16x8*)(kp + d0 * 2048), a1 = *(const LAS bf16x8*)(kp + d0 * 2048 + 512);
;                     if (d0 == 0) { p0 = MFMA32(a0, qr[0], (TYPE == 1 ? cvec : zvec)); p1 = MFMA32(a1, qr[0], (TYPE == 1 ? cvec : zvec)); }
;                     else { p0 = MFMA32(a0, qr[d0], p0); p1 = MFMA32(a1, qr[d0], p1); }
;                 }
;                 const int xi = sq - 64 * t - 4 * hi;
;                 if (TYPE == 0) {
;                     const float xf = (float)xi;
; #pragma unroll
;                     for (int r = 0; r < 16; ++r) { const float c = (float)((r & 3) + 8 * (r >> 2));
;                         p0[r] = fast_exp2(p0[r] - sl2 * fabsf(xf - c)); p1[r] = fast_exp2(p1[r] - sl2 * fabsf(xf - (c + 32.f))); }
;                 } else if (TYPE == 1) {
;                     const LAS float* fp = Fb + (t & 3) * 64 + 4 * hi;
; #pragma unroll
;                     for (int g = 0; g < 4; ++g) { const f32x4 fa = *(const LAS f32x4*)(fp + 8 * g), fb2 = *(const LAS f32x4*)(fp + 32 + 8 * g);
; #pragma unroll
;                         for (int i = 0; i < 4; i += 2) {
;                             const f32x2_t d0_ = (f32x2_t){p0[4 * g + i], p0[4 * g + i + 1]} - (f32x2_t){fa[i], fa[i + 1]}, d1_ = (f32x2_t){p1[4 * g + i], p1[4 * g + i + 1]} - (f32x2_t){fb2[i], fb2[i + 1]};
;                             p0[4 * g + i] = fast_exp2(d0_[0]); p0[4 * g + i + 1] = fast_exp2(d0_[1]); p1[4 * g + i] = fast_exp2(d1_[0]); p1[4 * g + i + 1] = fast_exp2(d1_[1]); } }
;                     if (t == cq) { const int qrel = 32 * (w & 1) + r32;
; #pragma unroll
;                         for (int r = 0; r < 16; ++r) { const int kv = crow(r, hi); if (kv > qrel) p0[r] = 0.f; if (kv + 32 > qrel) p1[r] = 0.f; } }
;                 } else {
;                     if (cq - t >= 3) { const float bc = relb[256];
; #pragma unroll
;                         for (int r = 0; r < 16; ++r) { p0[r] = fast_exp2(p0[r] + bc); p1[r] = fast_exp2(p1[r] + bc); }
.Lt2far_2:
	v_add_u32_e32 v40, s17, v139
	ds_read_b128 v[32:35], v40
	ds_read_b128 v[36:39], v40 offset:512
	s_waitcnt vmcnt(5) lgkmcnt(1)
	v_mfma_f32_32x32x16_bf16 v[80:95], v[32:35], v[104:107], v[214:229]
	s_waitcnt lgkmcnt(0)
	v_mfma_f32_32x32x16_bf16 v[64:79], v[36:39], v[104:107], v[214:229]
	ds_read_b128 v[32:35], v40 offset:2048
	ds_read_b128 v[36:39], v40 offset:2560
	s_waitcnt lgkmcnt(1)
	v_mfma_f32_32x32x16_bf16 v[80:95], v[32:35], v[96:99], v[80:95]
	s_waitcnt lgkmcnt(0)
	v_mfma_f32_32x32x16_bf16 v[64:79], v[36:39], v[96:99], v[64:79]
	ds_read_b128 v[32:35], v40 offset:4096
	ds_read_b128 v[36:39], v40 offset:4608
	s_waitcnt lgkmcnt(1)
	v_mfma_f32_32x32x16_bf16 v[80:95], v[32:35], v[100:103], v[80:95]
	ds_read_b128 v[32:35], v40 offset:6144
	ds_read_b128 v[146:149], v40 offset:6656
	s_waitcnt lgkmcnt(2)
	v_mfma_f32_32x32x16_bf16 v[64:79], v[36:39], v[100:103], v[64:79]
	s_waitcnt vmcnt(4) lgkmcnt(1)
	v_mfma_f32_32x32x16_bf16 v[80:95], v[32:35], v[108:111], v[80:95]
	s_waitcnt lgkmcnt(0)
	v_mfma_f32_32x32x16_bf16 v[64:79], v[146:149], v[108:111], v[64:79]
	s_nop 11
	v_exp_f32_e32 v48, v64
	v_exp_f32_e32 v33, v81
	v_exp_f32_e32 v49, v65
	v_exp_f32_e32 v50, v66
	v_exp_f32_e32 v51, v67
	v_exp_f32_e32 v52, v68
	v_exp_f32_e32 v53, v69
	v_exp_f32_e32 v54, v70
	v_exp_f32_e32 v55, v71
	v_exp_f32_e32 v56, v72
	v_exp_f32_e32 v57, v73
	v_exp_f32_e32 v58, v74
	v_exp_f32_e32 v59, v75
	v_exp_f32_e32 v60, v76
	v_exp_f32_e32 v61, v77
	v_exp_f32_e32 v62, v78
	v_exp_f32_e32 v32, v80
	v_exp_f32_e32 v34, v82
	v_exp_f32_e32 v35, v83
	v_exp_f32_e32 v36, v84
	v_exp_f32_e32 v37, v85
	v_exp_f32_e32 v38, v86
	v_exp_f32_e32 v39, v87
	v_exp_f32_e32 v40, v88
	v_exp_f32_e32 v41, v89
	v_exp_f32_e32 v42, v90
	v_exp_f32_e32 v43, v91
	v_exp_f32_e32 v44, v92
	v_exp_f32_e32 v45, v93
	v_exp_f32_e32 v46, v94
	v_exp_f32_e32 v47, v95
	v_mov_b32_e32 v63, v79
	s_branch .LBB0_1310

; __device__ __forceinline__ float row_rstd(const u64_t* rsq, int row) { return fast_rsq(rsq_sum(rsq, row) * (1.0f / DM) + EPS); }
;     __device__ __forceinline__ void run(const f32x4 (&acc)[2][2][4][2], const Unit& u, const Unit& nxt, bool has_next, int ui, int wr, int wc, int fr_in, int fq_in) const {
;         int fr = fr_in, fq = fq_in; asm volatile("" : "+v"(fr), "+v"(fq));
;         const int tid = (wr * 4 + wc) * 64 + fq * 16 + fr;
;         const int slot = ui & 1;
;         if (ui == 0) {
;             prm[slot * 1024 + tid] = ldp(tid, u.pn); prm[slot * 1024 + tid + 512] = ldp(tid + 512, u.pn);
;             if (tid < 256) rsd[slot * 256 + tid] = row_rstd(rsq, u.pm * BM + tid);
.LBB0_1555:
	v_bfe_u32 v73, v226, 7, 2
	v_ashrrev_i32_e32 v72, 9, v226
	v_and_b32_e32 v74, 0x7f, v226
	v_mul_u32_u24_e32 v75, 0x1600, v73
	v_cmp_eq_u32_e64 s[6:7], 3, v73
	v_add_u32_e32 v102, 0x200, v226
	v_mul_i32_i24_e32 v72, 0xb00, v72
	v_cndmask_b32_e64 v100, v75, 0, s[6:7]
	v_lshl_or_b32 v101, s40, 7, v74
	v_mov_b32_e32 v73, s53
	v_mov_b32_e32 v74, s55
	v_ashrrev_i32_e32 v102, 9, v102
	v_add3_u32 v72, v101, v72, v100
	v_cndmask_b32_e64 v75, v73, v74, s[6:7]
	v_mov_b32_e32 v73, s52
	v_mov_b32_e32 v74, s54
	v_mul_i32_i24_e32 v102, 0xb00, v102
	v_cndmask_b32_e64 v74, v73, v74, s[6:7]
	v_ashrrev_i32_e32 v73, 31, v72
	v_add3_u32 v100, v102, v101, v100
	v_lshl_add_u64 v[72:73], v[72:73], 2, v[74:75]
	v_ashrrev_i32_e32 v101, 31, v100
	v_lshl_add_u64 v[74:75], v[100:101], 2, v[74:75]
	global_load_dword v72, v[72:73], off
	s_nop 0
	global_load_dword v73, v[74:75], off
	v_lshl_add_u32 v74, v226, 2, v224
	s_waitcnt vmcnt(0)
	v_mul_f32_e32 v72, 0xbfb8aa3b, v72
	v_mul_f32_e32 v73, 0xbf317218, v73
	ds_write2st64_b32 v74, v72, v73 offset1:8
	s_and_saveexec_b64 s[0:1], vcc
	s_cbranch_execz .LBB0_1557
	v_lshl_add_u32 v72, s38, 8, v226
	v_ashrrev_i32_e32 v73, 31, v72
	v_lshl_add_u64 v[72:73], v[72:73], 3, s[18:19]
	global_load_dwordx2 v[72:73], v[72:73], off
	s_waitcnt vmcnt(0)
	v_ffbh_u32_e32 v74, v73
	v_min_u32_e32 v74, 32, v74
	v_lshlrev_b64 v[72:73], v74, v[72:73]
	v_min_u32_e32 v72, 1, v72
	v_or_b32_e32 v72, v73, v72
	v_cvt_f32_u32_e32 v72, v72
	v_sub_u32_e32 v73, 32, v74
	v_ldexp_f32 v72, v72, v73
	v_mul_f32_e32 v72, 0x33800000, v72
	v_fmamk_f32 v72, v72, 0x3a800000, v223
	v_rsq_f32_e32 v72, v72
	v_lshl_add_u32 v73, v226, 2, v225
	ds_write_b32 v73, v72

; __device__ __forceinline__ unsigned pk2(float lo, float hi) { f32x2_t v = {lo, hi}; bf16x2_t b = __builtin_convertvector(v, bf16x2_t); return __builtin_bit_cast(unsigned, b); }
; #define DPPF(v, ctrl) __builtin_bit_cast(float, __builtin_amdgcn_update_dpp(0, __builtin_bit_cast(int, (v)), (ctrl), 0xf, 0xf, false))
; __device__ __forceinline__ float sigmoidf_(float v) { return fast_rcp(1.0f + fast_exp2(-v * LOG2E)); }
; #define PG8_LAS __attribute__((address_space(3)))
;     __device__ __forceinline__ void run(const f32x4 (&acc)[2][2][4][2], const Unit& u, const Unit& nxt, bool has_next, int ui, int wr, int wc, int fr_in, int fq_in) const {
;     ...
;                 if (grp > 0 && fr == 0) { const PG8_LAS float* xp = xr + ((grp - 1) * 2) * 256 + cl;
;                     hg2 = *(const PG8_LAS f32x4*)(xp); hg3 = *(const PG8_LAS f32x4*)(xp + 256); hv2 = *(const PG8_LAS f32x4*)(xp + 128); hv3 = *(const PG8_LAS f32x4*)(xp + 256 + 128); }
;                 f32x4 pg2, pg1, pv2, pv1;
;                 {
;                     const f32x4 g2 = acc[ai][0][2][n] * rs[ai][2], g3 = acc[ai][0][3][n] * rs[ai][3], v2 = acc[ai][1][2][n] * rs[ai][2], v3 = acc[ai][1][3][n] * rs[ai][3];
; #pragma unroll
;                     for (int i = 0; i < 4; ++i) {
;                         float a0 = g2[i], a1 = g3[i], a2 = v2[i], a3 = v3[i];
;                         asm volatile("" : "+v"(a0), "+v"(a1), "+v"(a2), "+v"(a3));
;                         const float t0 = DPPF(a0, 0x111), t1 = DPPF(a1, 0x111), t2 = DPPF(a2, 0x111), t3 = DPPF(a3, 0x111);
;                         pg2[i] = t0 + hg2[i]; pg1[i] = t1 + hg3[i]; pv2[i] = t2 + hv2[i]; pv1[i] = t3 + hv3[i]; }
;                 }
; #pragma unroll
;                 for (int m = 0; m < 4; ++m) {
;                     const f32x4 gc = acc[ai][0][m][n] * rs[ai][m], vc = acc[ai][1][m][n] * rs[ai][m];
;                     const f32x4 cgt = bg + wg0 * pg2 + wg1 * pg1 + wg2 * gc, cvl = bv + wv0 * pv2 + wv1 * pv1 + wv2 * vc;
;                     float a[4];
; #pragma unroll
;                     for (int i = 0; i < 4; ++i) a[i] = cgt[i] * sigmoidf_(cgt[i]) * cvl[i];
;                     u32x2 w; w.x = pk2(a[0], a[1]); w.y = pk2(a[2], a[3]);
;                     *(u32x2*)(A + (size_t)(u.pm * BM + ai * 128 + wr * 64 + 4 * fr + m) * DFF + ch) = w;
;                     pg2 = pg1; pg1 = gc; pv2 = pv1; pv1 = vc;
.LBB0_1581:
	s_or_b64 exec, exec, s[0:1]
	s_lshl_b32 s0, s38, 8
	s_add_i32 s0, s0, s58
	v_lshl_add_u32 v231, v169, 2, s0
	v_mul_f32_e32 v169, v116, v102
	v_mul_f32_e32 v235, v108, v103
	v_mul_f32_e32 v237, v112, v102
	v_mul_f32_e32 v239, v104, v103
	v_mov_b32_dpp v234, v169 row_shr:1 row_mask:0xf bank_mask:0xf bound_ctrl:1
	s_nop 0
	v_mov_b32_dpp v240, v239 row_shr:1 row_mask:0xf bank_mask:0xf bound_ctrl:1
	v_mul_f32_e32 v169, v117, v102
	v_mul_f32_e32 v239, v109, v103
	v_mul_f32_e32 v241, v113, v102
	v_mul_f32_e32 v242, v105, v103
	v_mov_b32_dpp v236, v235 row_shr:1 row_mask:0xf bank_mask:0xf bound_ctrl:1
	v_mov_b32_dpp v238, v237 row_shr:1 row_mask:0xf bank_mask:0xf bound_ctrl:1
	v_mul_f32_e32 v243, v110, v103
	v_mov_b32_dpp v235, v169 row_shr:1 row_mask:0xf bank_mask:0xf bound_ctrl:1
	v_mov_b32_dpp v237, v239 row_shr:1 row_mask:0xf bank_mask:0xf bound_ctrl:1
	v_mul_f32_e32 v169, v118, v102
	v_mul_f32_e32 v245, v114, v102
	v_mov_b32_dpp v239, v241 row_shr:1 row_mask:0xf bank_mask:0xf bound_ctrl:1
	v_mul_f32_e32 v247, v106, v103
	s_waitcnt lgkmcnt(0)
	v_pk_add_f32 v[182:183], v[182:183], v[234:235]
	v_mov_b32_dpp v241, v242 row_shr:1 row_mask:0xf bank_mask:0xf bound_ctrl:1
	v_pk_add_f32 v[178:179], v[178:179], v[236:237]
	v_pk_fma_f32 v[182:183], v[152:153], v[182:183], v[164:165]
	v_mov_b32_dpp v242, v169 row_shr:1 row_mask:0xf bank_mask:0xf bound_ctrl:1
	v_mov_b32_dpp v248, v247 row_shr:1 row_mask:0xf bank_mask:0xf bound_ctrl:1
	v_mul_f32_e32 v169, v119, v102
	v_mul_f32_e32 v247, v111, v103
	v_mul_f32_e32 v249, v115, v102
	v_mul_f32_e32 v250, v107, v103
	v_pk_mul_f32 v[132:133], v[132:133], v[100:101] op_sel_hi:[1,0]
	v_pk_fma_f32 v[182:183], v[156:157], v[178:179], v[182:183]
	v_mov_b32_dpp v244, v243 row_shr:1 row_mask:0xf bank_mask:0xf bound_ctrl:1
	v_pk_fma_f32 v[182:183], v[132:133], v[160:161], v[182:183]
	v_mov_b32_dpp v243, v169 row_shr:1 row_mask:0xf bank_mask:0xf bound_ctrl:1
	v_exp_f32_e32 v169, v182
	v_exp_f32_e32 v235, v183
	v_mov_b32_dpp v246, v245 row_shr:1 row_mask:0xf bank_mask:0xf bound_ctrl:1
	v_add_f32_e32 v169, 1.0, v169
	v_rcp_f32_e32 v234, v169
	v_add_f32_e32 v169, 1.0, v235
	v_rcp_f32_e32 v235, v169
	v_pk_mul_f32 v[236:237], v[128:129], v[100:101] op_sel_hi:[1,0]
	v_pk_add_f32 v[128:129], v[174:175], v[238:239]
	v_mov_b32_dpp v245, v247 row_shr:1 row_mask:0xf bank_mask:0xf bound_ctrl:1
	v_pk_mul_f32 v[174:175], v[182:183], v[234:235]
	v_pk_add_f32 v[182:183], v[184:185], v[242:243]
	v_pk_add_f32 v[180:181], v[180:181], v[244:245]
	v_pk_fma_f32 v[182:183], v[154:155], v[182:183], v[166:167]
	v_pk_mul_f32 v[134:135], v[134:135], v[100:101] op_sel_hi:[1,0]
	v_pk_fma_f32 v[182:183], v[158:159], v[180:181], v[182:183]
	v_pk_add_f32 v[170:171], v[170:171], v[240:241]
	v_pk_fma_f32 v[182:183], v[134:135], v[162:163], v[182:183]
	v_pk_fma_f32 v[128:129], v[136:137], v[128:129], v[148:149]
	v_exp_f32_e32 v169, v182
	v_exp_f32_e32 v185, v183
	v_add_f32_e32 v169, 1.0, v169
	v_pk_fma_f32 v[128:129], v[140:141], v[170:171], v[128:129]
	v_rcp_f32_e32 v184, v169
	v_add_f32_e32 v169, 1.0, v185
	v_mov_b32_dpp v247, v249 row_shr:1 row_mask:0xf bank_mask:0xf bound_ctrl:1
	v_pk_fma_f32 v[128:129], v[236:237], v[144:145], v[128:129]
	v_rcp_f32_e32 v185, v169
	v_mov_b32_dpp v249, v250 row_shr:1 row_mask:0xf bank_mask:0xf bound_ctrl:1
	v_pk_mul_f32 v[128:129], v[128:129], v[174:175]
	v_pk_add_f32 v[174:175], v[176:177], v[246:247]
	v_pk_add_f32 v[172:173], v[172:173], v[248:249]
	v_pk_fma_f32 v[174:175], v[138:139], v[174:175], v[150:151]
	s_lshl_b32 s12, s40, 7
	v_pk_mul_f32 v[130:131], v[130:131], v[100:101] op_sel_hi:[1,0]
	v_pk_fma_f32 v[174:175], v[142:143], v[172:173], v[174:175]
	v_add_u32_e32 v232, s12, v202
	v_pk_mul_f32 v[176:177], v[182:183], v[184:185]
	v_pk_fma_f32 v[174:175], v[130:131], v[146:147], v[174:175]
	v_ashrrev_i32_e32 v233, 31, v232
	v_pk_mul_f32 v[174:175], v[174:175], v[176:177]
	v_pk_fma_f32 v[178:179], v[152:153], v[178:179], v[164:165]
	v_cvt_pk_bf16_f32 v177, v174, v175
	v_lshlrev_b64 v[174:175], 1, v[232:233]
	v_mov_b32_e32 v232, v101
	v_pk_mul_f32 v[124:125], v[124:125], v[232:233] op_sel_hi:[1,0]
	v_pk_fma_f32 v[178:179], v[132:133], v[156:157], v[178:179]
	v_mov_b64_e32 v[182:183], s[16:17]
	v_pk_fma_f32 v[178:179], v[124:125], v[160:161], v[178:179]
	v_cvt_pk_bf16_f32 v176, v128, v129
	v_exp_f32_e32 v169, v178
	v_exp_f32_e32 v233, v179
	v_mad_i64_i32 v[128:129], s[0:1], v231, s73, v[182:183]
	v_lshl_add_u64 v[184:185], v[128:129], 0, v[174:175]
	v_add_f32_e32 v169, 1.0, v169
	global_store_dwordx2 v[184:185], v[176:177], off
	v_rcp_f32_e32 v176, v169
	v_add_f32_e32 v169, 1.0, v233
	v_rcp_f32_e32 v177, v169
	v_pk_mul_f32 v[184:185], v[126:127], v[232:233] op_sel_hi:[1,0]
	v_pk_fma_f32 v[132:133], v[132:133], v[152:153], v[164:165]
	v_pk_fma_f32 v[170:171], v[136:137], v[170:171], v[148:149]
	v_pk_mul_f32 v[126:127], v[178:179], v[176:177]
	v_pk_fma_f32 v[176:177], v[154:155], v[180:181], v[166:167]
	v_pk_mul_f32 v[116:117], v[116:117], v[102:103] op_sel_hi:[1,0]
	v_pk_fma_f32 v[176:177], v[134:135], v[158:159], v[176:177]
	v_pk_fma_f32 v[132:133], v[124:125], v[156:157], v[132:133]
	v_pk_fma_f32 v[176:177], v[184:185], v[162:163], v[176:177]
	v_pk_mul_f32 v[120:121], v[120:121], v[232:233] op_sel_hi:[1,0]
	v_exp_f32_e32 v169, v176
	v_exp_f32_e32 v179, v177
	v_pk_fma_f32 v[170:171], v[236:237], v[140:141], v[170:171]
	v_add_f32_e32 v169, 1.0, v169
	v_rcp_f32_e32 v178, v169
	v_add_f32_e32 v169, 1.0, v179
	v_rcp_f32_e32 v179, v169
	v_pk_fma_f32 v[132:133], v[116:117], v[160:161], v[132:133]
	v_pk_fma_f32 v[170:171], v[120:121], v[144:145], v[170:171]
	v_pk_fma_f32 v[172:173], v[138:139], v[172:173], v[150:151]
; __device__ __forceinline__ unsigned pk2(float lo, float hi) { f32x2_t v = {lo, hi}; bf16x2_t b = __builtin_convertvector(v, bf16x2_t); return __builtin_bit_cast(unsigned, b); }
; #define DPPF(v, ctrl) __builtin_bit_cast(float, __builtin_amdgcn_update_dpp(0, __builtin_bit_cast(int, (v)), (ctrl), 0xf, 0xf, false))
; __device__ __forceinline__ float sigmoidf_(float v) { return fast_rcp(1.0f + fast_exp2(-v * LOG2E)); }
; #define PG8_LAS __attribute__((address_space(3)))
;     __device__ __forceinline__ void run(const f32x4 (&acc)[2][2][4][2], const Unit& u, const Unit& nxt, bool has_next, int ui, int wr, int wc, int fr_in, int fq_in) const {
;     ...
;                 if (grp > 0 && fr == 0) { const PG8_LAS float* xp = xr + ((grp - 1) * 2) * 256 + cl;
;                     hg2 = *(const PG8_LAS f32x4*)(xp); hg3 = *(const PG8_LAS f32x4*)(xp + 256); hv2 = *(const PG8_LAS f32x4*)(xp + 128); hv3 = *(const PG8_LAS f32x4*)(xp + 256 + 128); }
;                 f32x4 pg2, pg1, pv2, pv1;
;                 {
;                     const f32x4 g2 = acc[ai][0][2][n] * rs[ai][2], g3 = acc[ai][0][3][n] * rs[ai][3], v2 = acc[ai][1][2][n] * rs[ai][2], v3 = acc[ai][1][3][n] * rs[ai][3];
; #pragma unroll
;                     for (int i = 0; i < 4; ++i) {
;                         float a0 = g2[i], a1 = g3[i], a2 = v2[i], a3 = v3[i];
;                         asm volatile("" : "+v"(a0), "+v"(a1), "+v"(a2), "+v"(a3));
;                         const float t0 = DPPF(a0, 0x111), t1 = DPPF(a1, 0x111), t2 = DPPF(a2, 0x111), t3 = DPPF(a3, 0x111);
;                         pg2[i] = t0 + hg2[i]; pg1[i] = t1 + hg3[i]; pv2[i] = t2 + hv2[i]; pv1[i] = t3 + hv3[i]; }
;                 }
; #pragma unroll
;                 for (int m = 0; m < 4; ++m) {
;                     const f32x4 gc = acc[ai][0][m][n] * rs[ai][m], vc = acc[ai][1][m][n] * rs[ai][m];
;                     const f32x4 cgt = bg + wg0 * pg2 + wg1 * pg1 + wg2 * gc, cvl = bv + wv0 * pv2 + wv1 * pv1 + wv2 * vc;
;                     float a[4];
; #pragma unroll
;                     for (int i = 0; i < 4; ++i) a[i] = cgt[i] * sigmoidf_(cgt[i]) * cvl[i];
;                     u32x2 w; w.x = pk2(a[0], a[1]); w.y = pk2(a[2], a[3]);
;                     *(u32x2*)(A + (size_t)(u.pm * BM + ai * 128 + wr * 64 + 4 * fr + m) * DFF + ch) = w;
;                     pg2 = pg1; pg1 = gc; pv2 = pv1; pv1 = vc;
;                 }
	v_pk_mul_f32 v[122:123], v[122:123], v[232:233] op_sel_hi:[1,0]
	v_pk_mul_f32 v[126:127], v[170:171], v[126:127]
	v_pk_mul_f32 v[170:171], v[176:177], v[178:179]
	v_pk_fma_f32 v[172:173], v[130:131], v[142:143], v[172:173]
	v_exp_f32_e32 v169, v132
	v_pk_fma_f32 v[172:173], v[122:123], v[146:147], v[172:173]
	v_exp_f32_e32 v176, v133
	v_pk_mul_f32 v[170:171], v[172:173], v[170:171]
	v_cvt_pk_bf16_f32 v172, v126, v127
	v_or_b32_e32 v126, 1, v231
	v_mad_i64_i32 v[126:127], s[0:1], v126, s73, v[182:183]
	v_cvt_pk_bf16_f32 v173, v170, v171
	v_lshl_add_u64 v[170:171], v[126:127], 0, v[174:175]
	v_add_f32_e32 v169, 1.0, v169
	global_store_dwordx2 v[170:171], v[172:173], off
	v_rcp_f32_e32 v170, v169
	v_add_f32_e32 v169, 1.0, v176
	v_rcp_f32_e32 v171, v169
	v_pk_fma_f32 v[134:135], v[134:135], v[154:155], v[166:167]
	v_pk_mul_f32 v[118:119], v[118:119], v[102:103] op_sel_hi:[1,0]
	v_pk_fma_f32 v[134:135], v[184:185], v[158:159], v[134:135]
	v_pk_mul_f32 v[132:133], v[132:133], v[170:171]
	v_pk_fma_f32 v[134:135], v[118:119], v[162:163], v[134:135]
	v_pk_mul_f32 v[112:113], v[112:113], v[102:103] op_sel_hi:[1,0]
	v_exp_f32_e32 v173, v135
	v_pk_fma_f32 v[170:171], v[236:237], v[136:137], v[148:149]
	v_pk_fma_f32 v[124:125], v[124:125], v[152:153], v[164:165]
	v_pk_fma_f32 v[170:171], v[120:121], v[140:141], v[170:171]
	v_pk_fma_f32 v[116:117], v[116:117], v[156:157], v[124:125]
	v_pk_fma_f32 v[170:171], v[112:113], v[144:145], v[170:171]
	v_pk_mul_f32 v[132:133], v[170:171], v[132:133]
	v_mov_b32_e32 v170, v103
	v_pk_mul_f32 v[108:109], v[108:109], v[170:171] op_sel_hi:[1,0]
	v_pk_mul_f32 v[110:111], v[110:111], v[170:171] op_sel_hi:[1,0]
	v_pk_fma_f32 v[108:109], v[108:109], v[160:161], v[116:117]
	v_exp_f32_e32 v169, v134
	v_exp_f32_e32 v116, v108
	v_exp_f32_e32 v117, v109
	v_add_f32_e32 v169, 1.0, v169
	v_rcp_f32_e32 v172, v169
	v_add_f32_e32 v116, 1.0, v116
	v_add_f32_e32 v117, 1.0, v117
	v_rcp_f32_e32 v116, v116
	v_rcp_f32_e32 v117, v117
	v_add_f32_e32 v169, 1.0, v173
	v_rcp_f32_e32 v173, v169
	v_pk_mul_f32 v[104:105], v[104:105], v[170:171] op_sel_hi:[1,0]
	v_pk_mul_f32 v[108:109], v[108:109], v[116:117]
	v_pk_fma_f32 v[116:117], v[184:185], v[154:155], v[166:167]
	v_pk_mul_f32 v[114:115], v[114:115], v[102:103] op_sel_hi:[1,0]
	v_pk_fma_f32 v[116:117], v[118:119], v[158:159], v[116:117]
	v_pk_fma_f32 v[130:131], v[130:131], v[138:139], v[150:151]
	v_pk_fma_f32 v[110:111], v[110:111], v[162:163], v[116:117]
	v_pk_fma_f32 v[130:131], v[122:123], v[142:143], v[130:131]
	v_exp_f32_e32 v118, v110
	v_exp_f32_e32 v119, v111
	v_pk_fma_f32 v[116:117], v[120:121], v[136:137], v[148:149]
	v_add_f32_e32 v118, 1.0, v118
	v_rcp_f32_e32 v118, v118
	v_add_f32_e32 v119, 1.0, v119
	v_rcp_f32_e32 v119, v119
	v_pk_fma_f32 v[112:113], v[112:113], v[140:141], v[116:117]
	v_pk_mul_f32 v[106:107], v[106:107], v[170:171] op_sel_hi:[1,0]
	v_pk_fma_f32 v[104:105], v[104:105], v[144:145], v[112:113]
	v_pk_mul_f32 v[134:135], v[134:135], v[172:173]
	v_pk_mul_f32 v[104:105], v[104:105], v[108:109]
	v_pk_mul_f32 v[108:109], v[110:111], v[118:119]
	v_pk_fma_f32 v[110:111], v[122:123], v[138:139], v[150:151]
	v_pk_fma_f32 v[130:131], v[114:115], v[146:147], v[130:131]
	v_pk_fma_f32 v[110:111], v[114:115], v[142:143], v[110:111]
	v_pk_mul_f32 v[130:131], v[130:131], v[134:135]
	v_pk_fma_f32 v[106:107], v[106:107], v[146:147], v[110:111]
	v_cvt_pk_bf16_f32 v135, v130, v131
	v_pk_mul_f32 v[106:107], v[106:107], v[108:109]
	v_or_b32_e32 v130, 2, v231
	v_cvt_pk_bf16_f32 v104, v104, v105
	v_cvt_pk_bf16_f32 v105, v106, v107
	v_or_b32_e32 v106, 3, v231
	v_cvt_pk_bf16_f32 v134, v132, v133
	v_mad_i64_i32 v[132:133], s[0:1], v130, s73, v[182:183]
	v_mad_i64_i32 v[172:173], s[0:1], v106, s73, v[182:183]
	v_lshl_add_u64 v[130:131], v[132:133], 0, v[174:175]
	v_lshl_add_u64 v[106:107], v[172:173], 0, v[174:175]
	global_store_dwordx2 v[130:131], v[134:135], off
	global_store_dwordx2 v[106:107], v[104:105], off
	s_and_b64 s[10:11], s[26:27], s[10:11]
	v_mov_b32_e32 v169, 0
	v_mov_b32_e32 v170, 0
	v_mov_b32_e32 v171, 0
	v_mov_b32_e32 v104, 0
	v_mov_b32_e32 v105, 0
	v_mov_b32_e32 v106, 0
	v_mov_b32_e32 v107, 0
	v_mov_b32_e32 v108, 0
	v_mov_b32_e32 v109, 0
	v_mov_b32_e32 v110, 0
	v_mov_b32_e32 v111, 0
	v_mov_b32_e32 v112, 0
	v_mov_b32_e32 v113, 0
	v_mov_b32_e32 v114, 0
	v_mov_b32_e32 v115, 0
	s_and_saveexec_b64 s[0:1], s[10:11]
	s_cbranch_execz .LBB0_1583
	ds_read_b128 v[112:115], v230 offset:2048
	ds_read_b128 v[104:107], v230 offset:2560
	ds_read_b128 v[108:111], v230 offset:3072
	ds_read_b128 v[168:171], v230 offset:3584
; __device__ __forceinline__ unsigned pk2(float lo, float hi) { f32x2_t v = {lo, hi}; bf16x2_t b = __builtin_convertvector(v, bf16x2_t); return __builtin_bit_cast(unsigned, b); }
; #define DPPF(v, ctrl) __builtin_bit_cast(float, __builtin_amdgcn_update_dpp(0, __builtin_bit_cast(int, (v)), (ctrl), 0xf, 0xf, false))
; __device__ __forceinline__ float sigmoidf_(float v) { return fast_rcp(1.0f + fast_exp2(-v * LOG2E)); }
; #define PG8_LAS __attribute__((address_space(3)))
;     __device__ __forceinline__ void run(const f32x4 (&acc)[2][2][4][2], const Unit& u, const Unit& nxt, bool has_next, int ui, int wr, int wc, int fr_in, int fq_in) const {
;     ...
;                 if (grp > 0 && fr == 0) { const PG8_LAS float* xp = xr + ((grp - 1) * 2) * 256 + cl;
;                     hg2 = *(const PG8_LAS f32x4*)(xp); hg3 = *(const PG8_LAS f32x4*)(xp + 256); hv2 = *(const PG8_LAS f32x4*)(xp + 128); hv3 = *(const PG8_LAS f32x4*)(xp + 256 + 128); }
;                 f32x4 pg2, pg1, pv2, pv1;
;                 {
;                     const f32x4 g2 = acc[ai][0][2][n] * rs[ai][2], g3 = acc[ai][0][3][n] * rs[ai][3], v2 = acc[ai][1][2][n] * rs[ai][2], v3 = acc[ai][1][3][n] * rs[ai][3];
; #pragma unroll
;                     for (int i = 0; i < 4; ++i) {
;                         float a0 = g2[i], a1 = g3[i], a2 = v2[i], a3 = v3[i];
;                         asm volatile("" : "+v"(a0), "+v"(a1), "+v"(a2), "+v"(a3));
;                         const float t0 = DPPF(a0, 0x111), t1 = DPPF(a1, 0x111), t2 = DPPF(a2, 0x111), t3 = DPPF(a3, 0x111);
;                         pg2[i] = t0 + hg2[i]; pg1[i] = t1 + hg3[i]; pv2[i] = t2 + hv2[i]; pv1[i] = t3 + hv3[i]; }
;                 }
; #pragma unroll
;                 for (int m = 0; m < 4; ++m) {
;                     const f32x4 gc = acc[ai][0][m][n] * rs[ai][m], vc = acc[ai][1][m][n] * rs[ai][m];
;                     const f32x4 cgt = bg + wg0 * pg2 + wg1 * pg1 + wg2 * gc, cvl = bv + wv0 * pv2 + wv1 * pv1 + wv2 * vc;
;                     float a[4];
; #pragma unroll
;                     for (int i = 0; i < 4; ++i) a[i] = cgt[i] * sigmoidf_(cgt[i]) * cvl[i];
;                     u32x2 w; w.x = pk2(a[0], a[1]); w.y = pk2(a[2], a[3]);
;                     *(u32x2*)(A + (size_t)(u.pm * BM + ai * 128 + wr * 64 + 4 * fr + m) * DFF + ch) = w;
;                     pg2 = pg1; pg1 = gc; pv2 = pv1; pv1 = vc;
.LBB0_1583:
	s_or_b64 exec, exec, s[0:1]
	v_mul_f32_e32 v117, v80, v74
	v_mul_f32_e32 v119, v68, v75
	v_mul_f32_e32 v121, v76, v74
	v_mul_f32_e32 v123, v64, v75
	v_mov_b32_dpp v118, v119 row_shr:1 row_mask:0xf bank_mask:0xf bound_ctrl:1
	v_mov_b32_dpp v120, v121 row_shr:1 row_mask:0xf bank_mask:0xf bound_ctrl:1
	v_mov_b32_dpp v122, v123 row_shr:1 row_mask:0xf bank_mask:0xf bound_ctrl:1
	v_mul_f32_e32 v119, v81, v74
	v_mul_f32_e32 v121, v69, v75
	v_mul_f32_e32 v123, v77, v74
	v_mul_f32_e32 v124, v65, v75
	v_mov_b32_dpp v116, v117 row_shr:1 row_mask:0xf bank_mask:0xf bound_ctrl:1
	v_pk_mul_f32 v[96:97], v[96:97], v[72:73] op_sel_hi:[1,0]
	v_mul_f32_e32 v125, v82, v74
	v_mov_b32_dpp v117, v119 row_shr:1 row_mask:0xf bank_mask:0xf bound_ctrl:1
	s_waitcnt lgkmcnt(0)
	v_pk_add_f32 v[112:113], v[112:113], v[116:117]
	v_mul_f32_e32 v131, v70, v75
	v_mov_b32_dpp v119, v121 row_shr:1 row_mask:0xf bank_mask:0xf bound_ctrl:1
	v_pk_add_f32 v[108:109], v[108:109], v[118:119]
	v_pk_fma_f32 v[112:113], v[152:153], v[112:113], v[164:165]
	v_pk_fma_f32 v[112:113], v[156:157], v[108:109], v[112:113]
	v_mul_f32_e32 v135, v78, v74
	v_pk_fma_f32 v[112:113], v[96:97], v[160:161], v[112:113]
	v_mul_f32_e32 v177, v66, v75
	v_exp_f32_e32 v116, v112
	v_exp_f32_e32 v117, v113
	v_mov_b32_dpp v121, v123 row_shr:1 row_mask:0xf bank_mask:0xf bound_ctrl:1
	v_mov_b32_dpp v123, v124 row_shr:1 row_mask:0xf bank_mask:0xf bound_ctrl:1
	v_mov_b32_dpp v130, v131 row_shr:1 row_mask:0xf bank_mask:0xf bound_ctrl:1
	v_mov_b32_dpp v134, v135 row_shr:1 row_mask:0xf bank_mask:0xf bound_ctrl:1
	v_mov_b32_dpp v178, v177 row_shr:1 row_mask:0xf bank_mask:0xf bound_ctrl:1
	v_mul_f32_e32 v131, v83, v74
	v_mul_f32_e32 v135, v71, v75
	v_mul_f32_e32 v177, v79, v74
	v_mul_f32_e32 v180, v67, v75
	v_mov_b32_dpp v124, v125 row_shr:1 row_mask:0xf bank_mask:0xf bound_ctrl:1
	v_add_f32_e32 v116, 1.0, v116
	v_add_f32_e32 v117, 1.0, v117
	v_mov_b32_dpp v125, v131 row_shr:1 row_mask:0xf bank_mask:0xf bound_ctrl:1
	v_rcp_f32_e32 v116, v116
	v_rcp_f32_e32 v117, v117
	v_mov_b32_dpp v131, v135 row_shr:1 row_mask:0xf bank_mask:0xf bound_ctrl:1
	v_pk_add_f32 v[114:115], v[114:115], v[124:125]
	v_pk_add_f32 v[110:111], v[110:111], v[130:131]
	v_pk_fma_f32 v[114:115], v[154:155], v[114:115], v[166:167]
	v_pk_mul_f32 v[98:99], v[98:99], v[72:73] op_sel_hi:[1,0]
	v_pk_fma_f32 v[114:115], v[158:159], v[110:111], v[114:115]
	v_pk_mul_f32 v[112:113], v[112:113], v[116:117]
	v_pk_fma_f32 v[114:115], v[98:99], v[162:163], v[114:115]
	v_pk_add_f32 v[104:105], v[104:105], v[120:121]
	v_exp_f32_e32 v116, v114
	v_exp_f32_e32 v117, v115
	v_pk_add_f32 v[118:119], v[168:169], v[122:123]
	v_add_f32_e32 v116, 1.0, v116
	v_add_f32_e32 v117, 1.0, v117
	v_rcp_f32_e32 v116, v116
	v_rcp_f32_e32 v117, v117
	v_pk_fma_f32 v[104:105], v[136:137], v[104:105], v[148:149]
	v_mov_b32_dpp v135, v177 row_shr:1 row_mask:0xf bank_mask:0xf bound_ctrl:1
	v_pk_mul_f32 v[92:93], v[92:93], v[72:73] op_sel_hi:[1,0]
	v_pk_fma_f32 v[104:105], v[140:141], v[118:119], v[104:105]
	v_mov_b32_dpp v179, v180 row_shr:1 row_mask:0xf bank_mask:0xf bound_ctrl:1
	v_pk_fma_f32 v[104:105], v[92:93], v[144:145], v[104:105]
	v_pk_add_f32 v[106:107], v[106:107], v[134:135]
	v_pk_mul_f32 v[114:115], v[114:115], v[116:117]
	v_mov_b32_e32 v116, v73
	v_pk_fma_f32 v[108:109], v[152:153], v[108:109], v[164:165]
	v_pk_mul_f32 v[104:105], v[104:105], v[112:113]
	v_pk_add_f32 v[112:113], v[170:171], v[178:179]
	v_pk_fma_f32 v[106:107], v[138:139], v[106:107], v[150:151]
	v_pk_mul_f32 v[88:89], v[88:89], v[116:117] op_sel_hi:[1,0]
	v_pk_fma_f32 v[108:109], v[96:97], v[156:157], v[108:109]
	v_pk_mul_f32 v[94:95], v[94:95], v[72:73] op_sel_hi:[1,0]
	v_pk_fma_f32 v[106:107], v[142:143], v[112:113], v[106:107]
	v_pk_fma_f32 v[108:109], v[88:89], v[160:161], v[108:109]
	v_pk_fma_f32 v[106:107], v[94:95], v[146:147], v[106:107]
	v_pk_mul_f32 v[106:107], v[106:107], v[114:115]
	v_exp_f32_e32 v117, v108
	v_exp_f32_e32 v120, v109
	v_add_u32_e32 v177, 0x80, v231
	v_cvt_pk_bf16_f32 v104, v104, v105
	v_cvt_pk_bf16_f32 v105, v106, v107
	v_mov_b64_e32 v[106:107], s[16:17]
	v_mad_i64_i32 v[122:123], s[0:1], v177, s73, v[106:107]
	v_lshl_add_u64 v[114:115], v[122:123], 0, v[174:175]
	global_store_dwordx2 v[114:115], v[104:105], off
	v_add_f32_e32 v104, 1.0, v117
	v_add_f32_e32 v105, 1.0, v120
	v_rcp_f32_e32 v104, v104
	v_rcp_f32_e32 v105, v105
	v_pk_mul_f32 v[90:91], v[90:91], v[116:117] op_sel_hi:[1,0]
	v_pk_mul_f32 v[84:85], v[84:85], v[116:117] op_sel_hi:[1,0]
	v_pk_fma_f32 v[96:97], v[96:97], v[152:153], v[164:165]
	v_pk_mul_f32 v[104:105], v[108:109], v[104:105]
	v_pk_fma_f32 v[108:109], v[154:155], v[110:111], v[166:167]
	v_pk_mul_f32 v[86:87], v[86:87], v[116:117] op_sel_hi:[1,0]
	v_pk_fma_f32 v[108:109], v[98:99], v[158:159], v[108:109]
	v_pk_mul_f32 v[80:81], v[80:81], v[74:75] op_sel_hi:[1,0]
	v_pk_fma_f32 v[108:109], v[90:91], v[162:163], v[108:109]
	v_pk_fma_f32 v[96:97], v[88:89], v[156:157], v[96:97]
	v_exp_f32_e32 v114, v108
	v_exp_f32_e32 v115, v109
	v_pk_fma_f32 v[110:111], v[136:137], v[118:119], v[148:149]
	v_add_f32_e32 v114, 1.0, v114
	v_rcp_f32_e32 v114, v114
	v_add_f32_e32 v115, 1.0, v115
	v_rcp_f32_e32 v115, v115
	v_pk_fma_f32 v[110:111], v[92:93], v[140:141], v[110:111]
	v_pk_fma_f32 v[96:97], v[80:81], v[160:161], v[96:97]
	v_pk_fma_f32 v[110:111], v[84:85], v[144:145], v[110:111]
	v_pk_mul_f32 v[108:109], v[108:109], v[114:115]
	v_pk_mul_f32 v[104:105], v[110:111], v[104:105]
	v_pk_fma_f32 v[110:111], v[138:139], v[112:113], v[150:151]
	v_cvt_pk_bf16_f32 v104, v104, v105
	v_pk_fma_f32 v[110:111], v[94:95], v[142:143], v[110:111]
	v_pk_fma_f32 v[98:99], v[98:99], v[154:155], v[166:167]
; __device__ __forceinline__ unsigned pk2(float lo, float hi) { f32x2_t v = {lo, hi}; bf16x2_t b = __builtin_convertvector(v, bf16x2_t); return __builtin_bit_cast(unsigned, b); }
; __device__ __forceinline__ float sigmoidf_(float v) { return fast_rcp(1.0f + fast_exp2(-v * LOG2E)); }
; #define PG8_LAS __attribute__((address_space(3)))
;     __device__ __forceinline__ void run(const f32x4 (&acc)[2][2][4][2], const Unit& u, const Unit& nxt, bool has_next, int ui, int wr, int wc, int fr_in, int fq_in) const {
;     ...
;         for (int n = 0; n < 2; ++n) {
;             const int cl = wc * 32 + n * 16 + 4 * fq, ch = u.pn * 128 + cl;
;             const PG8_LAS float* pp = prm + slot * 1024 + cl;
;             const f32x4 wg0 = *(const PG8_LAS f32x4*)(pp), wg1 = *(const PG8_LAS f32x4*)(pp + 128), wg2 = *(const PG8_LAS f32x4*)(pp + 256), bg = *(const PG8_LAS f32x4*)(pp + 384);
;             const f32x4 wv0 = *(const PG8_LAS f32x4*)(pp + 512), wv1 = *(const PG8_LAS f32x4*)(pp + 640), wv2 = *(const PG8_LAS f32x4*)(pp + 768), bv = *(const PG8_LAS f32x4*)(pp + 896);
; #pragma unroll
;             for (int ai = 0; ai < 2; ++ai) {
;                 const int grp = 2 * ai + wr;
;                 f32x4 hg2 = {0.f, 0.f, 0.f, 0.f}, hg3 = hg2, hv2 = hg2, hv3 = hg2;
;                 if (grp > 0 && fr == 0) { const PG8_LAS float* xp = xr + ((grp - 1) * 2) * 256 + cl;
;                     hg2 = *(const PG8_LAS f32x4*)(xp); hg3 = *(const PG8_LAS f32x4*)(xp + 256); hv2 = *(const PG8_LAS f32x4*)(xp + 128); hv3 = *(const PG8_LAS f32x4*)(xp + 256 + 128); }
;     ...
;                 for (int m = 0; m < 4; ++m) {
;                     const f32x4 gc = acc[ai][0][m][n] * rs[ai][m], vc = acc[ai][1][m][n] * rs[ai][m];
;                     const f32x4 cgt = bg + wg0 * pg2 + wg1 * pg1 + wg2 * gc, cvl = bv + wv0 * pv2 + wv1 * pv1 + wv2 * vc;
;                     float a[4];
; #pragma unroll
;                     for (int i = 0; i < 4; ++i) a[i] = cgt[i] * sigmoidf_(cgt[i]) * cvl[i];
;                     u32x2 w; w.x = pk2(a[0], a[1]); w.y = pk2(a[2], a[3]);
;                     *(u32x2*)(A + (size_t)(u.pm * BM + ai * 128 + wr * 64 + 4 * fr + m) * DFF + ch) = w;
;                     pg2 = pg1; pg1 = gc; pv2 = pv1; pv1 = vc;
;                 }
	v_pk_fma_f32 v[110:111], v[86:87], v[146:147], v[110:111]
	v_pk_mul_f32 v[82:83], v[82:83], v[74:75] op_sel_hi:[1,0]
	v_pk_mul_f32 v[108:109], v[110:111], v[108:109]
	v_exp_f32_e32 v110, v96
	v_exp_f32_e32 v111, v97
	v_cvt_pk_bf16_f32 v105, v108, v109
	v_add_u32_e32 v108, 0x81, v231
	v_mad_i64_i32 v[124:125], s[0:1], v108, s73, v[106:107]
	v_lshl_add_u64 v[108:109], v[124:125], 0, v[174:175]
	global_store_dwordx2 v[108:109], v[104:105], off
	v_add_f32_e32 v104, 1.0, v110
	v_add_f32_e32 v105, 1.0, v111
	v_rcp_f32_e32 v104, v104
	v_rcp_f32_e32 v105, v105
	v_pk_fma_f32 v[98:99], v[90:91], v[158:159], v[98:99]
	v_pk_fma_f32 v[92:93], v[92:93], v[136:137], v[148:149]
	v_pk_fma_f32 v[98:99], v[82:83], v[162:163], v[98:99]
	v_pk_mul_f32 v[96:97], v[96:97], v[104:105]
	v_exp_f32_e32 v104, v98
	v_exp_f32_e32 v105, v99
	v_pk_mul_f32 v[76:77], v[76:77], v[74:75] op_sel_hi:[1,0]
	v_pk_fma_f32 v[92:93], v[84:85], v[140:141], v[92:93]
	v_add_f32_e32 v104, 1.0, v104
	v_add_f32_e32 v105, 1.0, v105
	v_rcp_f32_e32 v104, v104
	v_rcp_f32_e32 v105, v105
	v_pk_fma_f32 v[94:95], v[94:95], v[138:139], v[150:151]
	v_pk_mul_f32 v[78:79], v[78:79], v[74:75] op_sel_hi:[1,0]
	v_pk_fma_f32 v[92:93], v[76:77], v[144:145], v[92:93]
	v_pk_fma_f32 v[94:95], v[86:87], v[142:143], v[94:95]
	v_pk_mul_f32 v[92:93], v[92:93], v[96:97]
	v_pk_mul_f32 v[96:97], v[98:99], v[104:105]
	v_pk_fma_f32 v[94:95], v[78:79], v[146:147], v[94:95]
	v_pk_fma_f32 v[88:89], v[152:153], v[88:89], v[164:165]
	v_pk_mul_f32 v[94:95], v[94:95], v[96:97]
	v_mov_b32_e32 v96, v75
	v_pk_mul_f32 v[68:69], v[68:69], v[96:97] op_sel_hi:[1,0]
	v_pk_fma_f32 v[80:81], v[156:157], v[80:81], v[88:89]
	v_pk_mul_f32 v[70:71], v[70:71], v[96:97] op_sel_hi:[1,0]
	v_pk_fma_f32 v[68:69], v[160:161], v[68:69], v[80:81]
	v_pk_mul_f32 v[64:65], v[64:65], v[96:97] op_sel_hi:[1,0]
	v_exp_f32_e32 v80, v68
	v_exp_f32_e32 v81, v69
	v_pk_mul_f32 v[66:67], v[66:67], v[96:97] op_sel_hi:[1,0]
	v_cvt_pk_bf16_f32 v92, v92, v93
	v_add_f32_e32 v80, 1.0, v80
	v_add_f32_e32 v81, 1.0, v81
	v_rcp_f32_e32 v80, v80
	v_rcp_f32_e32 v81, v81
	v_cvt_pk_bf16_f32 v93, v94, v95
	v_add_u32_e32 v94, 0x82, v231
	v_mad_i64_i32 v[130:131], s[0:1], v94, s73, v[106:107]
	v_pk_mul_f32 v[68:69], v[68:69], v[80:81]
	v_pk_fma_f32 v[80:81], v[154:155], v[90:91], v[166:167]
	v_lshl_add_u64 v[94:95], v[130:131], 0, v[174:175]
	v_pk_fma_f32 v[80:81], v[158:159], v[82:83], v[80:81]
	global_store_dwordx2 v[94:95], v[92:93], off
	v_pk_fma_f32 v[70:71], v[162:163], v[70:71], v[80:81]
	v_add_u32_e32 v176, 16, v202
	v_exp_f32_e32 v82, v70
	v_exp_f32_e32 v83, v71
	v_pk_fma_f32 v[80:81], v[84:85], v[136:137], v[148:149]
	v_add_f32_e32 v82, 1.0, v82
	v_rcp_f32_e32 v82, v82
	v_add_f32_e32 v83, 1.0, v83
	v_rcp_f32_e32 v83, v83
	v_pk_fma_f32 v[76:77], v[76:77], v[140:141], v[80:81]
	v_mov_b32_e32 v104, 0
	v_pk_fma_f32 v[64:65], v[64:65], v[144:145], v[76:77]
	v_mov_b32_e32 v108, 0
	v_pk_mul_f32 v[64:65], v[64:65], v[68:69]
	v_pk_mul_f32 v[68:69], v[70:71], v[82:83]
	v_pk_fma_f32 v[70:71], v[86:87], v[138:139], v[150:151]
	v_cvt_pk_bf16_f32 v64, v64, v65
	v_pk_fma_f32 v[70:71], v[78:79], v[142:143], v[70:71]
	v_mov_b32_e32 v109, 0
	v_pk_fma_f32 v[66:67], v[66:67], v[146:147], v[70:71]
	v_mov_b32_e32 v110, 0
	v_pk_mul_f32 v[66:67], v[66:67], v[68:69]
	v_mov_b32_e32 v111, 0
	v_cvt_pk_bf16_f32 v65, v66, v67
	v_add_u32_e32 v66, 0x83, v231
	v_mad_i64_i32 v[134:135], s[0:1], v66, s73, v[106:107]
	v_lshl_add_u64 v[66:67], v[134:135], 0, v[174:175]
	global_store_dwordx2 v[66:67], v[64:65], off
	ds_read_b128 v[84:87], v203 offset:64
	ds_read_b128 v[88:91], v203 offset:576
	ds_read_b128 v[92:95], v203 offset:1088
	ds_read_b128 v[96:99], v203 offset:1600
	ds_read_b128 v[64:67], v203 offset:2112
	ds_read_b128 v[68:71], v203 offset:2624
	ds_read_b128 v[76:79], v203 offset:3136
	ds_read_b128 v[80:83], v203 offset:3648
	v_mov_b32_e32 v106, 0
	v_mov_b32_e32 v107, 0
	v_mov_b32_e32 v112, 0
	v_mov_b32_e32 v113, 0
	v_mov_b32_e32 v114, 0
	v_mov_b32_e32 v115, 0
	v_mov_b32_e32 v116, 0
	v_mov_b32_e32 v117, 0
	v_mov_b32_e32 v118, 0
	v_mov_b32_e32 v119, 0
	v_mov_b32_e32 v120, 0
	v_mov_b32_e32 v121, 0
	s_and_saveexec_b64 s[0:1], s[4:5]
	s_cbranch_execz .LBB0_1585
	v_lshl_add_u32 v105, v176, 2, s69
	ds_read_b128 v[118:121], v105
	ds_read_b128 v[110:113], v105 offset:512
	ds_read_b128 v[114:117], v105 offset:1024
	ds_read_b128 v[106:109], v105 offset:1536
; __device__ __forceinline__ unsigned pk2(float lo, float hi) { f32x2_t v = {lo, hi}; bf16x2_t b = __builtin_convertvector(v, bf16x2_t); return __builtin_bit_cast(unsigned, b); }
; #define DPPF(v, ctrl) __builtin_bit_cast(float, __builtin_amdgcn_update_dpp(0, __builtin_bit_cast(int, (v)), (ctrl), 0xf, 0xf, false))
; __device__ __forceinline__ float sigmoidf_(float v) { return fast_rcp(1.0f + fast_exp2(-v * LOG2E)); }
; #define PG8_LAS __attribute__((address_space(3)))
;     __device__ __forceinline__ void run(const f32x4 (&acc)[2][2][4][2], const Unit& u, const Unit& nxt, bool has_next, int ui, int wr, int wc, int fr_in, int fq_in) const {
;     ...
;                 if (grp > 0 && fr == 0) { const PG8_LAS float* xp = xr + ((grp - 1) * 2) * 256 + cl;
;                     hg2 = *(const PG8_LAS f32x4*)(xp); hg3 = *(const PG8_LAS f32x4*)(xp + 256); hv2 = *(const PG8_LAS f32x4*)(xp + 128); hv3 = *(const PG8_LAS f32x4*)(xp + 256 + 128); }
;                 f32x4 pg2, pg1, pv2, pv1;
;                 {
;                     const f32x4 g2 = acc[ai][0][2][n] * rs[ai][2], g3 = acc[ai][0][3][n] * rs[ai][3], v2 = acc[ai][1][2][n] * rs[ai][2], v3 = acc[ai][1][3][n] * rs[ai][3];
; #pragma unroll
;                     for (int i = 0; i < 4; ++i) {
;                         float a0 = g2[i], a1 = g3[i], a2 = v2[i], a3 = v3[i];
;                         asm volatile("" : "+v"(a0), "+v"(a1), "+v"(a2), "+v"(a3));
;                         const float t0 = DPPF(a0, 0x111), t1 = DPPF(a1, 0x111), t2 = DPPF(a2, 0x111), t3 = DPPF(a3, 0x111);
;                         pg2[i] = t0 + hg2[i]; pg1[i] = t1 + hg3[i]; pv2[i] = t2 + hv2[i]; pv1[i] = t3 + hv3[i]; }
;                 }
; #pragma unroll
;                 for (int m = 0; m < 4; ++m) {
;                     const f32x4 gc = acc[ai][0][m][n] * rs[ai][m], vc = acc[ai][1][m][n] * rs[ai][m];
;                     const f32x4 cgt = bg + wg0 * pg2 + wg1 * pg1 + wg2 * gc, cvl = bv + wv0 * pv2 + wv1 * pv1 + wv2 * vc;
;                     float a[4];
; #pragma unroll
;                     for (int i = 0; i < 4; ++i) a[i] = cgt[i] * sigmoidf_(cgt[i]) * cvl[i];
;                     u32x2 w; w.x = pk2(a[0], a[1]); w.y = pk2(a[2], a[3]);
;                     *(u32x2*)(A + (size_t)(u.pm * BM + ai * 128 + wr * 64 + 4 * fr + m) * DFF + ch) = w;
;                     pg2 = pg1; pg1 = gc; pv2 = pv1; pv1 = vc;
.LBB0_1585:
	s_or_b64 exec, exec, s[0:1]
	v_mul_f32_e32 v105, v44, v102
	v_mul_f32_e32 v147, v36, v103
	v_mul_f32_e32 v149, v40, v102
	v_mul_f32_e32 v151, v32, v103
	v_mov_b32_dpp v146, v105 row_shr:1 row_mask:0xf bank_mask:0xf bound_ctrl:1
	s_nop 0
	v_mov_b32_dpp v152, v151 row_shr:1 row_mask:0xf bank_mask:0xf bound_ctrl:1
	v_mul_f32_e32 v105, v45, v102
	v_mul_f32_e32 v151, v37, v103
	v_mul_f32_e32 v153, v41, v102
	v_mul_f32_e32 v154, v33, v103
	v_mov_b32_dpp v150, v149 row_shr:1 row_mask:0xf bank_mask:0xf bound_ctrl:1
	v_mov_b32_dpp v148, v147 row_shr:1 row_mask:0xf bank_mask:0xf bound_ctrl:1
	v_mov_b32_dpp v149, v151 row_shr:1 row_mask:0xf bank_mask:0xf bound_ctrl:1
	v_mov_b32_dpp v147, v105 row_shr:1 row_mask:0xf bank_mask:0xf bound_ctrl:1
	v_mul_f32_e32 v105, v46, v102
	v_mov_b32_dpp v151, v153 row_shr:1 row_mask:0xf bank_mask:0xf bound_ctrl:1
	v_mul_f32_e32 v155, v38, v103
	v_mul_f32_e32 v157, v42, v102
	v_mul_f32_e32 v159, v34, v103
	v_mov_b32_dpp v153, v154 row_shr:1 row_mask:0xf bank_mask:0xf bound_ctrl:1
	v_mov_b32_dpp v154, v105 row_shr:1 row_mask:0xf bank_mask:0xf bound_ctrl:1
	v_mov_b32_dpp v160, v159 row_shr:1 row_mask:0xf bank_mask:0xf bound_ctrl:1
	v_mul_f32_e32 v105, v47, v102
	v_mul_f32_e32 v159, v39, v103
	v_mul_f32_e32 v161, v43, v102
	v_mul_f32_e32 v162, v35, v103
	s_waitcnt lgkmcnt(0)
	v_pk_add_f32 v[118:119], v[118:119], v[146:147]
	v_mov_b32_e32 v140, v100
	v_mov_b32_e32 v141, v100
	v_mov_b32_dpp v158, v157 row_shr:1 row_mask:0xf bank_mask:0xf bound_ctrl:1
	v_pk_add_f32 v[114:115], v[114:115], v[148:149]
	v_pk_fma_f32 v[118:119], v[84:85], v[118:119], v[96:97]
	v_mov_b32_dpp v157, v159 row_shr:1 row_mask:0xf bank_mask:0xf bound_ctrl:1
	v_pk_mul_f32 v[60:61], v[60:61], v[140:141]
	v_pk_fma_f32 v[118:119], v[88:89], v[114:115], v[118:119]
	v_mov_b32_dpp v159, v161 row_shr:1 row_mask:0xf bank_mask:0xf bound_ctrl:1
	v_pk_fma_f32 v[118:119], v[60:61], v[92:93], v[118:119]
	v_mov_b32_dpp v156, v155 row_shr:1 row_mask:0xf bank_mask:0xf bound_ctrl:1
	v_mov_b32_dpp v161, v162 row_shr:1 row_mask:0xf bank_mask:0xf bound_ctrl:1
	v_mov_b32_e32 v162, v100
	v_mov_b32_e32 v163, v100
	v_mov_b32_dpp v155, v105 row_shr:1 row_mask:0xf bank_mask:0xf bound_ctrl:1
	v_exp_f32_e32 v100, v118
	v_exp_f32_e32 v105, v119
	v_pk_mul_f32 v[140:141], v[56:57], v[140:141]
	v_add_f32_e32 v100, 1.0, v100
	v_rcp_f32_e32 v146, v100
	v_add_f32_e32 v100, 1.0, v105
	v_rcp_f32_e32 v147, v100
	v_pk_add_f32 v[56:57], v[110:111], v[150:151]
	v_pk_add_f32 v[116:117], v[116:117], v[156:157]
	v_pk_mul_f32 v[62:63], v[62:63], v[162:163]
	v_pk_mul_f32 v[110:111], v[118:119], v[146:147]
	v_pk_add_f32 v[118:119], v[120:121], v[154:155]
	v_pk_add_f32 v[106:107], v[106:107], v[152:153]
	v_pk_fma_f32 v[118:119], v[86:87], v[118:119], v[98:99]
	v_pk_fma_f32 v[56:57], v[64:65], v[56:57], v[80:81]
	v_pk_fma_f32 v[118:119], v[90:91], v[116:117], v[118:119]
	v_pk_fma_f32 v[56:57], v[68:69], v[106:107], v[56:57]
	v_pk_fma_f32 v[118:119], v[62:63], v[94:95], v[118:119]
	v_pk_fma_f32 v[56:57], v[140:141], v[76:77], v[56:57]
	v_exp_f32_e32 v100, v118
	v_exp_f32_e32 v105, v119
	v_pk_mul_f32 v[56:57], v[56:57], v[110:111]
	v_add_f32_e32 v100, 1.0, v100
	v_rcp_f32_e32 v120, v100
	v_add_f32_e32 v100, 1.0, v105
	v_rcp_f32_e32 v121, v100
	v_pk_add_f32 v[110:111], v[112:113], v[158:159]
	v_pk_add_f32 v[108:109], v[108:109], v[160:161]
	v_pk_fma_f32 v[110:111], v[66:67], v[110:111], v[82:83]
	v_add_u32_e32 v144, s12, v176
	v_pk_mul_f32 v[58:59], v[58:59], v[162:163]
	v_pk_fma_f32 v[110:111], v[70:71], v[108:109], v[110:111]
	v_ashrrev_i32_e32 v145, 31, v144
	v_pk_mul_f32 v[112:113], v[118:119], v[120:121]
	v_pk_fma_f32 v[110:111], v[58:59], v[78:79], v[110:111]
	v_mov_b32_e32 v142, v101
	v_pk_mul_f32 v[110:111], v[110:111], v[112:113]
	v_cvt_pk_bf16_f32 v112, v56, v57
	v_lshlrev_b64 v[56:57], 1, v[144:145]
	v_cvt_pk_bf16_f32 v113, v110, v111
	v_lshl_add_u64 v[110:111], v[128:129], 0, v[56:57]
	v_mov_b32_e32 v143, v101
	global_store_dwordx2 v[110:111], v[112:113], off
	v_pk_fma_f32 v[110:111], v[84:85], v[114:115], v[96:97]
	v_pk_mul_f32 v[52:53], v[52:53], v[142:143]
	v_pk_fma_f32 v[110:111], v[60:61], v[88:89], v[110:111]
	v_pk_fma_f32 v[106:107], v[64:65], v[106:107], v[80:81]
	v_pk_fma_f32 v[110:111], v[52:53], v[92:93], v[110:111]
	v_pk_mul_f32 v[48:49], v[48:49], v[142:143]
	v_exp_f32_e32 v105, v110
	v_exp_f32_e32 v113, v111
	v_mov_b32_e32 v100, v101
	v_add_f32_e32 v105, 1.0, v105
	v_rcp_f32_e32 v112, v105
	v_add_f32_e32 v105, 1.0, v113
	v_rcp_f32_e32 v113, v105
	v_pk_mul_f32 v[54:55], v[54:55], v[100:101]
	v_pk_mul_f32 v[50:51], v[50:51], v[100:101]
	v_pk_fma_f32 v[106:107], v[140:141], v[68:69], v[106:107]
	v_pk_mul_f32 v[100:101], v[110:111], v[112:113]
	v_pk_fma_f32 v[110:111], v[86:87], v[116:117], v[98:99]
	v_pk_fma_f32 v[108:109], v[66:67], v[108:109], v[82:83]
	v_pk_fma_f32 v[110:111], v[62:63], v[90:91], v[110:111]
	v_pk_fma_f32 v[106:107], v[48:49], v[76:77], v[106:107]
	v_pk_fma_f32 v[110:111], v[54:55], v[94:95], v[110:111]
	v_pk_fma_f32 v[108:109], v[58:59], v[70:71], v[108:109]
	v_exp_f32_e32 v105, v110
	v_exp_f32_e32 v113, v111
	v_mov_b32_e32 v138, v102
	v_add_f32_e32 v105, 1.0, v105
	v_rcp_f32_e32 v112, v105
	v_add_f32_e32 v105, 1.0, v113
	v_rcp_f32_e32 v113, v105
	v_mov_b32_e32 v139, v102
	v_pk_mul_f32 v[100:101], v[106:107], v[100:101]
	v_pk_fma_f32 v[108:109], v[50:51], v[78:79], v[108:109]
	v_pk_mul_f32 v[106:107], v[110:111], v[112:113]
	v_pk_fma_f32 v[60:61], v[60:61], v[84:85], v[96:97]
	v_pk_mul_f32 v[106:107], v[108:109], v[106:107]
	v_pk_mul_f32 v[44:45], v[44:45], v[138:139]
	v_pk_fma_f32 v[60:61], v[52:53], v[88:89], v[60:61]
	v_cvt_pk_bf16_f32 v100, v100, v101
; __device__ __forceinline__ unsigned pk2(float lo, float hi) { f32x2_t v = {lo, hi}; bf16x2_t b = __builtin_convertvector(v, bf16x2_t); return __builtin_bit_cast(unsigned, b); }
; #define DPPF(v, ctrl) __builtin_bit_cast(float, __builtin_amdgcn_update_dpp(0, __builtin_bit_cast(int, (v)), (ctrl), 0xf, 0xf, false))
; __device__ __forceinline__ float sigmoidf_(float v) { return fast_rcp(1.0f + fast_exp2(-v * LOG2E)); }
; #define PG8_LAS __attribute__((address_space(3)))
;     __device__ __forceinline__ void run(const f32x4 (&acc)[2][2][4][2], const Unit& u, const Unit& nxt, bool has_next, int ui, int wr, int wc, int fr_in, int fq_in) const {
;     ...
;                 if (grp > 0 && fr == 0) { const PG8_LAS float* xp = xr + ((grp - 1) * 2) * 256 + cl;
;                     hg2 = *(const PG8_LAS f32x4*)(xp); hg3 = *(const PG8_LAS f32x4*)(xp + 256); hv2 = *(const PG8_LAS f32x4*)(xp + 128); hv3 = *(const PG8_LAS f32x4*)(xp + 256 + 128); }
;                 f32x4 pg2, pg1, pv2, pv1;
;                 {
;                     const f32x4 g2 = acc[ai][0][2][n] * rs[ai][2], g3 = acc[ai][0][3][n] * rs[ai][3], v2 = acc[ai][1][2][n] * rs[ai][2], v3 = acc[ai][1][3][n] * rs[ai][3];
; #pragma unroll
;                     for (int i = 0; i < 4; ++i) {
;                         float a0 = g2[i], a1 = g3[i], a2 = v2[i], a3 = v3[i];
;                         asm volatile("" : "+v"(a0), "+v"(a1), "+v"(a2), "+v"(a3));
;                         const float t0 = DPPF(a0, 0x111), t1 = DPPF(a1, 0x111), t2 = DPPF(a2, 0x111), t3 = DPPF(a3, 0x111);
;                         pg2[i] = t0 + hg2[i]; pg1[i] = t1 + hg3[i]; pv2[i] = t2 + hv2[i]; pv1[i] = t3 + hv3[i]; }
;                 }
; #pragma unroll
;                 for (int m = 0; m < 4; ++m) {
;                     const f32x4 gc = acc[ai][0][m][n] * rs[ai][m], vc = acc[ai][1][m][n] * rs[ai][m];
;                     const f32x4 cgt = bg + wg0 * pg2 + wg1 * pg1 + wg2 * gc, cvl = bv + wv0 * pv2 + wv1 * pv1 + wv2 * vc;
;                     float a[4];
; #pragma unroll
;                     for (int i = 0; i < 4; ++i) a[i] = cgt[i] * sigmoidf_(cgt[i]) * cvl[i];
;                     u32x2 w; w.x = pk2(a[0], a[1]); w.y = pk2(a[2], a[3]);
;                     *(u32x2*)(A + (size_t)(u.pm * BM + ai * 128 + wr * 64 + 4 * fr + m) * DFF + ch) = w;
;                     pg2 = pg1; pg1 = gc; pv2 = pv1; pv1 = vc;
;                 }
	v_cvt_pk_bf16_f32 v101, v106, v107
	v_lshl_add_u64 v[106:107], v[126:127], 0, v[56:57]
	v_pk_fma_f32 v[60:61], v[44:45], v[92:93], v[60:61]
	v_mov_b32_e32 v136, v103
	v_mov_b32_e32 v137, v103
	global_store_dwordx2 v[106:107], v[100:101], off
	v_pk_fma_f32 v[52:53], v[52:53], v[84:85], v[96:97]
	v_exp_f32_e32 v105, v60
	v_pk_mul_f32 v[36:37], v[36:37], v[136:137]
	v_pk_fma_f32 v[44:45], v[44:45], v[88:89], v[52:53]
	v_exp_f32_e32 v107, v61
	v_pk_fma_f32 v[36:37], v[36:37], v[92:93], v[44:45]
	v_mov_b32_e32 v100, v102
	v_mov_b32_e32 v101, v102
	v_pk_fma_f32 v[62:63], v[62:63], v[86:87], v[98:99]
	v_pk_mul_f32 v[46:47], v[46:47], v[100:101]
	v_pk_fma_f32 v[62:63], v[54:55], v[90:91], v[62:63]
	v_exp_f32_e32 v44, v36
	v_exp_f32_e32 v45, v37
	v_add_f32_e32 v102, 1.0, v105
	v_pk_fma_f32 v[62:63], v[46:47], v[94:95], v[62:63]
	v_rcp_f32_e32 v106, v102
	v_add_f32_e32 v102, 1.0, v107
	v_pk_mul_f32 v[42:43], v[42:43], v[100:101]
	v_rcp_f32_e32 v107, v102
	v_exp_f32_e32 v102, v62
	v_exp_f32_e32 v105, v63
	v_add_f32_e32 v44, 1.0, v44
	v_add_f32_e32 v45, 1.0, v45
	v_rcp_f32_e32 v44, v44
	v_rcp_f32_e32 v45, v45
	v_add_f32_e32 v102, 1.0, v102
	v_pk_mul_f32 v[60:61], v[60:61], v[106:107]
	v_rcp_f32_e32 v106, v102
	v_add_f32_e32 v102, 1.0, v105
	v_rcp_f32_e32 v107, v102
	v_mov_b32_e32 v102, v103
	v_pk_mul_f32 v[36:37], v[36:37], v[44:45]
	v_pk_fma_f32 v[44:45], v[54:55], v[86:87], v[98:99]
	v_pk_mul_f32 v[38:39], v[38:39], v[102:103]
	v_pk_fma_f32 v[44:45], v[46:47], v[90:91], v[44:45]
	v_pk_fma_f32 v[100:101], v[140:141], v[64:65], v[80:81]
	v_pk_fma_f32 v[38:39], v[38:39], v[94:95], v[44:45]
	v_pk_mul_f32 v[40:41], v[40:41], v[138:139]
	v_exp_f32_e32 v46, v38
	v_exp_f32_e32 v47, v39
	v_pk_fma_f32 v[100:101], v[48:49], v[68:69], v[100:101]
	v_add_f32_e32 v46, 1.0, v46
	v_rcp_f32_e32 v46, v46
	v_add_f32_e32 v47, 1.0, v47
	v_rcp_f32_e32 v47, v47
	v_pk_fma_f32 v[44:45], v[48:49], v[64:65], v[80:81]
	v_pk_fma_f32 v[100:101], v[40:41], v[76:77], v[100:101]
	v_pk_mul_f32 v[32:33], v[32:33], v[136:137]
	v_pk_fma_f32 v[40:41], v[40:41], v[68:69], v[44:45]
	v_pk_fma_f32 v[58:59], v[58:59], v[66:67], v[82:83]
	v_pk_fma_f32 v[32:33], v[32:33], v[76:77], v[40:41]
	v_pk_fma_f32 v[58:59], v[50:51], v[70:71], v[58:59]
	v_pk_mul_f32 v[32:33], v[32:33], v[36:37]
	v_pk_mul_f32 v[36:37], v[38:39], v[46:47]
	v_pk_fma_f32 v[38:39], v[50:51], v[66:67], v[82:83]
	v_pk_mul_f32 v[34:35], v[34:35], v[102:103]
	v_pk_fma_f32 v[38:39], v[42:43], v[70:71], v[38:39]
	v_pk_mul_f32 v[62:63], v[62:63], v[106:107]
	v_pk_fma_f32 v[58:59], v[42:43], v[78:79], v[58:59]
	v_pk_fma_f32 v[34:35], v[34:35], v[78:79], v[38:39]
	v_pk_mul_f32 v[60:61], v[100:101], v[60:61]
	v_pk_mul_f32 v[58:59], v[58:59], v[62:63]
	v_pk_mul_f32 v[34:35], v[34:35], v[36:37]
	v_cvt_pk_bf16_f32 v60, v60, v61
	v_cvt_pk_bf16_f32 v61, v58, v59
	v_lshl_add_u64 v[58:59], v[132:133], 0, v[56:57]
	v_cvt_pk_bf16_f32 v32, v32, v33
	v_cvt_pk_bf16_f32 v33, v34, v35
	v_lshl_add_u64 v[34:35], v[172:173], 0, v[56:57]
	global_store_dwordx2 v[58:59], v[60:61], off
	global_store_dwordx2 v[34:35], v[32:33], off
	v_mov_b32_e32 v105, 0
	v_mov_b32_e32 v106, 0
	v_mov_b32_e32 v107, 0
	v_mov_b32_e32 v32, 0
	v_mov_b32_e32 v33, 0
	v_mov_b32_e32 v34, 0
	v_mov_b32_e32 v35, 0
	v_mov_b32_e32 v36, 0
	v_mov_b32_e32 v37, 0
	v_mov_b32_e32 v38, 0
	v_mov_b32_e32 v39, 0
	v_mov_b32_e32 v40, 0
	v_mov_b32_e32 v41, 0
	v_mov_b32_e32 v42, 0
	v_mov_b32_e32 v43, 0
	s_and_saveexec_b64 s[0:1], s[10:11]
	s_cbranch_execz .LBB0_1587
	ds_read_b128 v[40:43], v230 offset:2112
	ds_read_b128 v[32:35], v230 offset:2624
	ds_read_b128 v[36:39], v230 offset:3136
	ds_read_b128 v[104:107], v230 offset:3648
.LBB0_1587:
	s_or_b64 exec, exec, s[0:1]
	v_mul_f32_e32 v53, v12, v74
	v_mul_f32_e32 v55, v4, v75
	v_mul_f32_e32 v59, v8, v74
	v_mul_f32_e32 v61, v0, v75
	v_mov_b32_dpp v54, v55 row_shr:1 row_mask:0xf bank_mask:0xf bound_ctrl:1
	v_mov_b32_dpp v58, v59 row_shr:1 row_mask:0xf bank_mask:0xf bound_ctrl:1
	v_mov_b32_dpp v60, v61 row_shr:1 row_mask:0xf bank_mask:0xf bound_ctrl:1
	v_mul_f32_e32 v55, v13, v74
	v_mul_f32_e32 v59, v5, v75
	v_mul_f32_e32 v61, v9, v74
	v_mul_f32_e32 v62, v1, v75
	v_mov_b32_dpp v52, v53 row_shr:1 row_mask:0xf bank_mask:0xf bound_ctrl:1
	v_mov_b32_e32 v48, v72
	v_mov_b32_e32 v49, v72
	v_mov_b32_dpp v53, v55 row_shr:1 row_mask:0xf bank_mask:0xf bound_ctrl:1
	s_waitcnt lgkmcnt(0)
; __device__ __forceinline__ unsigned pk2(float lo, float hi) { f32x2_t v = {lo, hi}; bf16x2_t b = __builtin_convertvector(v, bf16x2_t); return __builtin_bit_cast(unsigned, b); }
; __device__ __forceinline__ float sigmoidf_(float v) { return fast_rcp(1.0f + fast_exp2(-v * LOG2E)); }
;     __device__ __forceinline__ void run(const f32x4 (&acc)[2][2][4][2], const Unit& u, const Unit& nxt, bool has_next, int ui, int wr, int wc, int fr_in, int fq_in) const {
;     ...
;             for (int ai = 0; ai < 2; ++ai) {
;                 const int grp = 2 * ai + wr;
;                 f32x4 hg2 = {0.f, 0.f, 0.f, 0.f}, hg3 = hg2, hv2 = hg2, hv3 = hg2;
;                 if (grp > 0 && fr == 0) { const PG8_LAS float* xp = xr + ((grp - 1) * 2) * 256 + cl;
;                     hg2 = *(const PG8_LAS f32x4*)(xp); hg3 = *(const PG8_LAS f32x4*)(xp + 256); hv2 = *(const PG8_LAS f32x4*)(xp + 128); hv3 = *(const PG8_LAS f32x4*)(xp + 256 + 128); }
;                 f32x4 pg2, pg1, pv2, pv1;
;                 {
;                     const f32x4 g2 = acc[ai][0][2][n] * rs[ai][2], g3 = acc[ai][0][3][n] * rs[ai][3], v2 = acc[ai][1][2][n] * rs[ai][2], v3 = acc[ai][1][3][n] * rs[ai][3];
; #pragma unroll
;                     for (int i = 0; i < 4; ++i) {
;                         float a0 = g2[i], a1 = g3[i], a2 = v2[i], a3 = v3[i];
;                         asm volatile("" : "+v"(a0), "+v"(a1), "+v"(a2), "+v"(a3));
;                         const float t0 = DPPF(a0, 0x111), t1 = DPPF(a1, 0x111), t2 = DPPF(a2, 0x111), t3 = DPPF(a3, 0x111);
;                         pg2[i] = t0 + hg2[i]; pg1[i] = t1 + hg3[i]; pv2[i] = t2 + hv2[i]; pv1[i] = t3 + hv3[i]; }
;                 }
; #pragma unroll
;                 for (int m = 0; m < 4; ++m) {
;                     const f32x4 gc = acc[ai][0][m][n] * rs[ai][m], vc = acc[ai][1][m][n] * rs[ai][m];
;                     const f32x4 cgt = bg + wg0 * pg2 + wg1 * pg1 + wg2 * gc, cvl = bv + wv0 * pv2 + wv1 * pv1 + wv2 * vc;
;                     float a[4];
; #pragma unroll
;                     for (int i = 0; i < 4; ++i) a[i] = cgt[i] * sigmoidf_(cgt[i]) * cvl[i];
;                     u32x2 w; w.x = pk2(a[0], a[1]); w.y = pk2(a[2], a[3]);
;                     *(u32x2*)(A + (size_t)(u.pm * BM + ai * 128 + wr * 64 + 4 * fr + m) * DFF + ch) = w;
;                     pg2 = pg1; pg1 = gc; pv2 = pv1; pv1 = vc;
;                 }
	v_pk_add_f32 v[40:41], v[40:41], v[52:53]
	v_pk_mul_f32 v[28:29], v[28:29], v[48:49]
	v_mov_b32_dpp v55, v59 row_shr:1 row_mask:0xf bank_mask:0xf bound_ctrl:1
	v_pk_add_f32 v[36:37], v[36:37], v[54:55]
	v_pk_fma_f32 v[40:41], v[84:85], v[40:41], v[96:97]
	v_pk_fma_f32 v[40:41], v[88:89], v[36:37], v[40:41]
	v_mul_f32_e32 v63, v14, v74
	v_pk_fma_f32 v[40:41], v[28:29], v[92:93], v[40:41]
	v_mul_f32_e32 v101, v6, v75
	v_mul_f32_e32 v103, v10, v74
	v_mul_f32_e32 v109, v2, v75
	v_mov_b32_dpp v59, v61 row_shr:1 row_mask:0xf bank_mask:0xf bound_ctrl:1
	v_exp_f32_e32 v52, v40
	v_exp_f32_e32 v53, v41
	v_mov_b32_dpp v61, v62 row_shr:1 row_mask:0xf bank_mask:0xf bound_ctrl:1
	v_mov_b32_dpp v100, v101 row_shr:1 row_mask:0xf bank_mask:0xf bound_ctrl:1
	v_mov_b32_dpp v102, v103 row_shr:1 row_mask:0xf bank_mask:0xf bound_ctrl:1
	v_mov_b32_dpp v108, v109 row_shr:1 row_mask:0xf bank_mask:0xf bound_ctrl:1
	v_mul_f32_e32 v101, v15, v74
	v_mul_f32_e32 v103, v7, v75
	v_mul_f32_e32 v109, v11, v74
	v_mul_f32_e32 v110, v3, v75
	v_mov_b32_dpp v62, v63 row_shr:1 row_mask:0xf bank_mask:0xf bound_ctrl:1
	v_add_f32_e32 v52, 1.0, v52
	v_add_f32_e32 v53, 1.0, v53
	v_mov_b32_dpp v63, v101 row_shr:1 row_mask:0xf bank_mask:0xf bound_ctrl:1
	v_rcp_f32_e32 v52, v52
	v_rcp_f32_e32 v53, v53
	v_mov_b32_dpp v101, v103 row_shr:1 row_mask:0xf bank_mask:0xf bound_ctrl:1
	v_pk_add_f32 v[42:43], v[42:43], v[62:63]
	v_mov_b32_e32 v111, v72
	v_mov_b32_dpp v103, v109 row_shr:1 row_mask:0xf bank_mask:0xf bound_ctrl:1
	v_pk_add_f32 v[38:39], v[38:39], v[100:101]
	v_pk_fma_f32 v[42:43], v[86:87], v[42:43], v[98:99]
	v_mov_b32_dpp v109, v110 row_shr:1 row_mask:0xf bank_mask:0xf bound_ctrl:1
	v_mov_b32_e32 v110, v72
	v_pk_mul_f32 v[30:31], v[30:31], v[110:111]
	v_pk_fma_f32 v[42:43], v[90:91], v[38:39], v[42:43]
	v_pk_mul_f32 v[40:41], v[40:41], v[52:53]
	v_pk_fma_f32 v[42:43], v[30:31], v[94:95], v[42:43]
	v_pk_add_f32 v[32:33], v[32:33], v[58:59]
	v_exp_f32_e32 v52, v42
	v_exp_f32_e32 v53, v43
	v_pk_mul_f32 v[24:25], v[24:25], v[48:49]
	v_pk_add_f32 v[48:49], v[104:105], v[60:61]
	v_pk_fma_f32 v[32:33], v[64:65], v[32:33], v[80:81]
	v_add_f32_e32 v52, 1.0, v52
	v_add_f32_e32 v53, 1.0, v53
	v_pk_fma_f32 v[32:33], v[68:69], v[48:49], v[32:33]
	v_rcp_f32_e32 v52, v52
	v_rcp_f32_e32 v53, v53
	v_pk_fma_f32 v[32:33], v[24:25], v[76:77], v[32:33]
	v_pk_add_f32 v[34:35], v[34:35], v[102:103]
	v_pk_mul_f32 v[32:33], v[32:33], v[40:41]
	v_pk_add_f32 v[40:41], v[106:107], v[108:109]
	v_pk_fma_f32 v[34:35], v[66:67], v[34:35], v[82:83]
	v_pk_mul_f32 v[26:27], v[26:27], v[110:111]
	v_pk_fma_f32 v[34:35], v[70:71], v[40:41], v[34:35]
	v_pk_mul_f32 v[42:43], v[42:43], v[52:53]
	v_pk_fma_f32 v[34:35], v[26:27], v[78:79], v[34:35]
	v_cvt_pk_bf16_f32 v32, v32, v33
	v_pk_mul_f32 v[34:35], v[34:35], v[42:43]
	v_mov_b32_e32 v50, v73
	v_cvt_pk_bf16_f32 v33, v34, v35
	v_lshl_add_u64 v[34:35], v[122:123], 0, v[56:57]
	v_mov_b32_e32 v51, v73
	global_store_dwordx2 v[34:35], v[32:33], off
	v_pk_fma_f32 v[32:33], v[84:85], v[36:37], v[96:97]
	v_pk_mul_f32 v[20:21], v[20:21], v[50:51]
	v_pk_fma_f32 v[32:33], v[28:29], v[88:89], v[32:33]
	v_mov_b32_e32 v72, v73
	v_pk_fma_f32 v[32:33], v[20:21], v[92:93], v[32:33]
	v_pk_mul_f32 v[22:23], v[22:23], v[72:73]
	v_exp_f32_e32 v34, v32
	v_exp_f32_e32 v35, v33
	v_mov_b32_e32 v46, v74
	v_mov_b32_e32 v47, v74
	v_add_f32_e32 v34, 1.0, v34
	v_add_f32_e32 v35, 1.0, v35
	v_rcp_f32_e32 v34, v34
	v_rcp_f32_e32 v35, v35
	v_pk_fma_f32 v[28:29], v[28:29], v[84:85], v[96:97]
	v_mov_b32_e32 v44, v75
	v_mov_b32_e32 v45, v75
	v_pk_mul_f32 v[32:33], v[32:33], v[34:35]
	v_pk_fma_f32 v[34:35], v[86:87], v[38:39], v[98:99]
	v_pk_mul_f32 v[12:13], v[12:13], v[46:47]
	v_pk_fma_f32 v[34:35], v[30:31], v[90:91], v[34:35]
	v_pk_fma_f32 v[28:29], v[20:21], v[88:89], v[28:29]
	v_pk_fma_f32 v[34:35], v[22:23], v[94:95], v[34:35]
	v_pk_fma_f32 v[20:21], v[20:21], v[84:85], v[96:97]
	v_exp_f32_e32 v38, v34
	v_exp_f32_e32 v39, v35
	v_pk_fma_f32 v[28:29], v[12:13], v[92:93], v[28:29]
; __device__ __forceinline__ unsigned pk2(float lo, float hi) { f32x2_t v = {lo, hi}; bf16x2_t b = __builtin_convertvector(v, bf16x2_t); return __builtin_bit_cast(unsigned, b); }
; __device__ __forceinline__ float fast_rsq(float x) { return __builtin_amdgcn_rsqf(x); }
; __device__ __forceinline__ float sigmoidf_(float v) { return fast_rcp(1.0f + fast_exp2(-v * LOG2E)); }
;     __device__ __forceinline__ void run(const f32x4 (&acc)[2][2][4][2], const Unit& u, const Unit& nxt, bool has_next, int ui, int wr, int wc, int fr_in, int fq_in) const {
;     ...
;                 for (int m = 0; m < 4; ++m) {
;                     const f32x4 gc = acc[ai][0][m][n] * rs[ai][m], vc = acc[ai][1][m][n] * rs[ai][m];
;                     const f32x4 cgt = bg + wg0 * pg2 + wg1 * pg1 + wg2 * gc, cvl = bv + wv0 * pv2 + wv1 * pv1 + wv2 * vc;
;                     float a[4];
; #pragma unroll
;                     for (int i = 0; i < 4; ++i) a[i] = cgt[i] * sigmoidf_(cgt[i]) * cvl[i];
;                     u32x2 w; w.x = pk2(a[0], a[1]); w.y = pk2(a[2], a[3]);
;                     *(u32x2*)(A + (size_t)(u.pm * BM + ai * 128 + wr * 64 + 4 * fr + m) * DFF + ch) = w;
;                     pg2 = pg1; pg1 = gc; pv2 = pv1; pv1 = vc;
;                 }
;                 asm volatile("" ::: "memory");
;             }
;         }
;         if (has_next) {
;             prm[(slot ^ 1) * 1024 + tid] = nx0; prm[(slot ^ 1) * 1024 + tid + 512] = nx1;
;             if (tid < 256) rsd[(slot ^ 1) * 256 + tid] = fast_rsq(nrs * (1.0f / DM) + EPS);
;         }
	v_pk_mul_f32 v[4:5], v[4:5], v[44:45]
	v_pk_fma_f32 v[12:13], v[12:13], v[88:89], v[20:21]
	v_pk_fma_f32 v[36:37], v[64:65], v[48:49], v[80:81]
	v_add_f32_e32 v38, 1.0, v38
	v_add_f32_e32 v39, 1.0, v39
	v_pk_fma_f32 v[4:5], v[4:5], v[92:93], v[12:13]
	v_pk_mul_f32 v[16:17], v[16:17], v[50:51]
	v_rcp_f32_e32 v38, v38
	v_rcp_f32_e32 v39, v39
	v_pk_fma_f32 v[36:37], v[24:25], v[68:69], v[36:37]
	v_pk_fma_f32 v[36:37], v[16:17], v[76:77], v[36:37]
	v_exp_f32_e32 v12, v4
	v_exp_f32_e32 v13, v5
	v_pk_mul_f32 v[32:33], v[36:37], v[32:33]
	v_pk_fma_f32 v[36:37], v[66:67], v[40:41], v[82:83]
	v_pk_mul_f32 v[18:19], v[18:19], v[72:73]
	v_pk_fma_f32 v[36:37], v[26:27], v[70:71], v[36:37]
	v_pk_mul_f32 v[34:35], v[34:35], v[38:39]
	v_pk_fma_f32 v[36:37], v[18:19], v[78:79], v[36:37]
	v_add_f32_e32 v12, 1.0, v12
	v_pk_mul_f32 v[34:35], v[36:37], v[34:35]
	v_add_f32_e32 v13, 1.0, v13
	v_cvt_pk_bf16_f32 v32, v32, v33
	v_cvt_pk_bf16_f32 v33, v34, v35
	v_lshl_add_u64 v[34:35], v[124:125], 0, v[56:57]
	v_rcp_f32_e32 v12, v12
	v_rcp_f32_e32 v13, v13
	global_store_dwordx2 v[34:35], v[32:33], off
	v_exp_f32_e32 v34, v28
	v_mov_b32_e32 v32, v74
	v_exp_f32_e32 v35, v29
	v_mov_b32_e32 v33, v74
	v_pk_mul_f32 v[14:15], v[14:15], v[32:33]
	v_mov_b32_e32 v74, v75
	v_pk_mul_f32 v[4:5], v[4:5], v[12:13]
	v_pk_fma_f32 v[12:13], v[22:23], v[86:87], v[98:99]
	v_pk_mul_f32 v[6:7], v[6:7], v[74:75]
	v_pk_fma_f32 v[12:13], v[14:15], v[90:91], v[12:13]
	v_pk_fma_f32 v[30:31], v[30:31], v[86:87], v[98:99]
	v_pk_fma_f32 v[6:7], v[6:7], v[94:95], v[12:13]
	v_pk_fma_f32 v[30:31], v[22:23], v[90:91], v[30:31]
	v_pk_fma_f32 v[30:31], v[14:15], v[94:95], v[30:31]
	v_exp_f32_e32 v14, v6
	v_exp_f32_e32 v15, v7
	v_pk_mul_f32 v[10:11], v[10:11], v[32:33]
	v_exp_f32_e32 v32, v30
	v_exp_f32_e32 v33, v31
	v_add_f32_e32 v14, 1.0, v14
	v_add_f32_e32 v15, 1.0, v15
	v_add_f32_e32 v34, 1.0, v34
	v_add_f32_e32 v35, 1.0, v35
	v_pk_fma_f32 v[24:25], v[24:25], v[64:65], v[80:81]
	v_rcp_f32_e32 v14, v14
	v_rcp_f32_e32 v15, v15
	v_rcp_f32_e32 v34, v34
	v_rcp_f32_e32 v35, v35
	v_pk_mul_f32 v[8:9], v[8:9], v[46:47]
	v_add_f32_e32 v32, 1.0, v32
	v_add_f32_e32 v33, 1.0, v33
	v_pk_fma_f32 v[24:25], v[16:17], v[68:69], v[24:25]
	v_pk_fma_f32 v[12:13], v[16:17], v[64:65], v[80:81]
	v_rcp_f32_e32 v32, v32
	v_rcp_f32_e32 v33, v33
	v_pk_fma_f32 v[24:25], v[8:9], v[76:77], v[24:25]
	v_pk_mul_f32 v[0:1], v[0:1], v[44:45]
	v_pk_fma_f32 v[8:9], v[8:9], v[68:69], v[12:13]
	v_pk_fma_f32 v[26:27], v[26:27], v[66:67], v[82:83]
	v_pk_fma_f32 v[0:1], v[0:1], v[76:77], v[8:9]
	v_pk_mul_f32 v[28:29], v[28:29], v[34:35]
	v_pk_mul_f32 v[0:1], v[0:1], v[4:5]
	v_pk_mul_f32 v[4:5], v[6:7], v[14:15]
	v_pk_fma_f32 v[6:7], v[18:19], v[66:67], v[82:83]
	v_pk_fma_f32 v[26:27], v[18:19], v[70:71], v[26:27]
	v_pk_mul_f32 v[2:3], v[2:3], v[74:75]
	v_pk_fma_f32 v[6:7], v[10:11], v[70:71], v[6:7]
	v_pk_mul_f32 v[24:25], v[24:25], v[28:29]
	v_pk_mul_f32 v[28:29], v[30:31], v[32:33]
	v_pk_fma_f32 v[26:27], v[10:11], v[78:79], v[26:27]
	v_pk_fma_f32 v[2:3], v[2:3], v[78:79], v[6:7]
	v_pk_mul_f32 v[26:27], v[26:27], v[28:29]
	v_pk_mul_f32 v[2:3], v[2:3], v[4:5]
	v_cvt_pk_bf16_f32 v24, v24, v25
	v_cvt_pk_bf16_f32 v25, v26, v27
	v_lshl_add_u64 v[26:27], v[130:131], 0, v[56:57]
	v_cvt_pk_bf16_f32 v0, v0, v1
	v_cvt_pk_bf16_f32 v1, v2, v3
	v_lshl_add_u64 v[2:3], v[134:135], 0, v[56:57]
	global_store_dwordx2 v[26:27], v[24:25], off
	global_store_dwordx2 v[2:3], v[0:1], off
	s_and_b64 vcc, exec, s[6:7]
	s_mov_b64 s[0:1], -1
	s_cbranch_vccnz .LBB0_1543
	s_xor_b32 s4, s29, 0x400
	v_lshlrev_b32_e32 v0, 2, v226
	v_lshl_add_u32 v0, s4, 2, v0
	v_add_u32_e32 v0, 0x22040, v0
	v_cmp_gt_i32_e32 vcc, s33, v226
	s_waitcnt vmcnt(0)
	v_mul_f32_e32 v228, 0xbfb8aa3b, v228
	v_mul_f32_e32 v227, 0xbf317218, v227
	ds_write2st64_b32 v0, v228, v227 offset1:8
	s_and_saveexec_b64 s[0:1], vcc
	s_cbranch_execz .LBB0_1590
	v_rsq_f32_e32 v0, v229
	v_lshl_add_u32 v1, v226, 2, s4
	v_add_u32_e32 v1, 0x24040, v1
	ds_write_b32 v1, v0

; __device__ __forceinline__ unsigned pk2(float lo, float hi) { f32x2_t v = {lo, hi}; bf16x2_t b = __builtin_convertvector(v, bf16x2_t); return __builtin_bit_cast(unsigned, b); }
; __device__ __forceinline__ float fast_rsq(float x) { return __builtin_amdgcn_rsqf(x); }
; __device__ __forceinline__ float rsq_sum(const u64_t* rsq, int row) { return (float)rsq[row] * (1.0f / 16777216.0f); }
; __device__ __forceinline__ float sigmoidf_(float v) { return fast_rcp(1.0f + fast_exp2(-v * LOG2E)); }
;     __device__ __forceinline__ void operator()(const f32x4 (&acc)[2][2][4][2], const Unit& u, int wr, int wc, int fr_in, int fq_in) const {
;     ...
;         const int rowb = u.pm * BM + wr * 64 + fr;
;         float rs[2][4];
; #pragma unroll
;         for (int ai = 0; ai < 2; ++ai)
; #pragma unroll
;             for (int m = 0; m < 4; ++m) rs[ai][m] = rsq_sum(rsq, rowb + ai * 128 + m * 16);
; #pragma unroll
;         for (int ai = 0; ai < 2; ++ai)
; #pragma unroll
;             for (int m = 0; m < 4; ++m) rs[ai][m] = fast_rsq(rs[ai][m] * (1.0f / DM) + EPS);
; #pragma unroll
;         for (int ai = 0; ai < 2; ++ai)
; #pragma unroll
;             for (int m = 0; m < 4; ++m) {
;                 const int row = rowb + ai * 128 + m * 16;
; #pragma unroll
;                 for (int bj = 0; bj < 2; ++bj) {
;                     const size_t off = (size_t)row * DM + u.pn * BM + bj * HALF + wc * 32 + 8 * fq;
;                     const f32x4 a = acc[ai][bj][m][0] * rs[ai][m], b = acc[ai][bj][m][1] * rs[ai][m];
;                     u32x4 w; w.x = pk2(sigmoidf_(a[0]), sigmoidf_(a[1])); w.y = pk2(sigmoidf_(a[2]), sigmoidf_(a[3]));
;                     w.z = pk2(sigmoidf_(b[0]), sigmoidf_(b[1])); w.w = pk2(sigmoidf_(b[2]), sigmoidf_(b[3]));
;                     *(u32x4*)(SG + off) = w;
;                 }
.LBB0_1830:
	s_lshl_b32 s0, s4, 8
	v_mov_b32_e32 v188, v147
	v_mov_b32_e32 v144, v145
	s_add_i32 s0, s0, s58
	s_nop 0
	v_add_u32_e32 v170, s0, v144
	v_ashrrev_i32_e32 v171, 31, v170
	v_lshl_add_u64 v[172:173], v[170:171], 3, s[14:15]
	global_load_dwordx2 v[174:175], v[172:173], off
	global_load_dwordx2 v[176:177], v[172:173], off offset:128
	global_load_dwordx2 v[178:179], v[172:173], off offset:256
	global_load_dwordx2 v[180:181], v[172:173], off offset:384
	global_load_dwordx2 v[182:183], v[172:173], off offset:1024
	global_load_dwordx2 v[184:185], v[172:173], off offset:1152
	global_load_dwordx2 v[186:187], v[172:173], off offset:1280
	s_nop 0
	global_load_dwordx2 v[172:173], v[172:173], off offset:1408
	s_lshl_b32 s0, s74, 8
	v_lshlrev_b64 v[170:171], 11, v[170:171]
	s_ashr_i32 s1, s0, 31
	s_waitcnt vmcnt(0)
	v_ffbh_u32_e32 v144, v175
	v_min_u32_e32 v144, 32, v144
	v_lshlrev_b64 v[174:175], v144, v[174:175]
	v_ffbh_u32_e32 v146, v177
	v_ffbh_u32_e32 v148, v179
	v_ffbh_u32_e32 v150, v181
	v_min_u32_e32 v174, 1, v174
	v_ffbh_u32_e32 v190, v173
	v_min_u32_e32 v190, 32, v190
	v_lshlrev_b64 v[172:173], v190, v[172:173]
	v_min_u32_e32 v146, 32, v146
	v_min_u32_e32 v148, 32, v148
	v_min_u32_e32 v150, 32, v150
	v_min_u32_e32 v172, 1, v172
	v_or_b32_e32 v174, v175, v174
	v_ffbh_u32_e32 v152, v183
	v_ffbh_u32_e32 v154, v185
	v_ffbh_u32_e32 v189, v187
	v_lshlrev_b64 v[176:177], v146, v[176:177]
	v_lshlrev_b64 v[178:179], v148, v[178:179]
	v_lshlrev_b64 v[180:181], v150, v[180:181]
	v_or_b32_e32 v172, v173, v172
	v_cvt_f32_u32_e32 v173, v174
	v_min_u32_e32 v152, 32, v152
	v_min_u32_e32 v154, 32, v154
	v_min_u32_e32 v189, 32, v189
	v_min_u32_e32 v176, 1, v176
	v_min_u32_e32 v178, 1, v178
	v_min_u32_e32 v180, 1, v180
	v_lshlrev_b64 v[182:183], v152, v[182:183]
	v_lshlrev_b64 v[184:185], v154, v[184:185]
	v_lshlrev_b64 v[186:187], v189, v[186:187]
	v_or_b32_e32 v175, v177, v176
	v_or_b32_e32 v176, v179, v178
	v_or_b32_e32 v177, v181, v180
	v_cvt_f32_u32_e32 v172, v172
	v_sub_u32_e32 v144, 32, v144
	v_min_u32_e32 v182, 1, v182
	v_min_u32_e32 v184, 1, v184
	v_min_u32_e32 v186, 1, v186
	v_cvt_f32_u32_e32 v174, v175
	v_cvt_f32_u32_e32 v175, v176
	v_cvt_f32_u32_e32 v176, v177
	v_or_b32_e32 v178, v183, v182
	v_or_b32_e32 v179, v185, v184
	v_or_b32_e32 v180, v187, v186
	v_ldexp_f32 v144, v173, v144
	v_sub_u32_e32 v190, 32, v190
	v_cvt_f32_u32_e32 v177, v178
	v_cvt_f32_u32_e32 v178, v179
	v_cvt_f32_u32_e32 v179, v180
	v_mul_f32_e32 v144, 0x33800000, v144
	v_sub_u32_e32 v150, 32, v150
	v_ldexp_f32 v172, v172, v190
	v_fmamk_f32 v144, v144, 0x3a800000, v169
	v_ldexp_f32 v150, v176, v150
	v_mul_f32_e32 v176, 0x33800000, v172
	v_rsq_f32_e32 v172, v144
	s_nop 0
	v_mul_f32_e32 v172, 0xbfb8aa3b, v172
	v_sub_u32_e32 v189, 32, v189
	v_ldexp_f32 v173, v179, v189
	v_mul_f32_e32 v173, 0x33800000, v173
	v_pk_mul_f32 v[122:123], v[122:123], v[172:173] op_sel_hi:[1,0]
	v_sub_u32_e32 v148, 32, v148
	v_exp_f32_e32 v122, v122
	v_sub_u32_e32 v154, 32, v154
	v_pk_mul_f32 v[124:125], v[124:125], v[172:173] op_sel_hi:[1,0]
	v_pk_mul_f32 v[120:121], v[120:121], v[172:173] op_sel_hi:[1,0]
	v_ldexp_f32 v148, v175, v148
	v_ldexp_f32 v154, v178, v154
	v_mul_f32_e32 v148, 0x33800000, v148
	v_mul_f32_e32 v175, 0x33800000, v154
	v_exp_f32_e32 v124, v124
	v_exp_f32_e32 v125, v125
	v_exp_f32_e32 v120, v120
	v_exp_f32_e32 v121, v121
	v_fmamk_f32 v148, v148, 0x3a800000, v169
	v_fmamk_f32 v144, v175, 0x3a800000, v169
	v_pk_mul_f32 v[126:127], v[126:127], v[172:173] op_sel_hi:[1,0]
	v_add_f32_e32 v122, 1.0, v122
	v_rsq_f32_e32 v154, v148
	s_nop 0
	v_mul_f32_e32 v154, 0xbfb8aa3b, v154
	v_rsq_f32_e32 v148, v144
	s_nop 0
	v_mul_f32_e32 v148, 0xbfb8aa3b, v148
	v_fmamk_f32 v144, v173, 0x3a800000, v169
	v_rcp_f32_e32 v173, v122
	v_exp_f32_e32 v126, v126
	v_exp_f32_e32 v127, v127
	v_exp_f32_e32 v123, v123
	v_add_f32_e32 v124, 1.0, v124
	v_add_f32_e32 v125, 1.0, v125
	v_add_f32_e32 v120, 1.0, v120
	v_add_f32_e32 v121, 1.0, v121
	v_rcp_f32_e32 v124, v124
	v_rcp_f32_e32 v125, v125
	v_rcp_f32_e32 v120, v120
	v_rcp_f32_e32 v121, v121
	v_sub_u32_e32 v146, 32, v146
	v_pk_mul_f32 v[112:113], v[112:113], v[172:173] op_sel_hi:[1,0]
	v_sub_u32_e32 v152, 32, v152
	v_ldexp_f32 v146, v174, v146
	v_add_f32_e32 v126, 1.0, v126
	v_add_f32_e32 v127, 1.0, v127
	v_add_f32_e32 v122, 1.0, v123
	v_ldexp_f32 v152, v177, v152
	v_mul_f32_e32 v146, 0x33800000, v146
	v_rcp_f32_e32 v126, v126
	v_rcp_f32_e32 v127, v127
	v_rcp_f32_e32 v175, v122
	v_exp_f32_e32 v112, v112
	v_mul_f32_e32 v150, 0x33800000, v150
	v_mul_f32_e32 v152, 0x33800000, v152
	v_fmamk_f32 v146, v146, 0x3a800000, v169
	v_cvt_pk_bf16_f32 v122, v124, v125
	v_cvt_pk_bf16_f32 v124, v120, v121
	v_lshl_add_u64 v[120:121], s[8:9], 0, v[170:171]
	v_exp_f32_e32 v113, v113
	v_fmamk_f32 v150, v150, 0x3a800000, v169
	v_fmamk_f32 v177, v152, 0x3a800000, v169
	v_rsq_f32_e32 v174, v146
	s_nop 0
	v_mul_f32_e32 v174, 0xbfb8aa3b, v174
	v_rsq_f32_e32 v146, v144
	s_nop 0
	v_mul_f32_e32 v146, 0xbfb8aa3b, v146
	v_fmamk_f32 v144, v176, 0x3a800000, v169
	v_lshlrev_b32_e32 v176, 3, v188
	v_lshl_add_u64 v[120:121], s[0:1], 1, v[120:121]
	v_rsq_f32_e32 v152, v150
	s_nop 0
	v_mul_f32_e32 v152, 0xbfb8aa3b, v152
	v_rsq_f32_e32 v150, v177
	s_nop 0
	v_mul_f32_e32 v150, 0xbfb8aa3b, v150
	v_ashrrev_i32_e32 v177, 31, v176
	v_lshl_add_u64 v[120:121], v[120:121], 0, s[20:21]
	v_cvt_pk_bf16_f32 v123, v126, v127
	v_cvt_pk_bf16_f32 v125, v173, v175
	v_lshl_add_u64 v[120:121], v[176:177], 1, v[120:121]
	v_pk_mul_f32 v[114:115], v[114:115], v[172:173] op_sel_hi:[1,0]
	v_add_f32_e32 v112, 1.0, v112
	global_store_dwordx4 v[120:121], v[122:125], off
	v_pk_mul_f32 v[118:119], v[118:119], v[172:173] op_sel_hi:[1,0]
; __device__ __forceinline__ unsigned pk2(float lo, float hi) { f32x2_t v = {lo, hi}; bf16x2_t b = __builtin_convertvector(v, bf16x2_t); return __builtin_bit_cast(unsigned, b); }
; __device__ __forceinline__ float fast_rsq(float x) { return __builtin_amdgcn_rsqf(x); }
; __device__ __forceinline__ float sigmoidf_(float v) { return fast_rcp(1.0f + fast_exp2(-v * LOG2E)); }
;     __device__ __forceinline__ void operator()(const f32x4 (&acc)[2][2][4][2], const Unit& u, int wr, int wc, int fr_in, int fq_in) const {
;     ...
;         for (int ai = 0; ai < 2; ++ai)
; #pragma unroll
;             for (int m = 0; m < 4; ++m) rs[ai][m] = fast_rsq(rs[ai][m] * (1.0f / DM) + EPS);
; #pragma unroll
;         for (int ai = 0; ai < 2; ++ai)
; #pragma unroll
;             for (int m = 0; m < 4; ++m) {
;                 const int row = rowb + ai * 128 + m * 16;
; #pragma unroll
;                 for (int bj = 0; bj < 2; ++bj) {
;                     const size_t off = (size_t)row * DM + u.pn * BM + bj * HALF + wc * 32 + 8 * fq;
;                     const f32x4 a = acc[ai][bj][m][0] * rs[ai][m], b = acc[ai][bj][m][1] * rs[ai][m];
;                     u32x4 w; w.x = pk2(sigmoidf_(a[0]), sigmoidf_(a[1])); w.y = pk2(sigmoidf_(a[2]), sigmoidf_(a[3]));
;                     w.z = pk2(sigmoidf_(b[0]), sigmoidf_(b[1])); w.w = pk2(sigmoidf_(b[2]), sigmoidf_(b[3]));
;                     *(u32x4*)(SG + off) = w;
;                 }
	v_pk_mul_f32 v[116:117], v[116:117], v[172:173] op_sel_hi:[1,0]
	v_rcp_f32_e32 v122, v112
	v_add_f32_e32 v112, 1.0, v113
	v_exp_f32_e32 v113, v114
	v_exp_f32_e32 v116, v116
	v_exp_f32_e32 v117, v117
	v_exp_f32_e32 v118, v118
	v_exp_f32_e32 v119, v119
	v_exp_f32_e32 v114, v115
	v_rcp_f32_e32 v115, v112
	v_add_f32_e32 v112, 1.0, v113
	v_pk_mul_f32 v[104:105], v[104:105], v[174:175] op_sel_hi:[1,0]
	v_add_f32_e32 v116, 1.0, v116
	v_add_f32_e32 v117, 1.0, v117
	v_add_f32_e32 v118, 1.0, v118
	v_add_f32_e32 v119, 1.0, v119
	v_rcp_f32_e32 v123, v112
	v_add_f32_e32 v112, 1.0, v114
	v_rcp_f32_e32 v116, v116
	v_rcp_f32_e32 v117, v117
	v_rcp_f32_e32 v118, v118
	v_rcp_f32_e32 v119, v119
	v_rcp_f32_e32 v124, v112
	v_exp_f32_e32 v104, v104
	v_exp_f32_e32 v105, v105
	v_cvt_pk_bf16_f32 v112, v116, v117
	v_cvt_pk_bf16_f32 v113, v118, v119
	v_cvt_pk_bf16_f32 v114, v122, v115
	v_cvt_pk_bf16_f32 v115, v123, v124
	v_pk_mul_f32 v[110:111], v[110:111], v[174:175] op_sel_hi:[1,0]
	v_pk_mul_f32 v[106:107], v[106:107], v[174:175] op_sel_hi:[1,0]
	v_add_f32_e32 v104, 1.0, v104
	global_store_dwordx4 v[120:121], v[112:115], off offset:256
	v_pk_mul_f32 v[108:109], v[108:109], v[174:175] op_sel_hi:[1,0]
	v_rcp_f32_e32 v112, v104
	v_add_f32_e32 v104, 1.0, v105
	v_exp_f32_e32 v110, v110
	v_exp_f32_e32 v111, v111
	v_exp_f32_e32 v105, v106
	v_exp_f32_e32 v108, v108
	v_exp_f32_e32 v109, v109
	v_exp_f32_e32 v106, v107
	v_add_f32_e32 v110, 1.0, v110
	v_add_f32_e32 v111, 1.0, v111
	v_rcp_f32_e32 v107, v104
	v_add_f32_e32 v104, 1.0, v105
	v_pk_mul_f32 v[96:97], v[96:97], v[174:175] op_sel_hi:[1,0]
	v_add_f32_e32 v108, 1.0, v108
	v_add_f32_e32 v109, 1.0, v109
	v_rcp_f32_e32 v110, v110
	v_rcp_f32_e32 v111, v111
	v_rcp_f32_e32 v113, v104
	v_add_f32_e32 v104, 1.0, v106
	v_rcp_f32_e32 v108, v108
	v_rcp_f32_e32 v109, v109
	v_rcp_f32_e32 v114, v104
	v_exp_f32_e32 v96, v96
	v_exp_f32_e32 v97, v97
	v_cvt_pk_bf16_f32 v105, v110, v111
	v_add_co_u32_e32 v110, vcc, s66, v120
	v_cvt_pk_bf16_f32 v104, v108, v109
	v_cvt_pk_bf16_f32 v106, v112, v107
	v_cvt_pk_bf16_f32 v107, v113, v114
	v_addc_co_u32_e32 v111, vcc, 0, v121, vcc
	v_pk_mul_f32 v[98:99], v[98:99], v[174:175] op_sel_hi:[1,0]
	v_add_f32_e32 v96, 1.0, v96
	global_store_dwordx4 v[110:111], v[104:107], off
	v_pk_mul_f32 v[102:103], v[102:103], v[174:175] op_sel_hi:[1,0]
	v_pk_mul_f32 v[100:101], v[100:101], v[174:175] op_sel_hi:[1,0]
	v_rcp_f32_e32 v104, v96
	v_add_f32_e32 v96, 1.0, v97
	v_exp_f32_e32 v97, v98
	v_exp_f32_e32 v100, v100
	v_exp_f32_e32 v101, v101
	v_exp_f32_e32 v102, v102
	v_exp_f32_e32 v103, v103
	v_exp_f32_e32 v98, v99
	v_rcp_f32_e32 v99, v96
	v_add_f32_e32 v96, 1.0, v97
	v_pk_mul_f32 v[88:89], v[88:89], v[154:155] op_sel_hi:[1,0]
	v_add_f32_e32 v100, 1.0, v100
	v_add_f32_e32 v101, 1.0, v101
	v_add_f32_e32 v102, 1.0, v102
	v_add_f32_e32 v103, 1.0, v103
	v_rcp_f32_e32 v105, v96
	v_add_f32_e32 v96, 1.0, v98
	v_rcp_f32_e32 v100, v100
	v_rcp_f32_e32 v101, v101
	v_rcp_f32_e32 v102, v102
	v_rcp_f32_e32 v103, v103
	v_rcp_f32_e32 v106, v96
	v_exp_f32_e32 v88, v88
	v_exp_f32_e32 v89, v89
	v_lshl_add_u64 v[108:109], v[120:121], 0, s[22:23]
	v_cvt_pk_bf16_f32 v96, v100, v101
	v_cvt_pk_bf16_f32 v97, v102, v103
	v_cvt_pk_bf16_f32 v98, v104, v99
	v_cvt_pk_bf16_f32 v99, v105, v106
	v_pk_mul_f32 v[94:95], v[94:95], v[154:155] op_sel_hi:[1,0]
	v_pk_mul_f32 v[90:91], v[90:91], v[154:155] op_sel_hi:[1,0]
	v_add_f32_e32 v88, 1.0, v88
	global_store_dwordx4 v[108:109], v[96:99], off offset:256
	v_pk_mul_f32 v[92:93], v[92:93], v[154:155] op_sel_hi:[1,0]
	v_rcp_f32_e32 v96, v88
	v_add_f32_e32 v88, 1.0, v89
	v_exp_f32_e32 v94, v94
	v_exp_f32_e32 v95, v95
	v_exp_f32_e32 v89, v90
	v_exp_f32_e32 v92, v92
	v_exp_f32_e32 v93, v93
	v_exp_f32_e32 v90, v91
	v_add_f32_e32 v94, 1.0, v94
	v_add_f32_e32 v95, 1.0, v95
	v_rcp_f32_e32 v91, v88
	v_add_f32_e32 v88, 1.0, v89
	v_pk_mul_f32 v[80:81], v[80:81], v[154:155] op_sel_hi:[1,0]
	v_add_f32_e32 v92, 1.0, v92
	v_add_f32_e32 v93, 1.0, v93
	v_rcp_f32_e32 v94, v94
	v_rcp_f32_e32 v95, v95
	v_rcp_f32_e32 v97, v88
	v_add_f32_e32 v88, 1.0, v90
	v_rcp_f32_e32 v92, v92
	v_rcp_f32_e32 v93, v93
	v_rcp_f32_e32 v98, v88
	v_exp_f32_e32 v80, v80
	v_exp_f32_e32 v81, v81
	v_cvt_pk_bf16_f32 v89, v94, v95
	v_add_co_u32_e32 v94, vcc, s57, v120
	v_cvt_pk_bf16_f32 v88, v92, v93
	v_cvt_pk_bf16_f32 v90, v96, v91
	v_cvt_pk_bf16_f32 v91, v97, v98
	v_addc_co_u32_e32 v95, vcc, 0, v121, vcc
	v_pk_mul_f32 v[82:83], v[82:83], v[154:155] op_sel_hi:[1,0]
	v_add_f32_e32 v80, 1.0, v80
	global_store_dwordx4 v[94:95], v[88:91], off
	v_pk_mul_f32 v[86:87], v[86:87], v[154:155] op_sel_hi:[1,0]
	v_pk_mul_f32 v[84:85], v[84:85], v[154:155] op_sel_hi:[1,0]
	v_rcp_f32_e32 v88, v80
	v_add_f32_e32 v80, 1.0, v81
	v_exp_f32_e32 v81, v82
	v_exp_f32_e32 v84, v84
	v_exp_f32_e32 v85, v85
	v_exp_f32_e32 v86, v86
	v_exp_f32_e32 v87, v87
	v_exp_f32_e32 v82, v83
	v_rcp_f32_e32 v83, v80
	v_add_f32_e32 v80, 1.0, v81
	v_pk_mul_f32 v[72:73], v[72:73], v[152:153] op_sel_hi:[1,0]
	v_add_f32_e32 v84, 1.0, v84
	v_add_f32_e32 v85, 1.0, v85
	v_add_f32_e32 v86, 1.0, v86
	v_add_f32_e32 v87, 1.0, v87
	v_rcp_f32_e32 v89, v80
	v_add_f32_e32 v80, 1.0, v82
	v_rcp_f32_e32 v84, v84
	v_rcp_f32_e32 v85, v85
	v_rcp_f32_e32 v86, v86
	v_rcp_f32_e32 v87, v87
	v_rcp_f32_e32 v90, v80
	v_exp_f32_e32 v72, v72
	v_exp_f32_e32 v73, v73
	v_lshl_add_u64 v[92:93], v[120:121], 0, s[24:25]
	v_cvt_pk_bf16_f32 v80, v84, v85
	v_cvt_pk_bf16_f32 v81, v86, v87
	v_cvt_pk_bf16_f32 v82, v88, v83
	v_cvt_pk_bf16_f32 v83, v89, v90
	v_pk_mul_f32 v[78:79], v[78:79], v[152:153] op_sel_hi:[1,0]
	v_pk_mul_f32 v[74:75], v[74:75], v[152:153] op_sel_hi:[1,0]
	v_add_f32_e32 v72, 1.0, v72
; __device__ __forceinline__ unsigned pk2(float lo, float hi) { f32x2_t v = {lo, hi}; bf16x2_t b = __builtin_convertvector(v, bf16x2_t); return __builtin_bit_cast(unsigned, b); }
; __device__ __forceinline__ float fast_rsq(float x) { return __builtin_amdgcn_rsqf(x); }
; __device__ __forceinline__ float sigmoidf_(float v) { return fast_rcp(1.0f + fast_exp2(-v * LOG2E)); }
;     __device__ __forceinline__ void operator()(const f32x4 (&acc)[2][2][4][2], const Unit& u, int wr, int wc, int fr_in, int fq_in) const {
;     ...
;         for (int ai = 0; ai < 2; ++ai)
; #pragma unroll
;             for (int m = 0; m < 4; ++m) rs[ai][m] = fast_rsq(rs[ai][m] * (1.0f / DM) + EPS);
; #pragma unroll
;         for (int ai = 0; ai < 2; ++ai)
; #pragma unroll
;             for (int m = 0; m < 4; ++m) {
;                 const int row = rowb + ai * 128 + m * 16;
; #pragma unroll
;                 for (int bj = 0; bj < 2; ++bj) {
;                     const size_t off = (size_t)row * DM + u.pn * BM + bj * HALF + wc * 32 + 8 * fq;
;                     const f32x4 a = acc[ai][bj][m][0] * rs[ai][m], b = acc[ai][bj][m][1] * rs[ai][m];
;                     u32x4 w; w.x = pk2(sigmoidf_(a[0]), sigmoidf_(a[1])); w.y = pk2(sigmoidf_(a[2]), sigmoidf_(a[3]));
;                     w.z = pk2(sigmoidf_(b[0]), sigmoidf_(b[1])); w.w = pk2(sigmoidf_(b[2]), sigmoidf_(b[3]));
;                     *(u32x4*)(SG + off) = w;
;                 }
	global_store_dwordx4 v[92:93], v[80:83], off offset:256
	v_pk_mul_f32 v[76:77], v[76:77], v[152:153] op_sel_hi:[1,0]
	v_rcp_f32_e32 v80, v72
	v_add_f32_e32 v72, 1.0, v73
	v_exp_f32_e32 v78, v78
	v_exp_f32_e32 v79, v79
	v_exp_f32_e32 v73, v74
	v_exp_f32_e32 v76, v76
	v_exp_f32_e32 v77, v77
	v_exp_f32_e32 v74, v75
	v_add_f32_e32 v78, 1.0, v78
	v_add_f32_e32 v79, 1.0, v79
	v_rcp_f32_e32 v75, v72
	v_add_f32_e32 v72, 1.0, v73
	v_pk_mul_f32 v[64:65], v[64:65], v[152:153] op_sel_hi:[1,0]
	v_add_f32_e32 v76, 1.0, v76
	v_add_f32_e32 v77, 1.0, v77
	v_rcp_f32_e32 v78, v78
	v_rcp_f32_e32 v79, v79
	v_rcp_f32_e32 v81, v72
	v_add_f32_e32 v72, 1.0, v74
	v_rcp_f32_e32 v76, v76
	v_rcp_f32_e32 v77, v77
	v_rcp_f32_e32 v82, v72
	v_exp_f32_e32 v64, v64
	v_exp_f32_e32 v65, v65
	v_cvt_pk_bf16_f32 v73, v78, v79
	v_add_co_u32_e32 v78, vcc, s65, v120
	v_cvt_pk_bf16_f32 v72, v76, v77
	v_cvt_pk_bf16_f32 v74, v80, v75
	v_cvt_pk_bf16_f32 v75, v81, v82
	v_addc_co_u32_e32 v79, vcc, 0, v121, vcc
	v_pk_mul_f32 v[66:67], v[66:67], v[152:153] op_sel_hi:[1,0]
	v_add_f32_e32 v64, 1.0, v64
	global_store_dwordx4 v[78:79], v[72:75], off
	v_pk_mul_f32 v[70:71], v[70:71], v[152:153] op_sel_hi:[1,0]
	v_pk_mul_f32 v[68:69], v[68:69], v[152:153] op_sel_hi:[1,0]
	v_rcp_f32_e32 v72, v64
	v_add_f32_e32 v64, 1.0, v65
	v_exp_f32_e32 v65, v66
	v_exp_f32_e32 v68, v68
	v_exp_f32_e32 v69, v69
	v_exp_f32_e32 v70, v70
	v_exp_f32_e32 v71, v71
	v_exp_f32_e32 v66, v67
	v_rcp_f32_e32 v67, v64
	v_add_f32_e32 v64, 1.0, v65
	v_pk_mul_f32 v[56:57], v[56:57], v[150:151] op_sel_hi:[1,0]
	v_add_f32_e32 v68, 1.0, v68
	v_add_f32_e32 v69, 1.0, v69
	v_add_f32_e32 v70, 1.0, v70
	v_add_f32_e32 v71, 1.0, v71
	v_rcp_f32_e32 v73, v64
	v_add_f32_e32 v64, 1.0, v66
	v_rcp_f32_e32 v68, v68
	v_rcp_f32_e32 v69, v69
	v_rcp_f32_e32 v70, v70
	v_rcp_f32_e32 v71, v71
	v_rcp_f32_e32 v74, v64
	v_exp_f32_e32 v56, v56
	v_exp_f32_e32 v57, v57
	v_lshl_add_u64 v[76:77], v[120:121], 0, s[26:27]
	v_cvt_pk_bf16_f32 v64, v68, v69
	v_cvt_pk_bf16_f32 v65, v70, v71
	v_cvt_pk_bf16_f32 v66, v72, v67
	v_cvt_pk_bf16_f32 v67, v73, v74
	v_pk_mul_f32 v[62:63], v[62:63], v[150:151] op_sel_hi:[1,0]
	v_pk_mul_f32 v[58:59], v[58:59], v[150:151] op_sel_hi:[1,0]
	v_add_f32_e32 v56, 1.0, v56
	global_store_dwordx4 v[76:77], v[64:67], off offset:256
	v_pk_mul_f32 v[60:61], v[60:61], v[150:151] op_sel_hi:[1,0]
	v_rcp_f32_e32 v64, v56
	v_add_f32_e32 v56, 1.0, v57
	v_exp_f32_e32 v62, v62
	v_exp_f32_e32 v63, v63
	v_exp_f32_e32 v57, v58
	v_exp_f32_e32 v60, v60
	v_exp_f32_e32 v61, v61
	v_exp_f32_e32 v58, v59
	v_add_f32_e32 v62, 1.0, v62
	v_add_f32_e32 v63, 1.0, v63
	v_rcp_f32_e32 v59, v56
	v_add_f32_e32 v56, 1.0, v57
	v_pk_mul_f32 v[48:49], v[48:49], v[150:151] op_sel_hi:[1,0]
	v_add_f32_e32 v60, 1.0, v60
	v_add_f32_e32 v61, 1.0, v61
	v_rcp_f32_e32 v62, v62
	v_rcp_f32_e32 v63, v63
	v_rcp_f32_e32 v65, v56
	v_add_f32_e32 v56, 1.0, v58
	v_rcp_f32_e32 v60, v60
	v_rcp_f32_e32 v61, v61
	v_rcp_f32_e32 v66, v56
	v_exp_f32_e32 v48, v48
	v_exp_f32_e32 v49, v49
	v_cvt_pk_bf16_f32 v57, v62, v63
	v_add_co_u32_e32 v62, vcc, s69, v120
	v_cvt_pk_bf16_f32 v56, v60, v61
	v_cvt_pk_bf16_f32 v58, v64, v59
	v_cvt_pk_bf16_f32 v59, v65, v66
	v_addc_co_u32_e32 v63, vcc, 0, v121, vcc
	v_pk_mul_f32 v[50:51], v[50:51], v[150:151] op_sel_hi:[1,0]
	v_add_f32_e32 v48, 1.0, v48
	global_store_dwordx4 v[62:63], v[56:59], off
	v_pk_mul_f32 v[54:55], v[54:55], v[150:151] op_sel_hi:[1,0]
	v_pk_mul_f32 v[52:53], v[52:53], v[150:151] op_sel_hi:[1,0]
	v_rcp_f32_e32 v56, v48
	v_add_f32_e32 v48, 1.0, v49
	v_exp_f32_e32 v49, v50
	v_exp_f32_e32 v52, v52
	v_exp_f32_e32 v53, v53
	v_exp_f32_e32 v54, v54
	v_exp_f32_e32 v55, v55
	v_exp_f32_e32 v50, v51
	v_rcp_f32_e32 v51, v48
	v_add_f32_e32 v48, 1.0, v49
	v_pk_mul_f32 v[40:41], v[40:41], v[148:149] op_sel_hi:[1,0]
	v_add_f32_e32 v52, 1.0, v52
	v_add_f32_e32 v53, 1.0, v53
	v_add_f32_e32 v54, 1.0, v54
	v_add_f32_e32 v55, 1.0, v55
	v_rcp_f32_e32 v57, v48
	v_add_f32_e32 v48, 1.0, v50
	v_rcp_f32_e32 v52, v52
	v_rcp_f32_e32 v53, v53
	v_rcp_f32_e32 v54, v54
	v_rcp_f32_e32 v55, v55
	v_rcp_f32_e32 v58, v48
	v_exp_f32_e32 v40, v40
	v_exp_f32_e32 v41, v41
	v_lshl_add_u64 v[60:61], v[120:121], 0, s[10:11]
	v_cvt_pk_bf16_f32 v48, v52, v53
	v_cvt_pk_bf16_f32 v49, v54, v55
	v_cvt_pk_bf16_f32 v50, v56, v51
	v_cvt_pk_bf16_f32 v51, v57, v58
	v_pk_mul_f32 v[46:47], v[46:47], v[148:149] op_sel_hi:[1,0]
	v_pk_mul_f32 v[42:43], v[42:43], v[148:149] op_sel_hi:[1,0]
	v_add_f32_e32 v40, 1.0, v40
	global_store_dwordx4 v[60:61], v[48:51], off offset:256
	v_pk_mul_f32 v[44:45], v[44:45], v[148:149] op_sel_hi:[1,0]
	v_rcp_f32_e32 v48, v40
	v_add_f32_e32 v40, 1.0, v41
	v_exp_f32_e32 v46, v46
	v_exp_f32_e32 v47, v47
	v_exp_f32_e32 v41, v42
	v_exp_f32_e32 v44, v44
	v_exp_f32_e32 v45, v45
	v_exp_f32_e32 v42, v43
	v_add_f32_e32 v46, 1.0, v46
	v_add_f32_e32 v47, 1.0, v47
	v_rcp_f32_e32 v43, v40
	v_add_f32_e32 v40, 1.0, v41
	v_pk_mul_f32 v[32:33], v[32:33], v[148:149] op_sel_hi:[1,0]
	v_add_f32_e32 v44, 1.0, v44
	v_add_f32_e32 v45, 1.0, v45
	v_rcp_f32_e32 v46, v46
	v_rcp_f32_e32 v47, v47
	v_rcp_f32_e32 v49, v40
	v_add_f32_e32 v40, 1.0, v42
	v_rcp_f32_e32 v44, v44
	v_rcp_f32_e32 v45, v45
	v_rcp_f32_e32 v50, v40
	v_exp_f32_e32 v32, v32
	v_exp_f32_e32 v33, v33
	v_cvt_pk_bf16_f32 v41, v46, v47
	v_add_co_u32_e32 v46, vcc, s70, v120
	v_cvt_pk_bf16_f32 v40, v44, v45
	v_cvt_pk_bf16_f32 v42, v48, v43
	v_cvt_pk_bf16_f32 v43, v49, v50
	v_addc_co_u32_e32 v47, vcc, 0, v121, vcc
	v_pk_mul_f32 v[34:35], v[34:35], v[148:149] op_sel_hi:[1,0]
	v_add_f32_e32 v32, 1.0, v32
; __device__ __forceinline__ unsigned pk2(float lo, float hi) { f32x2_t v = {lo, hi}; bf16x2_t b = __builtin_convertvector(v, bf16x2_t); return __builtin_bit_cast(unsigned, b); }
; __device__ __forceinline__ float fast_rsq(float x) { return __builtin_amdgcn_rsqf(x); }
; __device__ __forceinline__ float sigmoidf_(float v) { return fast_rcp(1.0f + fast_exp2(-v * LOG2E)); }
;     __device__ __forceinline__ void operator()(const f32x4 (&acc)[2][2][4][2], const Unit& u, int wr, int wc, int fr_in, int fq_in) const {
;     ...
;         for (int ai = 0; ai < 2; ++ai)
; #pragma unroll
;             for (int m = 0; m < 4; ++m) rs[ai][m] = fast_rsq(rs[ai][m] * (1.0f / DM) + EPS);
; #pragma unroll
;         for (int ai = 0; ai < 2; ++ai)
; #pragma unroll
;             for (int m = 0; m < 4; ++m) {
;                 const int row = rowb + ai * 128 + m * 16;
; #pragma unroll
;                 for (int bj = 0; bj < 2; ++bj) {
;                     const size_t off = (size_t)row * DM + u.pn * BM + bj * HALF + wc * 32 + 8 * fq;
;                     const f32x4 a = acc[ai][bj][m][0] * rs[ai][m], b = acc[ai][bj][m][1] * rs[ai][m];
;                     u32x4 w; w.x = pk2(sigmoidf_(a[0]), sigmoidf_(a[1])); w.y = pk2(sigmoidf_(a[2]), sigmoidf_(a[3]));
;                     w.z = pk2(sigmoidf_(b[0]), sigmoidf_(b[1])); w.w = pk2(sigmoidf_(b[2]), sigmoidf_(b[3]));
;                     *(u32x4*)(SG + off) = w;
;                 }
	global_store_dwordx4 v[46:47], v[40:43], off
	v_pk_mul_f32 v[38:39], v[38:39], v[148:149] op_sel_hi:[1,0]
	v_pk_mul_f32 v[36:37], v[36:37], v[148:149] op_sel_hi:[1,0]
	v_rcp_f32_e32 v40, v32
	v_add_f32_e32 v32, 1.0, v33
	v_exp_f32_e32 v33, v34
	v_exp_f32_e32 v36, v36
	v_exp_f32_e32 v37, v37
	v_exp_f32_e32 v38, v38
	v_exp_f32_e32 v39, v39
	v_exp_f32_e32 v34, v35
	v_rcp_f32_e32 v35, v32
	v_add_f32_e32 v32, 1.0, v33
	v_pk_mul_f32 v[24:25], v[24:25], v[146:147] op_sel_hi:[1,0]
	v_add_f32_e32 v36, 1.0, v36
	v_add_f32_e32 v37, 1.0, v37
	v_add_f32_e32 v38, 1.0, v38
	v_add_f32_e32 v39, 1.0, v39
	v_rcp_f32_e32 v41, v32
	v_add_f32_e32 v32, 1.0, v34
	v_rcp_f32_e32 v36, v36
	v_rcp_f32_e32 v37, v37
	v_rcp_f32_e32 v38, v38
	v_rcp_f32_e32 v39, v39
	v_rcp_f32_e32 v42, v32
	v_exp_f32_e32 v24, v24
	v_exp_f32_e32 v25, v25
	v_lshl_add_u64 v[44:45], v[120:121], 0, s[28:29]
	v_cvt_pk_bf16_f32 v32, v36, v37
	v_cvt_pk_bf16_f32 v33, v38, v39
	v_cvt_pk_bf16_f32 v34, v40, v35
	v_cvt_pk_bf16_f32 v35, v41, v42
	v_pk_mul_f32 v[30:31], v[30:31], v[146:147] op_sel_hi:[1,0]
	v_pk_mul_f32 v[26:27], v[26:27], v[146:147] op_sel_hi:[1,0]
	v_add_f32_e32 v24, 1.0, v24
	global_store_dwordx4 v[44:45], v[32:35], off offset:256
	v_pk_mul_f32 v[28:29], v[28:29], v[146:147] op_sel_hi:[1,0]
	v_rcp_f32_e32 v32, v24
	v_add_f32_e32 v24, 1.0, v25
	v_exp_f32_e32 v30, v30
	v_exp_f32_e32 v31, v31
	v_exp_f32_e32 v25, v26
	v_exp_f32_e32 v28, v28
	v_exp_f32_e32 v29, v29
	v_exp_f32_e32 v26, v27
	v_add_f32_e32 v30, 1.0, v30
	v_add_f32_e32 v31, 1.0, v31
	v_rcp_f32_e32 v27, v24
	v_add_f32_e32 v24, 1.0, v25
	v_pk_mul_f32 v[16:17], v[16:17], v[146:147] op_sel_hi:[1,0]
	v_add_f32_e32 v28, 1.0, v28
	v_add_f32_e32 v29, 1.0, v29
	v_rcp_f32_e32 v30, v30
	v_rcp_f32_e32 v31, v31
	v_rcp_f32_e32 v33, v24
	v_add_f32_e32 v24, 1.0, v26
	v_rcp_f32_e32 v28, v28
	v_rcp_f32_e32 v29, v29
	v_rcp_f32_e32 v34, v24
	v_exp_f32_e32 v16, v16
	v_exp_f32_e32 v17, v17
	v_cvt_pk_bf16_f32 v25, v30, v31
	v_add_co_u32_e32 v30, vcc, s71, v120
	v_cvt_pk_bf16_f32 v24, v28, v29
	v_cvt_pk_bf16_f32 v26, v32, v27
	v_cvt_pk_bf16_f32 v27, v33, v34
	v_addc_co_u32_e32 v31, vcc, 0, v121, vcc
	v_pk_mul_f32 v[18:19], v[18:19], v[146:147] op_sel_hi:[1,0]
	v_add_f32_e32 v16, 1.0, v16
	global_store_dwordx4 v[30:31], v[24:27], off
	v_pk_mul_f32 v[22:23], v[22:23], v[146:147] op_sel_hi:[1,0]
	v_pk_mul_f32 v[20:21], v[20:21], v[146:147] op_sel_hi:[1,0]
	v_rcp_f32_e32 v24, v16
	v_add_f32_e32 v16, 1.0, v17
	v_rsq_f32_e32 v144, v144
	s_nop 0
	v_mul_f32_e32 v144, 0xbfb8aa3b, v144
	v_exp_f32_e32 v17, v18
	v_exp_f32_e32 v20, v20
	v_exp_f32_e32 v21, v21
	v_exp_f32_e32 v22, v22
	v_exp_f32_e32 v23, v23
	v_exp_f32_e32 v18, v19
	v_rcp_f32_e32 v19, v16
	v_add_f32_e32 v16, 1.0, v17
	v_pk_mul_f32 v[8:9], v[8:9], v[144:145] op_sel_hi:[1,0]
	v_add_f32_e32 v20, 1.0, v20
	v_add_f32_e32 v21, 1.0, v21
	v_add_f32_e32 v22, 1.0, v22
	v_add_f32_e32 v23, 1.0, v23
	v_rcp_f32_e32 v25, v16
	v_add_f32_e32 v16, 1.0, v18
	v_rcp_f32_e32 v20, v20
	v_rcp_f32_e32 v21, v21
	v_rcp_f32_e32 v22, v22
	v_rcp_f32_e32 v23, v23
	v_rcp_f32_e32 v26, v16
	v_exp_f32_e32 v8, v8
	v_exp_f32_e32 v9, v9
	v_lshl_add_u64 v[28:29], v[120:121], 0, s[30:31]
	v_cvt_pk_bf16_f32 v16, v20, v21
	v_cvt_pk_bf16_f32 v17, v22, v23
	v_cvt_pk_bf16_f32 v18, v24, v19
	v_cvt_pk_bf16_f32 v19, v25, v26
	v_pk_mul_f32 v[14:15], v[14:15], v[144:145] op_sel_hi:[1,0]
	v_pk_mul_f32 v[10:11], v[10:11], v[144:145] op_sel_hi:[1,0]
	v_add_f32_e32 v8, 1.0, v8
	global_store_dwordx4 v[28:29], v[16:19], off offset:256
	v_pk_mul_f32 v[12:13], v[12:13], v[144:145] op_sel_hi:[1,0]
	v_rcp_f32_e32 v16, v8
	v_add_f32_e32 v8, 1.0, v9
	v_exp_f32_e32 v14, v14
	v_exp_f32_e32 v15, v15
	v_exp_f32_e32 v9, v10
	v_exp_f32_e32 v12, v12
	v_exp_f32_e32 v13, v13
	v_exp_f32_e32 v10, v11
	v_add_f32_e32 v14, 1.0, v14
	v_add_f32_e32 v15, 1.0, v15
	v_rcp_f32_e32 v11, v8
	v_add_f32_e32 v8, 1.0, v9
	v_pk_mul_f32 v[0:1], v[0:1], v[144:145] op_sel_hi:[1,0]
	v_add_f32_e32 v12, 1.0, v12
	v_add_f32_e32 v13, 1.0, v13
	v_rcp_f32_e32 v14, v14
	v_rcp_f32_e32 v15, v15
	v_rcp_f32_e32 v17, v8
	v_add_f32_e32 v8, 1.0, v10
	v_rcp_f32_e32 v12, v12
	v_rcp_f32_e32 v13, v13
	v_rcp_f32_e32 v18, v8
	v_exp_f32_e32 v0, v0
	v_exp_f32_e32 v1, v1
	v_cvt_pk_bf16_f32 v9, v14, v15
	v_add_co_u32_e32 v14, vcc, s72, v120
	v_cvt_pk_bf16_f32 v8, v12, v13
	v_cvt_pk_bf16_f32 v10, v16, v11
	v_cvt_pk_bf16_f32 v11, v17, v18
	v_addc_co_u32_e32 v15, vcc, 0, v121, vcc
	v_pk_mul_f32 v[2:3], v[2:3], v[144:145] op_sel_hi:[1,0]
	v_add_f32_e32 v0, 1.0, v0
	global_store_dwordx4 v[14:15], v[8:11], off
	v_pk_mul_f32 v[6:7], v[6:7], v[144:145] op_sel_hi:[1,0]
	v_pk_mul_f32 v[4:5], v[4:5], v[144:145] op_sel_hi:[1,0]
	v_rcp_f32_e32 v8, v0
	v_add_f32_e32 v0, 1.0, v1
	v_exp_f32_e32 v1, v2
	v_exp_f32_e32 v4, v4
	v_exp_f32_e32 v5, v5
	v_exp_f32_e32 v6, v6
	v_exp_f32_e32 v7, v7
	v_exp_f32_e32 v2, v3
	v_rcp_f32_e32 v3, v0
	v_add_f32_e32 v0, 1.0, v1
	v_add_f32_e32 v4, 1.0, v4
	v_add_f32_e32 v5, 1.0, v5
	v_add_f32_e32 v6, 1.0, v6
	v_add_f32_e32 v7, 1.0, v7
	v_rcp_f32_e32 v9, v0
	v_add_f32_e32 v0, 1.0, v2
	v_rcp_f32_e32 v4, v4
	v_rcp_f32_e32 v5, v5
	v_rcp_f32_e32 v6, v6
	v_rcp_f32_e32 v7, v7
	v_rcp_f32_e32 v10, v0
	v_lshl_add_u64 v[12:13], v[120:121], 0, s[34:35]
	v_cvt_pk_bf16_f32 v0, v4, v5
	v_cvt_pk_bf16_f32 v1, v6, v7
	v_cvt_pk_bf16_f32 v2, v8, v3
	v_cvt_pk_bf16_f32 v3, v9, v10
	s_andn2_b64 vcc, exec, s[6:7]
	s_mov_b64 s[0:1], -1
	global_store_dwordx4 v[12:13], v[0:3], off offset:256
	s_cbranch_vccnz .LBB0_1819
	s_andn2_b64 vcc, exec, s[12:13]
	s_cbranch_vccnz .LBB0_1818
	s_barrier
	s_branch .LBB0_1818
